# scan compute loop: up-section e^G reads pipelined one to two consumers ahead through a spare quad; sample-path GEMM K-loops also issue stage loads first
# speedup vs baseline: 1.0034x; 1.0034x over previous
.LBB0_460:
	s_and_b32 s1, s0, 1
	s_mul_i32 s4, s1, 0x11400
	v_mov_b32_e32 v200, v242
	s_lshl_b32 s2, s1, 10
	s_add_i32 s1, s4, 0
	v_mov_b32_e32 v66, s1
	v_and_b32_e32 v131, 31, v200
	v_ashrrev_i32_e32 v221, 5, v200
	v_mad_u32_u24 v66, v131, s58, v66
	v_lshl_add_u32 v126, v221, 3, v66
	v_lshlrev_b32_e32 v202, 4, v221
	v_add_u32_e32 v128, 0x2000, v126
	v_add_u32_e32 v127, v66, v202
	ds_read2_b64 v[102:105], v126 offset1:2
	ds_read2_b64 v[106:109], v128 offset0:64 offset1:66
	ds_read_b128 v[66:69], v127 offset:17408
	ds_read_b128 v[70:73], v127 offset:26112
	v_cvt_pk_bf16_f32 v98, v2, v3
	v_cvt_pk_bf16_f32 v99, v4, v5
	v_cvt_pk_bf16_f32 v100, v6, v7
	v_cvt_pk_bf16_f32 v101, v8, v9
	v_cvt_pk_bf16_f32 v132, v10, v11
	v_cvt_pk_bf16_f32 v133, v12, v13
	v_cvt_pk_bf16_f32 v134, v14, v15
	v_cvt_pk_bf16_f32 v135, v16, v17
	v_cvt_pk_bf16_f32 v136, v18, v19
	v_cvt_pk_bf16_f32 v137, v20, v21
	v_cvt_pk_bf16_f32 v138, v22, v23
	v_cvt_pk_bf16_f32 v139, v24, v25
	v_cvt_pk_bf16_f32 v140, v26, v27
	v_cvt_pk_bf16_f32 v141, v28, v29
	v_cvt_pk_bf16_f32 v142, v30, v31
	v_cvt_pk_bf16_f32 v143, v32, v33
	v_cvt_pk_bf16_f32 v144, v34, v35
	v_cvt_pk_bf16_f32 v145, v36, v37
	v_cvt_pk_bf16_f32 v146, v38, v39
	v_cvt_pk_bf16_f32 v147, v40, v41
	v_cvt_pk_bf16_f32 v148, v42, v43
	v_cvt_pk_bf16_f32 v149, v44, v45
	v_cvt_pk_bf16_f32 v150, v46, v47
	v_cvt_pk_bf16_f32 v151, v48, v49
	v_cvt_pk_bf16_f32 v164, v50, v51
	v_cvt_pk_bf16_f32 v165, v52, v53
	v_cvt_pk_bf16_f32 v166, v54, v55
	v_cvt_pk_bf16_f32 v167, v56, v57
	v_cvt_pk_bf16_f32 v168, v58, v59
	v_cvt_pk_bf16_f32 v169, v60, v61
	v_cvt_pk_bf16_f32 v170, v62, v63
	v_cvt_pk_bf16_f32 v171, v64, v65
	ds_read2_b64 v[152:155], v126 offset0:4 offset1:6
	ds_read2_b64 v[156:159], v128 offset0:68 offset1:70
	ds_read_b128 v[110:113], v127 offset:17440
	ds_read_b128 v[114:117], v127 offset:26144
	s_waitcnt lgkmcnt(5)
	v_mfma_f32_32x32x16_bf16 v[82:97], v[66:69], v[98:101], 0
	s_waitcnt lgkmcnt(4)
	v_mfma_f32_32x32x16_bf16 v[66:81], v[70:73], v[98:101], 0
	ds_read2_b64 v[160:163], v126 offset0:8 offset1:10
	ds_read2_b64 v[172:175], v128 offset0:72 offset1:74
	ds_read_b128 v[118:121], v127 offset:17472
	ds_read_b128 v[122:125], v127 offset:26176
	s_waitcnt lgkmcnt(5)
	v_mfma_f32_32x32x16_bf16 v[82:97], v[110:113], v[132:135], v[82:97]
	s_waitcnt lgkmcnt(4)
	v_mfma_f32_32x32x16_bf16 v[66:81], v[114:117], v[132:135], v[66:81]
	ds_read2_b64 v[176:179], v126 offset0:12 offset1:14
	ds_read2_b64 v[180:183], v128 offset0:76 offset1:78
	ds_read_b128 v[110:113], v127 offset:17504
	ds_read_b128 v[114:117], v127 offset:26208
	s_waitcnt lgkmcnt(5)
	v_mfma_f32_32x32x16_bf16 v[82:97], v[118:121], v[136:139], v[82:97]
	s_waitcnt lgkmcnt(4)
	v_mfma_f32_32x32x16_bf16 v[66:81], v[122:125], v[136:139], v[66:81]
	ds_read2_b64 v[184:187], v126 offset0:16 offset1:18
	ds_read2_b64 v[188:191], v128 offset0:80 offset1:82
	ds_read_b128 v[118:121], v127 offset:17536
	ds_read_b128 v[122:125], v127 offset:26240
	s_waitcnt lgkmcnt(5)
	v_mfma_f32_32x32x16_bf16 v[82:97], v[110:113], v[140:143], v[82:97]
	s_waitcnt lgkmcnt(4)
	v_mfma_f32_32x32x16_bf16 v[66:81], v[114:117], v[140:143], v[66:81]
	ds_read2_b64 v[192:195], v126 offset0:20 offset1:22
	ds_read2_b64 v[222:225], v128 offset0:84 offset1:86
	ds_read_b128 v[110:113], v127 offset:17568
	ds_read_b128 v[114:117], v127 offset:26272
	s_waitcnt lgkmcnt(5)
	v_mfma_f32_32x32x16_bf16 v[82:97], v[118:121], v[144:147], v[82:97]
	s_waitcnt lgkmcnt(4)
	v_mfma_f32_32x32x16_bf16 v[66:81], v[122:125], v[144:147], v[66:81]
	ds_read2_b64 v[226:229], v126 offset0:24 offset1:26
	ds_read2_b64 v[230:233], v128 offset0:88 offset1:90
	ds_read_b128 v[118:121], v127 offset:17600
	ds_read_b128 v[122:125], v127 offset:26304
	s_waitcnt lgkmcnt(5)
	v_mfma_f32_32x32x16_bf16 v[82:97], v[110:113], v[148:151], v[82:97]
	s_waitcnt lgkmcnt(4)
	v_mfma_f32_32x32x16_bf16 v[66:81], v[114:117], v[148:151], v[66:81]
	ds_read2_b64 v[234:237], v126 offset0:28 offset1:30
	ds_read2_b64 v[238:241], v128 offset0:92 offset1:94
	ds_read_b128 v[244:247], v127 offset:17632
	ds_read_b128 v[248:251], v127 offset:26336
	s_waitcnt lgkmcnt(5)
	v_mfma_f32_32x32x16_bf16 v[82:97], v[118:121], v[164:167], v[82:97]
	s_waitcnt lgkmcnt(4)
	v_mfma_f32_32x32x16_bf16 v[66:81], v[122:125], v[164:167], v[66:81]
	v_mfma_f32_32x32x16_bf16 v[114:129], v[102:105], v[98:101], 0
	s_add_i32 s4, s2, 0
	s_add_i32 s4, s4, 0x22800
	v_mfma_f32_32x32x16_bf16 v[98:113], v[106:109], v[98:101], 0
	v_mfma_f32_32x32x16_bf16 v[114:129], v[152:155], v[132:135], v[114:129]
	v_mfma_f32_32x32x16_bf16 v[98:113], v[156:159], v[132:135], v[98:113]
	v_mul_u32_u24_e32 v132, 0x90, v131
	v_mfma_f32_32x32x16_bf16 v[114:129], v[160:163], v[136:139], v[114:129]
	v_mfma_f32_32x32x16_bf16 v[98:113], v[172:175], v[136:139], v[98:113]
	v_mfma_f32_32x32x16_bf16 v[114:129], v[176:179], v[140:143], v[114:129]
	v_mfma_f32_32x32x16_bf16 v[98:113], v[180:183], v[140:143], v[98:113]
	v_mfma_f32_32x32x16_bf16 v[114:129], v[184:187], v[144:147], v[114:129]
	v_mfma_f32_32x32x16_bf16 v[98:113], v[188:191], v[144:147], v[98:113]
	v_add3_u32 v190, s1, v132, v202
	ds_read_b128 v[136:139], v190 offset:52224
	ds_read_b128 v[132:135], v190 offset:52256
	v_mfma_f32_32x32x16_bf16 v[114:129], v[192:195], v[148:151], v[114:129]
	v_mfma_f32_32x32x16_bf16 v[98:113], v[222:225], v[148:151], v[98:113]
	ds_read_b128 v[160:163], v190 offset:56832
	ds_read_b128 v[156:159], v190 offset:56864
	ds_read_b128 v[148:151], v190 offset:52288
	ds_read_b128 v[140:143], v190 offset:52320
	ds_read_b128 v[152:155], v190 offset:56896
	ds_read_b128 v[144:147], v190 offset:56928
	v_mfma_f32_32x32x16_bf16 v[114:129], v[226:229], v[164:167], v[114:129]
	v_mfma_f32_32x32x16_bf16 v[98:113], v[230:233], v[164:167], v[98:113]
	s_waitcnt lgkmcnt(11)
	v_mfma_f32_32x32x16_bf16 v[114:129], v[234:237], v[168:171], v[114:129]
	s_waitcnt lgkmcnt(10)
	v_mfma_f32_32x32x16_bf16 v[98:113], v[238:241], v[168:171], v[98:113]
	s_waitcnt lgkmcnt(9)
	v_mfma_f32_32x32x16_bf16 v[82:97], v[244:247], v[168:171], v[82:97]
	s_waitcnt lgkmcnt(8)
	v_mfma_f32_32x32x16_bf16 v[66:81], v[248:251], v[168:171], v[66:81]
	v_bfe_u32 v164, v200, 2, 2
	v_lshl_or_b32 v165, v221, 2, v164
	v_lshlrev_b32_e32 v164, 1, v200
	v_and_b32_e32 v164, 32, v164
	v_lshlrev_b32_e32 v166, 3, v200
	v_and_or_b32 v164, v166, 24, v164
	s_add_i32 s2, s1, s56
	v_mad_u64_u32 v[200:201], s[6:7], v165, s58, v[164:165]
	s_add_i32 s5, s2, 0x8800
	v_add_u32_e32 v166, s5, v200
	ds_read_b64_tr_b16 v[174:175], v166 offset:0
	ds_read_b64_tr_b16 v[176:177], v166 offset:0x880
	ds_read_b64_tr_b16 v[178:179], v166 offset:0x1100
	ds_read_b64_tr_b16 v[180:181], v166 offset:0x1980
	ds_read_b64_tr_b16 v[182:183], v166 offset:0x2200
	ds_read_b64_tr_b16 v[184:185], v166 offset:0x2a80
	ds_read_b64_tr_b16 v[186:187], v166 offset:0x3300
	ds_read_b64_tr_b16 v[164:165], v166 offset:0x3b80
	s_waitcnt lgkmcnt(0)
	v_add_u32_e32 v201, s4, v202
	ds_read_b128 v[166:169], v201
	ds_read_b128 v[170:173], v201 offset:32
	ds_read_b128 v[222:225], v201 offset:64
	ds_read_b128 v[226:229], v201 offset:96
	ds_read_b128 v[230:233], v201 offset:128
	ds_read_b128 v[234:237], v201 offset:160
	ds_read_b128 v[238:241], v201 offset:192
	ds_read_b128 v[244:247], v201 offset:224
	v_and_b32_e32 v189, 0xffff0000, v174
	v_lshlrev_b32_e32 v188, 16, v174
	s_waitcnt lgkmcnt(7)
	v_pk_fma_f32 v[166:167], v[114:115], v[166:167], v[188:189] neg_lo:[1,0,0] neg_hi:[1,0,0]
	v_and_b32_e32 v115, 0xffff0000, v175
	v_lshlrev_b32_e32 v114, 16, v175
	v_pk_fma_f32 v[168:169], v[116:117], v[168:169], v[114:115] neg_lo:[1,0,0] neg_hi:[1,0,0]
	v_and_b32_e32 v115, 0xffff0000, v176
	v_lshlrev_b32_e32 v114, 16, v176
	s_waitcnt lgkmcnt(6)
	v_pk_fma_f32 v[118:119], v[118:119], v[170:171], v[114:115] neg_lo:[1,0,0] neg_hi:[1,0,0]
	v_and_b32_e32 v115, 0xffff0000, v177
	v_lshlrev_b32_e32 v114, 16, v177
	v_pk_fma_f32 v[120:121], v[120:121], v[172:173], v[114:115] neg_lo:[1,0,0] neg_hi:[1,0,0]
	v_and_b32_e32 v171, 0xffff0000, v178
	v_lshlrev_b32_e32 v170, 16, v178
	v_cvt_pk_bf16_f32 v166, v166, v167
	v_cvt_pk_bf16_f32 v167, v168, v169
	s_waitcnt lgkmcnt(5)
	v_pk_fma_f32 v[122:123], v[122:123], v[222:223], v[170:171] neg_lo:[1, 0, 0] neg_hi:[1, 0, 0]
	v_and_b32_e32 v115, 0xffff0000, v179
	v_lshlrev_b32_e32 v114, 16, v179
	v_pk_fma_f32 v[124:125], v[124:125], v[224:225], v[114:115] neg_lo:[1, 0, 0] neg_hi:[1, 0, 0]
	v_and_b32_e32 v171, 0xffff0000, v180
	v_lshlrev_b32_e32 v170, 16, v180
	v_cvt_pk_bf16_f32 v168, v118, v119
	v_and_b32_e32 v119, 0xffff0000, v182
	s_waitcnt lgkmcnt(4)
	v_pk_fma_f32 v[114:115], v[126:127], v[226:227], v[170:171] neg_lo:[1, 0, 0] neg_hi:[1, 0, 0]
	v_and_b32_e32 v127, 0xffff0000, v181
	v_lshlrev_b32_e32 v126, 16, v181
	v_pk_fma_f32 v[116:117], v[128:129], v[228:229], v[126:127] neg_lo:[1, 0, 0] neg_hi:[1, 0, 0]
	v_cvt_pk_bf16_f32 v172, v114, v115
	v_cvt_pk_bf16_f32 v173, v116, v117
	v_lshlrev_b32_e32 v118, 16, v182
	v_cvt_pk_bf16_f32 v169, v120, v121
	v_cvt_pk_bf16_f32 v170, v122, v123
	v_cvt_pk_bf16_f32 v171, v124, v125
	s_waitcnt lgkmcnt(3)
	v_pk_fma_f32 v[114:115], v[98:99], v[230:231], v[118:119] neg_lo:[1, 0, 0] neg_hi:[1, 0, 0]
	v_and_b32_e32 v99, 0xffff0000, v183
	v_lshlrev_b32_e32 v98, 16, v183
	v_pk_fma_f32 v[116:117], v[100:101], v[232:233], v[98:99] neg_lo:[1, 0, 0] neg_hi:[1, 0, 0]
	v_and_b32_e32 v119, 0xffff0000, v184
	v_lshlrev_b32_e32 v118, 16, v184
	v_cvt_pk_bf16_f32 v174, v114, v115
	v_cvt_pk_bf16_f32 v175, v116, v117
	s_waitcnt lgkmcnt(2)
	v_pk_fma_f32 v[102:103], v[102:103], v[234:235], v[118:119] neg_lo:[1, 0, 0] neg_hi:[1, 0, 0]
	v_and_b32_e32 v99, 0xffff0000, v185
	v_lshlrev_b32_e32 v98, 16, v185
	v_pk_fma_f32 v[104:105], v[104:105], v[236:237], v[98:99] neg_lo:[1, 0, 0] neg_hi:[1, 0, 0]
	v_and_b32_e32 v119, 0xffff0000, v186
	v_lshlrev_b32_e32 v118, 16, v186
	v_cvt_pk_bf16_f32 v176, v102, v103
	v_cvt_pk_bf16_f32 v177, v104, v105
	s_waitcnt lgkmcnt(1)
	v_pk_fma_f32 v[106:107], v[106:107], v[238:239], v[118:119] neg_lo:[1, 0, 0] neg_hi:[1, 0, 0]
	v_and_b32_e32 v99, 0xffff0000, v187
	v_lshlrev_b32_e32 v98, 16, v187
	v_pk_fma_f32 v[108:109], v[108:109], v[240:241], v[98:99] neg_lo:[1, 0, 0] neg_hi:[1, 0, 0]
	v_and_b32_e32 v119, 0xffff0000, v164
	v_lshlrev_b32_e32 v118, 16, v164
	v_cvt_pk_bf16_f32 v178, v106, v107
	v_cvt_pk_bf16_f32 v179, v108, v109
	s_waitcnt lgkmcnt(0)
	v_pk_fma_f32 v[98:99], v[110:111], v[244:245], v[118:119] neg_lo:[1, 0, 0] neg_hi:[1, 0, 0]
	v_and_b32_e32 v111, 0xffff0000, v165
	v_lshlrev_b32_e32 v110, 16, v165
	v_pk_fma_f32 v[100:101], v[112:113], v[246:247], v[110:111] neg_lo:[1, 0, 0] neg_hi:[1, 0, 0]
	v_cvt_pk_bf16_f32 v180, v98, v99
	v_cvt_pk_bf16_f32 v181, v100, v101
	v_mfma_f32_32x32x16_bf16 v[114:129], v[136:139], v[166:169], 0
	v_mfma_f32_32x32x16_bf16 v[98:113], v[160:163], v[166:169], 0
	v_mfma_f32_32x32x16_bf16 v[114:129], v[132:135], v[170:173], v[114:129]
	v_mfma_f32_32x32x16_bf16 v[98:113], v[156:159], v[170:173], v[98:113]
	v_mfma_f32_32x32x16_bf16 v[114:129], v[148:151], v[174:177], v[114:129]
	v_mfma_f32_32x32x16_bf16 v[98:113], v[152:155], v[174:177], v[98:113]
	v_mfma_f32_32x32x16_bf16 v[114:129], v[140:143], v[178:181], v[114:129]
	v_mfma_f32_32x32x16_bf16 v[98:113], v[144:147], v[178:181], v[98:113]
	v_add_u32_e32 v132, 0xf000, v190
	ds_read_b128 v[192:195], v190 offset:61440
	ds_read_b128 v[180:183], v190 offset:61472
	ds_read_b128 v[184:187], v132 offset:4608
	ds_read_b128 v[168:171], v132 offset:4640
	ds_read_b128 v[164:167], v190 offset:61504
	ds_read_b128 v[152:155], v190 offset:61536
	ds_read_b128 v[156:159], v132 offset:4672
	ds_read_b128 v[148:151], v132 offset:4704
	v_mov_b32_e32 v132, s4
	ds_read_b32 v202, v132 offset:512
	ds_read_b128 v[132:135], v201 offset:256
	ds_read_b128 v[136:139], v201 offset:288
	ds_read_b128 v[248:251], v201 offset:320
	v_cvt_pk_bf16_f32 v188, v114, v115
	v_cvt_pk_bf16_f32 v189, v116, v117
	v_cvt_pk_bf16_f32 v176, v122, v123
	s_waitcnt lgkmcnt(2)
	v_pk_mul_f32 v[132:133], v[114:115], v[132:133]
	v_pk_mul_f32 v[134:135], v[116:117], v[134:135]
	ds_read_b128 v[114:117], v201 offset:352
	v_cvt_pk_bf16_f32 v177, v124, v125
	v_cvt_pk_bf16_f32 v172, v98, v99
	v_cvt_pk_bf16_f32 v173, v100, v101
	v_cvt_pk_bf16_f32 v174, v102, v103
	s_waitcnt lgkmcnt(1)
	v_pk_mul_f32 v[122:123], v[122:123], v[248:249]
	v_pk_mul_f32 v[124:125], v[124:125], v[250:251]
	ds_read_b128 v[248:251], v201 offset:384
	v_cvt_pk_bf16_f32 v175, v104, v105
	v_cvt_pk_bf16_f32 v160, v106, v107
	v_cvt_pk_bf16_f32 v161, v108, v109
	v_cvt_pk_bf16_f32 v190, v118, v119
	s_waitcnt lgkmcnt(1)
	v_pk_mul_f32 v[114:115], v[126:127], v[114:115]
	v_cvt_pk_bf16_f32 v191, v120, v121
	v_cvt_pk_bf16_f32 v142, v114, v115
	v_pk_mul_f32 v[114:115], v[128:129], v[116:117]
	v_pk_mul_f32 v[118:119], v[118:119], v[136:137]
	v_cvt_pk_bf16_f32 v143, v114, v115
	v_pk_mul_f32 v[120:121], v[120:121], v[138:139]
	v_cvt_pk_bf16_f32 v145, v134, v135
	v_cvt_pk_bf16_f32 v178, v126, v127
	v_cvt_pk_bf16_f32 v179, v128, v129
	s_waitcnt lgkmcnt(0)
	v_pk_mul_f32 v[114:115], v[98:99], v[248:249]
	v_pk_mul_f32 v[116:117], v[100:101], v[250:251]
	ds_read_b128 v[248:251], v201 offset:416
	ds_read_b128 v[98:101], v201 offset:448
	v_cvt_pk_bf16_f32 v144, v132, v133
	v_cvt_pk_bf16_f32 v146, v118, v119
	v_cvt_pk_bf16_f32 v147, v120, v121
	v_cvt_pk_bf16_f32 v140, v122, v123
	s_waitcnt lgkmcnt(1)
	v_pk_mul_f32 v[102:103], v[102:103], v[248:249]
	v_pk_mul_f32 v[104:105], v[104:105], v[250:251]
	ds_read_b128 v[248:251], v201 offset:480
	v_cvt_pk_bf16_f32 v141, v124, v125
	v_cvt_pk_bf16_f32 v162, v110, v111
	v_cvt_pk_bf16_f32 v163, v112, v113
	v_cvt_pk_bf16_f32 v136, v114, v115
	s_waitcnt lgkmcnt(1)
	v_pk_mul_f32 v[106:107], v[106:107], v[98:99]
	v_pk_mul_f32 v[108:109], v[108:109], v[100:101]
	v_cvt_pk_bf16_f32 v137, v116, v117
	v_cvt_pk_bf16_f32 v138, v102, v103
	v_cvt_pk_bf16_f32 v139, v104, v105
	v_cvt_pk_bf16_f32 v132, v106, v107
	s_waitcnt lgkmcnt(0)
	v_pk_mul_f32 v[98:99], v[110:111], v[248:249]
	v_cvt_pk_bf16_f32 v133, v108, v109
	v_cvt_pk_bf16_f32 v134, v98, v99
	v_pk_mul_f32 v[98:99], v[112:113], v[250:251]
	v_mfma_f32_32x32x16_bf16 v[114:129], v[192:195], v[188:191], 0
	v_cvt_pk_bf16_f32 v135, v98, v99
	v_mfma_f32_32x32x16_bf16 v[98:113], v[184:187], v[188:191], 0
	v_mfma_f32_32x32x16_bf16 v[114:129], v[180:183], v[176:179], v[114:129]
	v_mfma_f32_32x32x16_bf16 v[98:113], v[168:171], v[176:179], v[98:113]
	v_mfma_f32_32x32x16_bf16 v[114:129], v[164:167], v[172:175], v[114:129]
	v_mfma_f32_32x32x16_bf16 v[98:113], v[156:159], v[172:175], v[98:113]
	v_mfma_f32_32x32x16_bf16 v[114:129], v[152:155], v[160:163], v[114:129]
	v_mfma_f32_32x32x16_bf16 v[98:113], v[148:151], v[160:163], v[98:113]
	v_add_u32_e32 v180, s1, v200
	ds_read_b64_tr_b16 v[148:149], v180 offset:0
	ds_read_b64_tr_b16 v[150:151], v180 offset:0x880
	ds_read_b64_tr_b16 v[152:153], v180 offset:64
	ds_read_b64_tr_b16 v[154:155], v180 offset:0x8c0
	ds_read_b64_tr_b16 v[156:157], v180 offset:0x80
	ds_read_b64_tr_b16 v[158:159], v180 offset:0x900
	ds_read_b64_tr_b16 v[160:161], v180 offset:0xc0
	ds_read_b64_tr_b16 v[162:163], v180 offset:0x940
	ds_read_b64_tr_b16 v[164:165], v180 offset:0x1100
	ds_read_b64_tr_b16 v[166:167], v180 offset:0x1980
	ds_read_b64_tr_b16 v[168:169], v180 offset:0x1140
	ds_read_b64_tr_b16 v[170:171], v180 offset:0x19c0
	ds_read_b64_tr_b16 v[172:173], v180 offset:0x1180
	ds_read_b64_tr_b16 v[174:175], v180 offset:0x1a00
	ds_read_b64_tr_b16 v[176:177], v180 offset:0x11c0
	ds_read_b64_tr_b16 v[178:179], v180 offset:0x1a40
	s_waitcnt lgkmcnt(0)
	v_mul_f32_e64 v16, v16, v202
	v_mul_f32_e64 v17, v17, v202
	v_mul_f32_e64 v14, v14, v202
	v_mul_f32_e64 v15, v15, v202
	v_pk_mul_f32 v[12:13], v[12:13], v[202:203] op_sel_hi:[1,0]
	v_pk_mul_f32 v[10:11], v[10:11], v[202:203] op_sel_hi:[1,0]
	v_pk_mul_f32 v[8:9], v[8:9], v[202:203] op_sel_hi:[1,0]
	v_pk_mul_f32 v[6:7], v[6:7], v[202:203] op_sel_hi:[1,0]
	v_pk_mul_f32 v[4:5], v[4:5], v[202:203] op_sel_hi:[1,0]
	v_pk_mul_f32 v[2:3], v[2:3], v[202:203] op_sel_hi:[1,0]
	v_pk_mul_f32 v[32:33], v[32:33], v[202:203] op_sel_hi:[1,0]
	v_pk_mul_f32 v[30:31], v[30:31], v[202:203] op_sel_hi:[1,0]
	v_pk_mul_f32 v[28:29], v[28:29], v[202:203] op_sel_hi:[1,0]
	v_pk_mul_f32 v[26:27], v[26:27], v[202:203] op_sel_hi:[1,0]
	v_pk_mul_f32 v[24:25], v[24:25], v[202:203] op_sel_hi:[1,0]
	v_pk_mul_f32 v[22:23], v[22:23], v[202:203] op_sel_hi:[1,0]
	v_pk_mul_f32 v[20:21], v[20:21], v[202:203] op_sel_hi:[1,0]
	v_pk_mul_f32 v[18:19], v[18:19], v[202:203] op_sel_hi:[1,0]
	v_pk_mul_f32 v[48:49], v[48:49], v[202:203] op_sel_hi:[1,0]
	v_pk_mul_f32 v[46:47], v[46:47], v[202:203] op_sel_hi:[1,0]
	v_pk_mul_f32 v[44:45], v[44:45], v[202:203] op_sel_hi:[1,0]
	v_pk_mul_f32 v[42:43], v[42:43], v[202:203] op_sel_hi:[1,0]
	v_pk_mul_f32 v[40:41], v[40:41], v[202:203] op_sel_hi:[1,0]
	v_pk_mul_f32 v[38:39], v[38:39], v[202:203] op_sel_hi:[1,0]
	v_pk_mul_f32 v[36:37], v[36:37], v[202:203] op_sel_hi:[1,0]
	v_pk_mul_f32 v[34:35], v[34:35], v[202:203] op_sel_hi:[1,0]
	v_pk_mul_f32 v[64:65], v[64:65], v[202:203] op_sel_hi:[1,0]
	v_pk_mul_f32 v[62:63], v[62:63], v[202:203] op_sel_hi:[1,0]
	v_pk_mul_f32 v[60:61], v[60:61], v[202:203] op_sel_hi:[1,0]
	v_pk_mul_f32 v[58:59], v[58:59], v[202:203] op_sel_hi:[1,0]
	v_pk_mul_f32 v[56:57], v[56:57], v[202:203] op_sel_hi:[1,0]
	v_pk_mul_f32 v[54:55], v[54:55], v[202:203] op_sel_hi:[1,0]
	v_pk_mul_f32 v[52:53], v[52:53], v[202:203] op_sel_hi:[1,0]
	v_pk_mul_f32 v[50:51], v[50:51], v[202:203] op_sel_hi:[1,0]
	v_mfma_f32_32x32x16_bf16 v[2:17], v[148:151], v[144:147], v[2:17]
	v_mfma_f32_32x32x16_bf16 v[18:33], v[152:155], v[144:147], v[18:33]
	v_mfma_f32_32x32x16_bf16 v[34:49], v[156:159], v[144:147], v[34:49]
	v_mfma_f32_32x32x16_bf16 v[50:65], v[160:163], v[144:147], v[50:65]
	v_mfma_f32_32x32x16_bf16 v[2:17], v[164:167], v[140:143], v[2:17]
	v_mfma_f32_32x32x16_bf16 v[18:33], v[168:171], v[140:143], v[18:33]
	v_mfma_f32_32x32x16_bf16 v[34:49], v[172:175], v[140:143], v[34:49]
	v_mfma_f32_32x32x16_bf16 v[50:65], v[176:179], v[140:143], v[50:65]
	ds_read_b64_tr_b16 v[140:141], v180 offset:0x2200
	ds_read_b64_tr_b16 v[142:143], v180 offset:0x2a80
	ds_read_b64_tr_b16 v[144:145], v180 offset:0x2240
	ds_read_b64_tr_b16 v[146:147], v180 offset:0x2ac0
	ds_read_b64_tr_b16 v[148:149], v180 offset:0x2280
	ds_read_b64_tr_b16 v[150:151], v180 offset:0x2b00
	ds_read_b64_tr_b16 v[152:153], v180 offset:0x22c0
	ds_read_b64_tr_b16 v[154:155], v180 offset:0x2b40
	ds_read_b64_tr_b16 v[156:157], v180 offset:0x3300
	ds_read_b64_tr_b16 v[158:159], v180 offset:0x3b80
	ds_read_b64_tr_b16 v[160:161], v180 offset:0x3340
	ds_read_b64_tr_b16 v[162:163], v180 offset:0x3bc0
	ds_read_b64_tr_b16 v[164:165], v180 offset:0x3380
	ds_read_b64_tr_b16 v[166:167], v180 offset:0x3c00
	ds_read_b64_tr_b16 v[168:169], v180 offset:0x33c0
	ds_read_b64_tr_b16 v[170:171], v180 offset:0x3c40
	s_waitcnt lgkmcnt(0)
	s_nop 0
	v_mfma_f32_32x32x16_bf16 v[2:17], v[140:143], v[136:139], v[2:17]
	v_mfma_f32_32x32x16_bf16 v[18:33], v[144:147], v[136:139], v[18:33]
	v_mfma_f32_32x32x16_bf16 v[34:49], v[148:151], v[136:139], v[34:49]
	v_mfma_f32_32x32x16_bf16 v[50:65], v[152:155], v[136:139], v[50:65]
	v_mfma_f32_32x32x16_bf16 v[2:17], v[156:159], v[132:135], v[2:17]
	v_mfma_f32_32x32x16_bf16 v[18:33], v[160:163], v[132:135], v[18:33]
	v_mfma_f32_32x32x16_bf16 v[34:49], v[164:167], v[132:135], v[34:49]
	v_mfma_f32_32x32x16_bf16 v[50:65], v[168:171], v[132:135], v[50:65]
	ds_read_b128 v[132:135], v201
	ds_read_b128 v[248:251], v201 offset:32
	s_movk_i32 s1, 0x440
	v_lshlrev_b32_e32 v131, 1, v131
	v_mul_lo_u32 v136, v221, s1
	v_add3_u32 v131, s2, v131, v136
	s_waitcnt lgkmcnt(0)
	v_fma_f32 v82, v82, v132, v114
	v_fma_f32 v83, v83, v133, v115
	v_cvt_pk_bf16_f32 v82, v82, s0
	ds_write_b16 v131, v82 offset:34816
	v_cvt_pk_bf16_f32 v82, v83, s0
	ds_write_b16 v131, v82 offset:35088
	v_fma_f32 v82, v84, v134, v116
	v_cvt_pk_bf16_f32 v82, v82, s0
	ds_write_b16 v131, v82 offset:35360
	v_fma_f32 v82, v85, v135, v117
	v_cvt_pk_bf16_f32 v82, v82, s0
	ds_write_b16 v131, v82 offset:35632
	v_fma_f32 v82, v86, v248, v118
	v_cvt_pk_bf16_f32 v82, v82, s0
	ds_write_b16 v131, v82 offset:36992
	v_fma_f32 v82, v87, v249, v119
	v_cvt_pk_bf16_f32 v82, v82, s0
	ds_write_b16 v131, v82 offset:37264
	v_fma_f32 v82, v88, v250, v120
	v_cvt_pk_bf16_f32 v82, v82, s0
	ds_write_b16 v131, v82 offset:37536
	v_fma_f32 v82, v89, v251, v121
	v_cvt_pk_bf16_f32 v82, v82, s0
	ds_write_b16 v131, v82 offset:37808
	v_fma_f32 v82, v90, v222, v122
	v_cvt_pk_bf16_f32 v82, v82, s0
	ds_write_b16 v131, v82 offset:39168
	v_fma_f32 v82, v91, v223, v123
	v_cvt_pk_bf16_f32 v82, v82, s0
	ds_write_b16 v131, v82 offset:39440
	v_fma_f32 v82, v92, v224, v124
	v_cvt_pk_bf16_f32 v82, v82, s0
	ds_write_b16 v131, v82 offset:39712
	v_fma_f32 v82, v93, v225, v125
	v_cvt_pk_bf16_f32 v82, v82, s0
	ds_write_b16 v131, v82 offset:39984
	v_fma_f32 v82, v94, v226, v126
	v_cvt_pk_bf16_f32 v82, v82, s0
	ds_write_b16 v131, v82 offset:41344
	v_fma_f32 v82, v95, v227, v127
	v_cvt_pk_bf16_f32 v82, v82, s0
	ds_write_b16 v131, v82 offset:41616
	v_fma_f32 v82, v96, v228, v128
	v_cvt_pk_bf16_f32 v82, v82, s0
	v_fmac_f32_e32 v129, v97, v229
	ds_write_b16 v131, v82 offset:41888
	v_cvt_pk_bf16_f32 v82, v129, s0
	ds_write_b16 v131, v82 offset:42160
	v_fma_f32 v66, v66, v230, v98
	v_cvt_pk_bf16_f32 v66, v66, s0
	ds_write_b16 v131, v66 offset:43520
	v_fma_f32 v66, v67, v231, v99
	v_cvt_pk_bf16_f32 v66, v66, s0
	ds_write_b16 v131, v66 offset:43792
	v_fma_f32 v66, v68, v232, v100
	v_cvt_pk_bf16_f32 v66, v66, s0
	ds_write_b16 v131, v66 offset:44064
	v_fma_f32 v66, v69, v233, v101
	v_cvt_pk_bf16_f32 v66, v66, s0
	ds_write_b16 v131, v66 offset:44336
	v_fma_f32 v66, v70, v234, v102
	v_cvt_pk_bf16_f32 v66, v66, s0
	ds_write_b16 v131, v66 offset:45696
	v_fma_f32 v66, v71, v235, v103
	v_cvt_pk_bf16_f32 v66, v66, s0
	ds_write_b16 v131, v66 offset:45968
	v_fma_f32 v66, v72, v236, v104
	v_cvt_pk_bf16_f32 v66, v66, s0
	ds_write_b16 v131, v66 offset:46240
	v_fma_f32 v66, v73, v237, v105
	v_cvt_pk_bf16_f32 v66, v66, s0
	ds_write_b16 v131, v66 offset:46512
	v_fma_f32 v66, v74, v238, v106
	v_cvt_pk_bf16_f32 v66, v66, s0
	ds_write_b16 v131, v66 offset:47872
	v_fma_f32 v66, v75, v239, v107
	v_cvt_pk_bf16_f32 v66, v66, s0
	ds_write_b16 v131, v66 offset:48144
	v_fma_f32 v66, v76, v240, v108
	v_cvt_pk_bf16_f32 v66, v66, s0
	ds_write_b16 v131, v66 offset:48416
	v_fma_f32 v66, v77, v241, v109
	v_cvt_pk_bf16_f32 v66, v66, s0
	ds_write_b16 v131, v66 offset:48688
	v_fma_f32 v66, v78, v244, v110
	v_cvt_pk_bf16_f32 v66, v66, s0
	ds_write_b16 v131, v66 offset:50048
	v_fma_f32 v66, v79, v245, v111
	v_cvt_pk_bf16_f32 v66, v66, s0
	ds_write_b16 v131, v66 offset:50320
	v_fma_f32 v66, v80, v246, v112
	v_cvt_pk_bf16_f32 v66, v66, s0
	v_fmac_f32_e32 v113, v81, v247
	ds_write_b16 v131, v66 offset:50592
	v_cvt_pk_bf16_f32 v66, v113, s0
	ds_write_b16 v131, v66 offset:50864
	s_waitcnt lgkmcnt(0)
	s_add_i32 s0, s0, 1
	s_cmpk_eq_i32 s0, 0x80
	s_waitcnt lgkmcnt(0)
	s_barrier
	s_cbranch_scc0 .LBB0_460
	s_mov_b64 s[0:1], 0
	s_barrier
	s_barrier
	ds_write2st64_b32 v197, v2, v3 offset1:2
	ds_write2st64_b32 v197, v4, v5 offset0:4 offset1:6
	ds_write2st64_b32 v197, v6, v7 offset0:16 offset1:18
	ds_write2st64_b32 v197, v8, v9 offset0:20 offset1:22
	ds_write2st64_b32 v197, v10, v11 offset0:32 offset1:34
	ds_write2st64_b32 v197, v12, v13 offset0:36 offset1:38
	ds_write2st64_b32 v197, v14, v15 offset0:48 offset1:50
	ds_write2st64_b32 v197, v16, v17 offset0:52 offset1:54
	ds_write2st64_b32 v197, v18, v19 offset0:64 offset1:66
	ds_write2st64_b32 v197, v20, v21 offset0:68 offset1:70
	ds_write2st64_b32 v197, v22, v23 offset0:80 offset1:82
	ds_write2st64_b32 v197, v24, v25 offset0:84 offset1:86
	ds_write2st64_b32 v197, v26, v27 offset0:96 offset1:98
	ds_write2st64_b32 v197, v28, v29 offset0:100 offset1:102
	ds_write2st64_b32 v197, v30, v31 offset0:112 offset1:114
	ds_write2st64_b32 v197, v32, v33 offset0:116 offset1:118
	ds_write2st64_b32 v197, v34, v35 offset0:128 offset1:130
	ds_write2st64_b32 v197, v36, v37 offset0:132 offset1:134
	ds_write2st64_b32 v197, v38, v39 offset0:144 offset1:146
	ds_write2st64_b32 v197, v40, v41 offset0:148 offset1:150
	ds_write2st64_b32 v197, v42, v43 offset0:160 offset1:162
	ds_write2st64_b32 v197, v44, v45 offset0:164 offset1:166
	ds_write2st64_b32 v197, v46, v47 offset0:176 offset1:178
	ds_write2st64_b32 v197, v48, v49 offset0:180 offset1:182
	ds_write2st64_b32 v197, v50, v51 offset0:192 offset1:194
	ds_write2st64_b32 v197, v52, v53 offset0:196 offset1:198
	ds_write2st64_b32 v197, v54, v55 offset0:208 offset1:210
	ds_write2st64_b32 v197, v56, v57 offset0:212 offset1:214
	ds_write2st64_b32 v197, v58, v59 offset0:224 offset1:226
	ds_write2st64_b32 v197, v60, v61 offset0:228 offset1:230
	ds_write2st64_b32 v197, v62, v63 offset0:240 offset1:242
	ds_write2st64_b32 v197, v64, v65 offset0:244 offset1:246

.LBB0_806:
	s_add_u32 s30, s28, 0x100
	s_addc_u32 s31, s29, 0
	s_add_u32 s34, s54, s28
	s_addc_u32 s35, s55, s29
	s_cmp_eq_u32 s56, 60
	s_cselect_b32 s36, 0, s30
	s_cselect_b32 s37, 0, s31
	s_cselect_b32 s34, s21, s34
	s_cselect_b32 s35, s8, s35
	s_add_u32 s36, s2, s36
	s_addc_u32 s37, s3, s37
	s_mov_b32 m0, s50
	v_lshl_add_u64 v[208:209], v[134:135], 0, s[28:29]
	global_load_lds_dwordx4 v[208:209], off
	v_lshl_add_u64 v[208:209], v[136:137], 0, s[28:29]
	s_mov_b32 m0, s51
	s_nop 0
	global_load_lds_dwordx4 v[208:209], off
	ds_read_b128 v[138:141], v144
	ds_read_b128 v[148:151], v144 offset:1024
	ds_read_b128 v[152:155], v144 offset:2048
	ds_read_b128 v[156:159], v144 offset:3072
	ds_read_b128 v[160:163], v145
	ds_read_b128 v[164:167], v145 offset:1024
	ds_read_b128 v[168:171], v145 offset:2048
	ds_read_b128 v[172:175], v145 offset:3072
	ds_read_b128 v[176:179], v146
	ds_read_b128 v[180:183], v146 offset:1024
	ds_read_b128 v[184:187], v146 offset:2048
	ds_read_b128 v[188:191], v146 offset:3072
	ds_read_b128 v[192:195], v146 offset:4096
	ds_read_b128 v[196:199], v146 offset:5120
	ds_read_b128 v[200:203], v146 offset:6144
	ds_read_b128 v[204:207], v146 offset:7168
	s_waitcnt vmcnt(8)
	s_waitcnt lgkmcnt(0)
	s_barrier
	s_setprio 1
	s_waitcnt lgkmcnt(0)
	v_mfma_f32_16x16x32_bf16 v[126:129], v[138:141], v[176:179], v[126:129]
	v_mfma_f32_16x16x32_bf16 v[122:125], v[152:155], v[176:179], v[122:125]
	v_mfma_f32_16x16x32_bf16 v[110:113], v[138:141], v[184:187], v[110:113]
	v_mfma_f32_16x16x32_bf16 v[106:109], v[152:155], v[184:187], v[106:109]
	v_mfma_f32_16x16x32_bf16 v[94:97], v[138:141], v[192:195], v[94:97]
	v_mfma_f32_16x16x32_bf16 v[90:93], v[152:155], v[192:195], v[90:93]
	v_mfma_f32_16x16x32_bf16 v[78:81], v[138:141], v[200:203], v[78:81]
	v_mfma_f32_16x16x32_bf16 v[74:77], v[152:155], v[200:203], v[74:77]
	v_mfma_f32_16x16x32_bf16 v[126:129], v[148:151], v[180:183], v[126:129]
	v_mfma_f32_16x16x32_bf16 v[122:125], v[156:159], v[180:183], v[122:125]
	v_mfma_f32_16x16x32_bf16 v[110:113], v[148:151], v[188:191], v[110:113]
	v_mfma_f32_16x16x32_bf16 v[106:109], v[156:159], v[188:191], v[106:109]
	v_mfma_f32_16x16x32_bf16 v[94:97], v[148:151], v[196:199], v[94:97]
	v_mfma_f32_16x16x32_bf16 v[90:93], v[156:159], v[196:199], v[90:93]
	v_mfma_f32_16x16x32_bf16 v[78:81], v[148:151], v[204:207], v[78:81]
	v_mfma_f32_16x16x32_bf16 v[74:77], v[156:159], v[204:207], v[74:77]
	s_setprio 0
	s_setprio 1
	v_mfma_f32_16x16x32_bf16 v[118:121], v[160:163], v[176:179], v[118:121]
	v_mfma_f32_16x16x32_bf16 v[114:117], v[168:171], v[176:179], v[114:117]
	v_mfma_f32_16x16x32_bf16 v[102:105], v[160:163], v[184:187], v[102:105]
	v_mfma_f32_16x16x32_bf16 v[98:101], v[168:171], v[184:187], v[98:101]
	v_mfma_f32_16x16x32_bf16 v[86:89], v[160:163], v[192:195], v[86:89]
	v_mfma_f32_16x16x32_bf16 v[82:85], v[168:171], v[192:195], v[82:85]
	v_mfma_f32_16x16x32_bf16 v[70:73], v[160:163], v[200:203], v[70:73]
	v_mfma_f32_16x16x32_bf16 v[66:69], v[168:171], v[200:203], v[66:69]
	v_mfma_f32_16x16x32_bf16 v[118:121], v[164:167], v[180:183], v[118:121]
	v_mfma_f32_16x16x32_bf16 v[114:117], v[172:175], v[180:183], v[114:117]
	v_mfma_f32_16x16x32_bf16 v[102:105], v[164:167], v[188:191], v[102:105]
	v_mfma_f32_16x16x32_bf16 v[98:101], v[172:175], v[188:191], v[98:101]
	v_mfma_f32_16x16x32_bf16 v[86:89], v[164:167], v[196:199], v[86:89]
	v_mfma_f32_16x16x32_bf16 v[82:85], v[172:175], v[196:199], v[82:85]
	v_mfma_f32_16x16x32_bf16 v[70:73], v[164:167], v[204:207], v[70:73]
	v_mfma_f32_16x16x32_bf16 v[66:69], v[172:175], v[204:207], v[66:69]
	s_setprio 0
	s_barrier
	s_add_i32 s28, s48, s33
	v_lshl_add_u64 v[208:209], s[34:35], 0, v[132:133]
	s_mov_b32 m0, s28
	s_nop 0
	global_load_lds_dwordx4 v[208:209], off
	s_add_i32 m0, s28, 0x2000
	s_add_u32 s28, s34, 0x100000
	v_lshl_add_u64 v[210:211], s[34:35], 0, v[130:131]
	s_addc_u32 s29, s35, 0
	s_add_i32 s57, s49, s33
	global_load_lds_dwordx4 v[210:211], off
	v_lshl_add_u64 v[212:213], s[28:29], 0, v[132:133]
	s_mov_b32 m0, s57
	v_lshl_add_u64 v[214:215], s[36:37], 0, v[130:131]
	global_load_lds_dwordx4 v[212:213], off
	v_lshl_add_u64 v[212:213], s[28:29], 0, v[130:131]
	s_add_i32 m0, s57, 0x2000
	s_nop 0
	global_load_lds_dwordx4 v[212:213], off
	v_lshl_add_u64 v[212:213], s[36:37], 0, v[132:133]
	s_mov_b32 m0, s39
	s_nop 0
	global_load_lds_dwordx4 v[212:213], off
	s_mov_b32 m0, s40
	s_nop 0
	global_load_lds_dwordx4 v[214:215], off
	ds_read_b128 v[176:179], v146 offset:16384
	ds_read_b128 v[180:183], v146 offset:17408
	ds_read_b128 v[184:187], v146 offset:18432
	ds_read_b128 v[188:191], v146 offset:19456
	ds_read_b128 v[192:195], v146 offset:20480
	ds_read_b128 v[196:199], v146 offset:21504
	ds_read_b128 v[200:203], v146 offset:22528
	ds_read_b128 v[204:207], v146 offset:23552
	s_waitcnt vmcnt(8)
	s_waitcnt lgkmcnt(0)
	s_barrier
	s_setprio 1
	s_waitcnt lgkmcnt(0)
	v_mfma_f32_16x16x32_bf16 v[62:65], v[138:141], v[176:179], v[62:65]
	v_mfma_f32_16x16x32_bf16 v[58:61], v[152:155], v[176:179], v[58:61]
	v_mfma_f32_16x16x32_bf16 v[46:49], v[138:141], v[184:187], v[46:49]
	v_mfma_f32_16x16x32_bf16 v[42:45], v[152:155], v[184:187], v[42:45]
	v_mfma_f32_16x16x32_bf16 v[30:33], v[138:141], v[192:195], v[30:33]
	v_mfma_f32_16x16x32_bf16 v[26:29], v[152:155], v[192:195], v[26:29]
	v_mfma_f32_16x16x32_bf16 v[14:17], v[138:141], v[200:203], v[14:17]
	v_mfma_f32_16x16x32_bf16 v[10:13], v[152:155], v[200:203], v[10:13]
	v_mfma_f32_16x16x32_bf16 v[62:65], v[148:151], v[180:183], v[62:65]
	v_mfma_f32_16x16x32_bf16 v[58:61], v[156:159], v[180:183], v[58:61]
	v_mfma_f32_16x16x32_bf16 v[46:49], v[148:151], v[188:191], v[46:49]
	v_mfma_f32_16x16x32_bf16 v[42:45], v[156:159], v[188:191], v[42:45]
	v_mfma_f32_16x16x32_bf16 v[30:33], v[148:151], v[196:199], v[30:33]
	v_mfma_f32_16x16x32_bf16 v[26:29], v[156:159], v[196:199], v[26:29]
	v_mfma_f32_16x16x32_bf16 v[14:17], v[148:151], v[204:207], v[14:17]
	v_mfma_f32_16x16x32_bf16 v[10:13], v[156:159], v[204:207], v[10:13]
	s_setprio 0
	s_setprio 1
	v_mfma_f32_16x16x32_bf16 v[54:57], v[160:163], v[176:179], v[54:57]
	v_mfma_f32_16x16x32_bf16 v[50:53], v[168:171], v[176:179], v[50:53]
	v_mfma_f32_16x16x32_bf16 v[38:41], v[160:163], v[184:187], v[38:41]
	v_mfma_f32_16x16x32_bf16 v[34:37], v[168:171], v[184:187], v[34:37]
	v_mfma_f32_16x16x32_bf16 v[22:25], v[160:163], v[192:195], v[22:25]
	v_mfma_f32_16x16x32_bf16 v[18:21], v[168:171], v[192:195], v[18:21]
	v_mfma_f32_16x16x32_bf16 v[6:9], v[160:163], v[200:203], v[6:9]
	v_mfma_f32_16x16x32_bf16 v[2:5], v[168:171], v[200:203], v[2:5]
	v_mfma_f32_16x16x32_bf16 v[54:57], v[164:167], v[180:183], v[54:57]
	v_mfma_f32_16x16x32_bf16 v[50:53], v[172:175], v[180:183], v[50:53]
	v_mfma_f32_16x16x32_bf16 v[38:41], v[164:167], v[188:191], v[38:41]
	v_mfma_f32_16x16x32_bf16 v[34:37], v[172:175], v[188:191], v[34:37]
	v_mfma_f32_16x16x32_bf16 v[22:25], v[164:167], v[196:199], v[22:25]
	v_mfma_f32_16x16x32_bf16 v[18:21], v[172:175], v[196:199], v[18:21]
	v_mfma_f32_16x16x32_bf16 v[6:9], v[164:167], v[204:207], v[6:9]
	v_mfma_f32_16x16x32_bf16 v[2:5], v[172:175], v[204:207], v[2:5]
	s_setprio 0
	s_barrier
	s_add_i32 s57, 0, 0x18000
	s_add_i32 s58, 0, 0x1c000
	s_add_u32 s28, s36, 0x100000
	s_addc_u32 s29, s37, 0
	s_mov_b32 m0, s41
	v_lshl_add_u64 v[216:217], s[28:29], 0, v[132:133]
	global_load_lds_dwordx4 v[216:217], off
	v_lshl_add_u64 v[216:217], s[28:29], 0, v[130:131]
	s_mov_b32 m0, s42
	s_nop 0
	global_load_lds_dwordx4 v[216:217], off
	v_add_u32_e32 v156, s57, v143
	v_add_u32_e32 v172, s58, v143
	ds_read_b128 v[138:141], v156
	ds_read_b128 v[148:151], v156 offset:1024
	ds_read_b128 v[152:155], v156 offset:2048
	ds_read_b128 v[156:159], v156 offset:3072
	ds_read_b128 v[160:163], v172
	ds_read_b128 v[164:167], v172 offset:1024
	ds_read_b128 v[168:171], v172 offset:2048
	ds_read_b128 v[172:175], v172 offset:3072
	ds_read_b128 v[176:179], v146 offset:32768
	ds_read_b128 v[180:183], v146 offset:33792
	ds_read_b128 v[184:187], v146 offset:34816
	ds_read_b128 v[188:191], v146 offset:35840
	ds_read_b128 v[192:195], v146 offset:36864
	ds_read_b128 v[196:199], v146 offset:37888
	ds_read_b128 v[200:203], v146 offset:38912
	ds_read_b128 v[204:207], v146 offset:39936
	s_waitcnt vmcnt(8)
	s_waitcnt lgkmcnt(0)
	s_barrier
	s_setprio 1
	s_waitcnt lgkmcnt(0)
	v_mfma_f32_16x16x32_bf16 v[126:129], v[138:141], v[176:179], v[126:129]
	v_mfma_f32_16x16x32_bf16 v[122:125], v[152:155], v[176:179], v[122:125]
	v_mfma_f32_16x16x32_bf16 v[110:113], v[138:141], v[184:187], v[110:113]
	v_mfma_f32_16x16x32_bf16 v[106:109], v[152:155], v[184:187], v[106:109]
	v_mfma_f32_16x16x32_bf16 v[94:97], v[138:141], v[192:195], v[94:97]
	v_mfma_f32_16x16x32_bf16 v[90:93], v[152:155], v[192:195], v[90:93]
	v_mfma_f32_16x16x32_bf16 v[78:81], v[138:141], v[200:203], v[78:81]
	v_mfma_f32_16x16x32_bf16 v[74:77], v[152:155], v[200:203], v[74:77]
	v_mfma_f32_16x16x32_bf16 v[126:129], v[148:151], v[180:183], v[126:129]
	v_mfma_f32_16x16x32_bf16 v[122:125], v[156:159], v[180:183], v[122:125]
	v_mfma_f32_16x16x32_bf16 v[110:113], v[148:151], v[188:191], v[110:113]
	v_mfma_f32_16x16x32_bf16 v[106:109], v[156:159], v[188:191], v[106:109]
	v_mfma_f32_16x16x32_bf16 v[94:97], v[148:151], v[196:199], v[94:97]
	v_mfma_f32_16x16x32_bf16 v[90:93], v[156:159], v[196:199], v[90:93]
	v_mfma_f32_16x16x32_bf16 v[78:81], v[148:151], v[204:207], v[78:81]
	v_mfma_f32_16x16x32_bf16 v[74:77], v[156:159], v[204:207], v[74:77]
	s_setprio 0
	s_setprio 1
	v_mfma_f32_16x16x32_bf16 v[118:121], v[160:163], v[176:179], v[118:121]
	v_mfma_f32_16x16x32_bf16 v[114:117], v[168:171], v[176:179], v[114:117]
	v_mfma_f32_16x16x32_bf16 v[102:105], v[160:163], v[184:187], v[102:105]
	v_mfma_f32_16x16x32_bf16 v[98:101], v[168:171], v[184:187], v[98:101]
	v_mfma_f32_16x16x32_bf16 v[86:89], v[160:163], v[192:195], v[86:89]
	v_mfma_f32_16x16x32_bf16 v[82:85], v[168:171], v[192:195], v[82:85]
	v_mfma_f32_16x16x32_bf16 v[70:73], v[160:163], v[200:203], v[70:73]
	v_mfma_f32_16x16x32_bf16 v[66:69], v[168:171], v[200:203], v[66:69]
	v_mfma_f32_16x16x32_bf16 v[118:121], v[164:167], v[180:183], v[118:121]
	v_mfma_f32_16x16x32_bf16 v[114:117], v[172:175], v[180:183], v[114:117]
	v_mfma_f32_16x16x32_bf16 v[102:105], v[164:167], v[188:191], v[102:105]
	v_mfma_f32_16x16x32_bf16 v[98:101], v[172:175], v[188:191], v[98:101]
	v_mfma_f32_16x16x32_bf16 v[86:89], v[164:167], v[196:199], v[86:89]
	v_mfma_f32_16x16x32_bf16 v[82:85], v[172:175], v[196:199], v[82:85]
	v_mfma_f32_16x16x32_bf16 v[70:73], v[164:167], v[204:207], v[70:73]
	v_mfma_f32_16x16x32_bf16 v[66:69], v[172:175], v[204:207], v[66:69]
	s_setprio 0
	s_barrier
	s_add_i32 s28, s57, s33
	v_lshl_add_u64 v[208:209], v[208:209], 0, s[16:17]
	s_mov_b32 m0, s28
	s_nop 0
	global_load_lds_dwordx4 v[208:209], off
	s_add_i32 m0, s28, 0x2000
	s_add_u32 s28, s34, 0x100080
	v_lshl_add_u64 v[208:209], v[210:211], 0, s[16:17]
	s_addc_u32 s29, s35, 0
	s_add_i32 s34, s58, s33
	global_load_lds_dwordx4 v[208:209], off
	v_lshl_add_u64 v[208:209], s[28:29], 0, v[132:133]
	s_mov_b32 m0, s34
	s_nop 0
	global_load_lds_dwordx4 v[208:209], off
	v_lshl_add_u64 v[208:209], s[28:29], 0, v[130:131]
	s_add_i32 m0, s34, 0x2000
	s_nop 0
	global_load_lds_dwordx4 v[208:209], off
	v_lshl_add_u64 v[208:209], v[212:213], 0, s[16:17]
	s_mov_b32 m0, s45
	s_nop 0
	global_load_lds_dwordx4 v[208:209], off
	v_lshl_add_u64 v[208:209], v[214:215], 0, s[16:17]
	s_mov_b32 m0, s46
	s_nop 0
	global_load_lds_dwordx4 v[208:209], off
	ds_read_b128 v[176:179], v146 offset:49152
	ds_read_b128 v[180:183], v146 offset:50176
	ds_read_b128 v[184:187], v146 offset:51200
	ds_read_b128 v[188:191], v146 offset:52224
	ds_read_b128 v[192:195], v146 offset:53248
	ds_read_b128 v[196:199], v146 offset:54272
	ds_read_b128 v[200:203], v146 offset:55296
	ds_read_b128 v[204:207], v146 offset:56320
	s_waitcnt vmcnt(8)
	s_waitcnt lgkmcnt(0)
	s_barrier
	s_setprio 1
	s_waitcnt lgkmcnt(0)
	v_mfma_f32_16x16x32_bf16 v[62:65], v[138:141], v[176:179], v[62:65]
	v_mfma_f32_16x16x32_bf16 v[58:61], v[152:155], v[176:179], v[58:61]
	v_mfma_f32_16x16x32_bf16 v[46:49], v[138:141], v[184:187], v[46:49]
	v_mfma_f32_16x16x32_bf16 v[42:45], v[152:155], v[184:187], v[42:45]
	v_mfma_f32_16x16x32_bf16 v[30:33], v[138:141], v[192:195], v[30:33]
	v_mfma_f32_16x16x32_bf16 v[26:29], v[152:155], v[192:195], v[26:29]
	v_mfma_f32_16x16x32_bf16 v[14:17], v[138:141], v[200:203], v[14:17]
	v_mfma_f32_16x16x32_bf16 v[10:13], v[152:155], v[200:203], v[10:13]
	v_mfma_f32_16x16x32_bf16 v[62:65], v[148:151], v[180:183], v[62:65]
	v_mfma_f32_16x16x32_bf16 v[58:61], v[156:159], v[180:183], v[58:61]
	v_mfma_f32_16x16x32_bf16 v[46:49], v[148:151], v[188:191], v[46:49]
	v_mfma_f32_16x16x32_bf16 v[42:45], v[156:159], v[188:191], v[42:45]
	v_mfma_f32_16x16x32_bf16 v[30:33], v[148:151], v[196:199], v[30:33]
	v_mfma_f32_16x16x32_bf16 v[26:29], v[156:159], v[196:199], v[26:29]
	v_mfma_f32_16x16x32_bf16 v[14:17], v[148:151], v[204:207], v[14:17]
	v_mfma_f32_16x16x32_bf16 v[10:13], v[156:159], v[204:207], v[10:13]
	s_setprio 0
	s_setprio 1
	v_mfma_f32_16x16x32_bf16 v[54:57], v[160:163], v[176:179], v[54:57]
	v_mfma_f32_16x16x32_bf16 v[50:53], v[168:171], v[176:179], v[50:53]
	v_mfma_f32_16x16x32_bf16 v[38:41], v[160:163], v[184:187], v[38:41]
	v_mfma_f32_16x16x32_bf16 v[34:37], v[168:171], v[184:187], v[34:37]
	v_mfma_f32_16x16x32_bf16 v[22:25], v[160:163], v[192:195], v[22:25]
	v_mfma_f32_16x16x32_bf16 v[18:21], v[168:171], v[192:195], v[18:21]
	v_mfma_f32_16x16x32_bf16 v[6:9], v[160:163], v[200:203], v[6:9]
	v_mfma_f32_16x16x32_bf16 v[2:5], v[168:171], v[200:203], v[2:5]
	v_mfma_f32_16x16x32_bf16 v[54:57], v[164:167], v[180:183], v[54:57]
	v_mfma_f32_16x16x32_bf16 v[50:53], v[172:175], v[180:183], v[50:53]
	v_mfma_f32_16x16x32_bf16 v[38:41], v[164:167], v[188:191], v[38:41]
	v_mfma_f32_16x16x32_bf16 v[34:37], v[172:175], v[188:191], v[34:37]
	v_mfma_f32_16x16x32_bf16 v[22:25], v[164:167], v[196:199], v[22:25]
	v_mfma_f32_16x16x32_bf16 v[18:21], v[172:175], v[196:199], v[18:21]
	v_mfma_f32_16x16x32_bf16 v[6:9], v[164:167], v[204:207], v[6:9]
	v_mfma_f32_16x16x32_bf16 v[2:5], v[172:175], v[204:207], v[2:5]
	s_setprio 0
	s_barrier
	s_add_i32 s56, s56, 2
	s_cmp_gt_u32 s56, 61
	s_mov_b64 s[28:29], s[30:31]
	s_cbranch_scc0 .LBB0_806
	s_and_b64 vcc, exec, s[18:19]
	s_cbranch_vccz .LBB0_809
	s_barrier

.LBB0_910:
	s_add_u32 s30, s6, 0xfff80080
	s_addc_u32 s31, s7, -1
	s_cmp_eq_u32 s58, 28
	s_cselect_b32 s35, s13, s31
	s_cselect_b32 s34, s12, s30
	s_cselect_b32 s31, s1, s57
	s_cselect_b32 s30, s55, s56
	s_mov_b32 m0, s49
	v_lshl_add_u64 v[154:155], s[6:7], 0, v[146:147]
	global_load_lds_dwordx4 v[154:155], off
	v_lshl_add_u64 v[154:155], s[6:7], 0, v[148:149]
	s_mov_b32 m0, s50
	s_nop 0
	global_load_lds_dwordx4 v[154:155], off
	ds_read_b128 v[130:133], v157
	ds_read_b128 v[134:137], v157 offset:1024
	ds_read_b128 v[164:167], v157 offset:2048
	ds_read_b128 v[168:171], v157 offset:3072
	ds_read_b128 v[172:175], v159
	ds_read_b128 v[176:179], v159 offset:1024
	ds_read_b128 v[180:183], v159 offset:2048
	ds_read_b128 v[184:187], v159 offset:3072
	ds_read_b128 v[188:191], v161
	ds_read_b128 v[192:195], v161 offset:1024
	ds_read_b128 v[196:199], v161 offset:2048
	ds_read_b128 v[200:203], v161 offset:3072
	ds_read_b128 v[204:207], v161 offset:4096
	ds_read_b128 v[208:211], v161 offset:5120
	ds_read_b128 v[212:215], v161 offset:6144
	ds_read_b128 v[216:219], v161 offset:7168
	s_waitcnt vmcnt(8)
	s_waitcnt lgkmcnt(0)
	s_barrier
	s_setprio 1
	s_waitcnt lgkmcnt(0)
	v_mfma_f32_16x16x32_bf16 v[126:129], v[130:133], v[188:191], v[126:129]
	v_mfma_f32_16x16x32_bf16 v[122:125], v[164:167], v[188:191], v[122:125]
	v_mfma_f32_16x16x32_bf16 v[118:121], v[130:133], v[196:199], v[118:121]
	v_mfma_f32_16x16x32_bf16 v[110:113], v[164:167], v[196:199], v[110:113]
	v_mfma_f32_16x16x32_bf16 v[102:105], v[130:133], v[204:207], v[102:105]
	v_mfma_f32_16x16x32_bf16 v[94:97], v[164:167], v[204:207], v[94:97]
	v_mfma_f32_16x16x32_bf16 v[86:89], v[130:133], v[212:215], v[86:89]
	v_mfma_f32_16x16x32_bf16 v[78:81], v[164:167], v[212:215], v[78:81]
	v_mfma_f32_16x16x32_bf16 v[126:129], v[134:137], v[192:195], v[126:129]
	v_mfma_f32_16x16x32_bf16 v[122:125], v[168:171], v[192:195], v[122:125]
	v_mfma_f32_16x16x32_bf16 v[118:121], v[134:137], v[200:203], v[118:121]
	v_mfma_f32_16x16x32_bf16 v[110:113], v[168:171], v[200:203], v[110:113]
	v_mfma_f32_16x16x32_bf16 v[102:105], v[134:137], v[208:211], v[102:105]
	v_mfma_f32_16x16x32_bf16 v[94:97], v[168:171], v[208:211], v[94:97]
	v_mfma_f32_16x16x32_bf16 v[86:89], v[134:137], v[216:219], v[86:89]
	v_mfma_f32_16x16x32_bf16 v[78:81], v[168:171], v[216:219], v[78:81]
	s_setprio 0
	s_setprio 1
	v_mfma_f32_16x16x32_bf16 v[114:117], v[172:175], v[188:191], v[114:117]
	v_mfma_f32_16x16x32_bf16 v[106:109], v[180:183], v[188:191], v[106:109]
	v_mfma_f32_16x16x32_bf16 v[98:101], v[172:175], v[196:199], v[98:101]
	v_mfma_f32_16x16x32_bf16 v[90:93], v[180:183], v[196:199], v[90:93]
	v_mfma_f32_16x16x32_bf16 v[82:85], v[172:175], v[204:207], v[82:85]
	v_mfma_f32_16x16x32_bf16 v[74:77], v[180:183], v[204:207], v[74:77]
	v_mfma_f32_16x16x32_bf16 v[70:73], v[172:175], v[212:215], v[70:73]
	v_mfma_f32_16x16x32_bf16 v[66:69], v[180:183], v[212:215], v[66:69]
	v_mfma_f32_16x16x32_bf16 v[114:117], v[176:179], v[192:195], v[114:117]
	v_mfma_f32_16x16x32_bf16 v[106:109], v[184:187], v[192:195], v[106:109]
	v_mfma_f32_16x16x32_bf16 v[98:101], v[176:179], v[200:203], v[98:101]
	v_mfma_f32_16x16x32_bf16 v[90:93], v[184:187], v[200:203], v[90:93]
	v_mfma_f32_16x16x32_bf16 v[82:85], v[176:179], v[208:211], v[82:85]
	v_mfma_f32_16x16x32_bf16 v[74:77], v[184:187], v[208:211], v[74:77]
	v_mfma_f32_16x16x32_bf16 v[70:73], v[176:179], v[216:219], v[70:73]
	v_mfma_f32_16x16x32_bf16 v[66:69], v[184:187], v[216:219], v[66:69]
	s_setprio 0
	s_barrier
	s_mov_b32 m0, s51
	v_lshl_add_u64 v[154:155], s[30:31], 0, v[142:143]
	global_load_lds_dwordx4 v[154:155], off
	s_add_i32 m0, s51, 0x2000
	s_add_u32 s60, s30, 0x80000
	v_lshl_add_u64 v[220:221], s[30:31], 0, v[138:139]
	s_addc_u32 s61, s31, 0
	s_add_i32 s59, s48, s36
	global_load_lds_dwordx4 v[220:221], off
	v_lshl_add_u64 v[222:223], s[60:61], 0, v[142:143]
	s_mov_b32 m0, s59
	v_lshl_add_u64 v[224:225], s[34:35], 0, v[140:141]
	global_load_lds_dwordx4 v[222:223], off
	v_lshl_add_u64 v[222:223], s[60:61], 0, v[138:139]
	s_add_i32 m0, s59, 0x2000
	s_nop 0
	global_load_lds_dwordx4 v[222:223], off
	v_lshl_add_u64 v[222:223], s[34:35], 0, v[144:145]
	s_mov_b32 m0, s37
	s_nop 0
	global_load_lds_dwordx4 v[222:223], off
	s_mov_b32 m0, s40
	s_nop 0
	global_load_lds_dwordx4 v[224:225], off
	ds_read_b128 v[188:191], v161 offset:16384
	ds_read_b128 v[192:195], v161 offset:17408
	ds_read_b128 v[196:199], v161 offset:18432
	ds_read_b128 v[200:203], v161 offset:19456
	ds_read_b128 v[204:207], v161 offset:20480
	ds_read_b128 v[208:211], v161 offset:21504
	ds_read_b128 v[212:215], v161 offset:22528
	ds_read_b128 v[216:219], v161 offset:23552
	s_waitcnt vmcnt(8)
	s_waitcnt lgkmcnt(0)
	s_barrier
	s_setprio 1
	s_waitcnt lgkmcnt(0)
	v_mfma_f32_16x16x32_bf16 v[62:65], v[130:133], v[188:191], v[62:65]
	v_mfma_f32_16x16x32_bf16 v[58:61], v[164:167], v[188:191], v[58:61]
	v_mfma_f32_16x16x32_bf16 v[54:57], v[130:133], v[196:199], v[54:57]
	v_mfma_f32_16x16x32_bf16 v[46:49], v[164:167], v[196:199], v[46:49]
	v_mfma_f32_16x16x32_bf16 v[38:41], v[130:133], v[204:207], v[38:41]
	v_mfma_f32_16x16x32_bf16 v[30:33], v[164:167], v[204:207], v[30:33]
	v_mfma_f32_16x16x32_bf16 v[22:25], v[130:133], v[212:215], v[22:25]
	v_mfma_f32_16x16x32_bf16 v[14:17], v[164:167], v[212:215], v[14:17]
	v_mfma_f32_16x16x32_bf16 v[62:65], v[134:137], v[192:195], v[62:65]
	v_mfma_f32_16x16x32_bf16 v[58:61], v[168:171], v[192:195], v[58:61]
	v_mfma_f32_16x16x32_bf16 v[54:57], v[134:137], v[200:203], v[54:57]
	v_mfma_f32_16x16x32_bf16 v[46:49], v[168:171], v[200:203], v[46:49]
	v_mfma_f32_16x16x32_bf16 v[38:41], v[134:137], v[208:211], v[38:41]
	v_mfma_f32_16x16x32_bf16 v[30:33], v[168:171], v[208:211], v[30:33]
	v_mfma_f32_16x16x32_bf16 v[22:25], v[134:137], v[216:219], v[22:25]
	v_mfma_f32_16x16x32_bf16 v[14:17], v[168:171], v[216:219], v[14:17]
	s_setprio 0
	s_setprio 1
	v_mfma_f32_16x16x32_bf16 v[50:53], v[172:175], v[188:191], v[50:53]
	v_mfma_f32_16x16x32_bf16 v[42:45], v[180:183], v[188:191], v[42:45]
	v_mfma_f32_16x16x32_bf16 v[34:37], v[172:175], v[196:199], v[34:37]
	v_mfma_f32_16x16x32_bf16 v[26:29], v[180:183], v[196:199], v[26:29]
	v_mfma_f32_16x16x32_bf16 v[18:21], v[172:175], v[204:207], v[18:21]
	v_mfma_f32_16x16x32_bf16 v[10:13], v[180:183], v[204:207], v[10:13]
	v_mfma_f32_16x16x32_bf16 v[6:9], v[172:175], v[212:215], v[6:9]
	v_mfma_f32_16x16x32_bf16 v[2:5], v[180:183], v[212:215], v[2:5]
	v_mfma_f32_16x16x32_bf16 v[50:53], v[176:179], v[192:195], v[50:53]
	v_mfma_f32_16x16x32_bf16 v[42:45], v[184:187], v[192:195], v[42:45]
	v_mfma_f32_16x16x32_bf16 v[34:37], v[176:179], v[200:203], v[34:37]
	v_mfma_f32_16x16x32_bf16 v[26:29], v[184:187], v[200:203], v[26:29]
	v_mfma_f32_16x16x32_bf16 v[18:21], v[176:179], v[208:211], v[18:21]
	v_mfma_f32_16x16x32_bf16 v[10:13], v[184:187], v[208:211], v[10:13]
	v_mfma_f32_16x16x32_bf16 v[6:9], v[176:179], v[216:219], v[6:9]
	v_mfma_f32_16x16x32_bf16 v[2:5], v[184:187], v[216:219], v[2:5]
	s_setprio 0
	s_barrier
	s_add_i32 s59, 0, 0x18000
	s_add_i32 s60, 0, 0x1c000
	s_add_u32 s34, s34, 0x80000
	s_addc_u32 s35, s35, 0
	s_mov_b32 m0, s41
	v_lshl_add_u64 v[226:227], s[34:35], 0, v[144:145]
	global_load_lds_dwordx4 v[226:227], off
	v_lshl_add_u64 v[226:227], s[34:35], 0, v[140:141]
	s_mov_b32 m0, s42
	s_nop 0
	global_load_lds_dwordx4 v[226:227], off
	v_add_u32_e32 v150, s59, v153
	ds_read_b128 v[130:133], v150
	ds_read_b128 v[134:137], v150 offset:1024
	ds_read_b128 v[164:167], v150 offset:2048
	ds_read_b128 v[168:171], v150 offset:3072
	v_add_u32_e32 v150, s60, v153
	ds_read_b128 v[172:175], v150
	ds_read_b128 v[176:179], v150 offset:1024
	ds_read_b128 v[180:183], v150 offset:2048
	ds_read_b128 v[184:187], v150 offset:3072
	ds_read_b128 v[188:191], v161 offset:32768
	ds_read_b128 v[192:195], v161 offset:33792
	ds_read_b128 v[196:199], v161 offset:34816
	ds_read_b128 v[200:203], v161 offset:35840
	ds_read_b128 v[204:207], v161 offset:36864
	ds_read_b128 v[208:211], v161 offset:37888
	ds_read_b128 v[212:215], v161 offset:38912
	ds_read_b128 v[216:219], v161 offset:39936
	s_waitcnt vmcnt(8)
	s_waitcnt lgkmcnt(0)
	s_barrier
	s_setprio 1
	s_waitcnt lgkmcnt(0)
	v_mfma_f32_16x16x32_bf16 v[126:129], v[130:133], v[188:191], v[126:129]
	v_mfma_f32_16x16x32_bf16 v[122:125], v[164:167], v[188:191], v[122:125]
	v_mfma_f32_16x16x32_bf16 v[118:121], v[130:133], v[196:199], v[118:121]
	v_mfma_f32_16x16x32_bf16 v[110:113], v[164:167], v[196:199], v[110:113]
	v_mfma_f32_16x16x32_bf16 v[102:105], v[130:133], v[204:207], v[102:105]
	v_mfma_f32_16x16x32_bf16 v[94:97], v[164:167], v[204:207], v[94:97]
	v_mfma_f32_16x16x32_bf16 v[86:89], v[130:133], v[212:215], v[86:89]
	v_mfma_f32_16x16x32_bf16 v[78:81], v[164:167], v[212:215], v[78:81]
	v_mfma_f32_16x16x32_bf16 v[126:129], v[134:137], v[192:195], v[126:129]
	v_mfma_f32_16x16x32_bf16 v[122:125], v[168:171], v[192:195], v[122:125]
	v_mfma_f32_16x16x32_bf16 v[118:121], v[134:137], v[200:203], v[118:121]
	v_mfma_f32_16x16x32_bf16 v[110:113], v[168:171], v[200:203], v[110:113]
	v_mfma_f32_16x16x32_bf16 v[102:105], v[134:137], v[208:211], v[102:105]
	v_mfma_f32_16x16x32_bf16 v[94:97], v[168:171], v[208:211], v[94:97]
	v_mfma_f32_16x16x32_bf16 v[86:89], v[134:137], v[216:219], v[86:89]
	v_mfma_f32_16x16x32_bf16 v[78:81], v[168:171], v[216:219], v[78:81]
	s_setprio 0
	s_setprio 1
	v_mfma_f32_16x16x32_bf16 v[114:117], v[172:175], v[188:191], v[114:117]
	v_mfma_f32_16x16x32_bf16 v[106:109], v[180:183], v[188:191], v[106:109]
	v_mfma_f32_16x16x32_bf16 v[98:101], v[172:175], v[196:199], v[98:101]
	v_mfma_f32_16x16x32_bf16 v[90:93], v[180:183], v[196:199], v[90:93]
	v_mfma_f32_16x16x32_bf16 v[82:85], v[172:175], v[204:207], v[82:85]
	v_mfma_f32_16x16x32_bf16 v[74:77], v[180:183], v[204:207], v[74:77]
	v_mfma_f32_16x16x32_bf16 v[70:73], v[172:175], v[212:215], v[70:73]
	v_mfma_f32_16x16x32_bf16 v[66:69], v[180:183], v[212:215], v[66:69]
	v_mfma_f32_16x16x32_bf16 v[114:117], v[176:179], v[192:195], v[114:117]
	v_mfma_f32_16x16x32_bf16 v[106:109], v[184:187], v[192:195], v[106:109]
	v_mfma_f32_16x16x32_bf16 v[98:101], v[176:179], v[200:203], v[98:101]
	v_mfma_f32_16x16x32_bf16 v[90:93], v[184:187], v[200:203], v[90:93]
	v_mfma_f32_16x16x32_bf16 v[82:85], v[176:179], v[208:211], v[82:85]
	v_mfma_f32_16x16x32_bf16 v[74:77], v[184:187], v[208:211], v[74:77]
	v_mfma_f32_16x16x32_bf16 v[70:73], v[176:179], v[216:219], v[70:73]
	v_mfma_f32_16x16x32_bf16 v[66:69], v[184:187], v[216:219], v[66:69]
	s_setprio 0
	s_barrier
	s_add_i32 s34, s59, s36
	v_lshl_add_u64 v[154:155], v[154:155], 0, s[16:17]
	s_mov_b32 m0, s34
	s_nop 0
	global_load_lds_dwordx4 v[154:155], off
	s_add_i32 m0, s34, 0x2000
	s_add_u32 s30, s30, 0x80080
	v_lshl_add_u64 v[154:155], v[220:221], 0, s[16:17]
	s_addc_u32 s31, s31, 0
	s_add_i32 s34, s60, s36
	global_load_lds_dwordx4 v[154:155], off
	v_lshl_add_u64 v[154:155], s[30:31], 0, v[142:143]
	s_mov_b32 m0, s34
	s_nop 0
	global_load_lds_dwordx4 v[154:155], off
	v_lshl_add_u64 v[154:155], s[30:31], 0, v[138:139]
	s_add_i32 m0, s34, 0x2000
	s_nop 0
	global_load_lds_dwordx4 v[154:155], off
	v_lshl_add_u64 v[154:155], v[222:223], 0, s[16:17]
	s_mov_b32 m0, s45
	s_nop 0
	global_load_lds_dwordx4 v[154:155], off
	v_lshl_add_u64 v[154:155], v[224:225], 0, s[16:17]
	s_mov_b32 m0, s46
	s_nop 0
	global_load_lds_dwordx4 v[154:155], off
	ds_read_b128 v[188:191], v161 offset:49152
	ds_read_b128 v[192:195], v161 offset:50176
	ds_read_b128 v[196:199], v161 offset:51200
	ds_read_b128 v[200:203], v161 offset:52224
	ds_read_b128 v[204:207], v161 offset:53248
	ds_read_b128 v[208:211], v161 offset:54272
	ds_read_b128 v[212:215], v161 offset:55296
	ds_read_b128 v[216:219], v161 offset:56320
	s_waitcnt vmcnt(8)
	s_waitcnt lgkmcnt(0)
	s_barrier
	s_setprio 1
	s_waitcnt lgkmcnt(0)
	v_mfma_f32_16x16x32_bf16 v[62:65], v[130:133], v[188:191], v[62:65]
	v_mfma_f32_16x16x32_bf16 v[58:61], v[164:167], v[188:191], v[58:61]
	v_mfma_f32_16x16x32_bf16 v[54:57], v[130:133], v[196:199], v[54:57]
	v_mfma_f32_16x16x32_bf16 v[46:49], v[164:167], v[196:199], v[46:49]
	v_mfma_f32_16x16x32_bf16 v[38:41], v[130:133], v[204:207], v[38:41]
	v_mfma_f32_16x16x32_bf16 v[30:33], v[164:167], v[204:207], v[30:33]
	v_mfma_f32_16x16x32_bf16 v[22:25], v[130:133], v[212:215], v[22:25]
	v_mfma_f32_16x16x32_bf16 v[14:17], v[164:167], v[212:215], v[14:17]
	v_mfma_f32_16x16x32_bf16 v[62:65], v[134:137], v[192:195], v[62:65]
	v_mfma_f32_16x16x32_bf16 v[58:61], v[168:171], v[192:195], v[58:61]
	v_mfma_f32_16x16x32_bf16 v[54:57], v[134:137], v[200:203], v[54:57]
	v_mfma_f32_16x16x32_bf16 v[46:49], v[168:171], v[200:203], v[46:49]
	v_mfma_f32_16x16x32_bf16 v[38:41], v[134:137], v[208:211], v[38:41]
	v_mfma_f32_16x16x32_bf16 v[30:33], v[168:171], v[208:211], v[30:33]
	v_mfma_f32_16x16x32_bf16 v[22:25], v[134:137], v[216:219], v[22:25]
	v_mfma_f32_16x16x32_bf16 v[14:17], v[168:171], v[216:219], v[14:17]
	s_setprio 0
	s_setprio 1
	v_mfma_f32_16x16x32_bf16 v[50:53], v[172:175], v[188:191], v[50:53]
	v_mfma_f32_16x16x32_bf16 v[42:45], v[180:183], v[188:191], v[42:45]
	v_mfma_f32_16x16x32_bf16 v[34:37], v[172:175], v[196:199], v[34:37]
	v_mfma_f32_16x16x32_bf16 v[26:29], v[180:183], v[196:199], v[26:29]
	v_mfma_f32_16x16x32_bf16 v[18:21], v[172:175], v[204:207], v[18:21]
	v_mfma_f32_16x16x32_bf16 v[10:13], v[180:183], v[204:207], v[10:13]
	v_mfma_f32_16x16x32_bf16 v[6:9], v[172:175], v[212:215], v[6:9]
	v_mfma_f32_16x16x32_bf16 v[2:5], v[180:183], v[212:215], v[2:5]
	v_mfma_f32_16x16x32_bf16 v[50:53], v[176:179], v[192:195], v[50:53]
	v_mfma_f32_16x16x32_bf16 v[42:45], v[184:187], v[192:195], v[42:45]
	v_mfma_f32_16x16x32_bf16 v[34:37], v[176:179], v[200:203], v[34:37]
	v_mfma_f32_16x16x32_bf16 v[26:29], v[184:187], v[200:203], v[26:29]
	v_mfma_f32_16x16x32_bf16 v[18:21], v[176:179], v[208:211], v[18:21]
	v_mfma_f32_16x16x32_bf16 v[10:13], v[184:187], v[208:211], v[10:13]
	v_mfma_f32_16x16x32_bf16 v[6:9], v[176:179], v[216:219], v[6:9]
	v_mfma_f32_16x16x32_bf16 v[2:5], v[184:187], v[216:219], v[2:5]
	s_setprio 0
	s_barrier
	s_add_i32 s58, s58, 2
	s_add_u32 s6, s6, 0x100
	s_addc_u32 s7, s7, 0
	s_add_u32 s56, s56, 0x100
	s_addc_u32 s57, s57, 0
	s_cmp_gt_u32 s58, 29
	s_cbranch_scc0 .LBB0_910
	s_and_b64 vcc, exec, s[18:19]
	s_cbranch_vccz .LBB0_913
	s_barrier

.LBB0_1112:
	s_add_u32 s22, s20, 0x100
	s_addc_u32 s23, s21, 0
	s_add_u32 s24, s0, s20
	s_addc_u32 s25, s1, s21
	s_cmpk_eq_i32 s6, 0x54
	s_cselect_b32 s26, 0, s22
	s_cselect_b32 s27, 0, s23
	s_cselect_b32 s24, s16, s24
	s_cselect_b32 s25, s17, s25
	s_add_u32 s26, s2, s26
	s_addc_u32 s27, s3, s27
	s_mov_b32 m0, s41
	v_lshl_add_u64 v[210:211], v[134:135], 0, s[20:21]
	global_load_lds_dwordx4 v[210:211], off
	v_lshl_add_u64 v[210:211], v[136:137], 0, s[20:21]
	s_mov_b32 m0, s42
	s_nop 0
	global_load_lds_dwordx4 v[210:211], off
	ds_read_b128 v[138:141], v143
	ds_read_b128 v[150:153], v143 offset:1024
	ds_read_b128 v[154:157], v143 offset:2048
	ds_read_b128 v[158:161], v143 offset:3072
	ds_read_b128 v[162:165], v144
	ds_read_b128 v[166:169], v144 offset:1024
	ds_read_b128 v[170:173], v144 offset:2048
	ds_read_b128 v[174:177], v144 offset:3072
	ds_read_b128 v[178:181], v145
	ds_read_b128 v[182:185], v145 offset:1024
	ds_read_b128 v[186:189], v145 offset:2048
	ds_read_b128 v[190:193], v145 offset:3072
	ds_read_b128 v[194:197], v145 offset:4096
	ds_read_b128 v[198:201], v145 offset:5120
	ds_read_b128 v[202:205], v145 offset:6144
	ds_read_b128 v[206:209], v145 offset:7168
	s_waitcnt vmcnt(8)
	s_waitcnt lgkmcnt(0)
	s_barrier
	s_setprio 1
	s_waitcnt lgkmcnt(0)
	v_mfma_f32_16x16x32_bf16 v[126:129], v[138:141], v[178:181], v[126:129]
	v_mfma_f32_16x16x32_bf16 v[122:125], v[154:157], v[178:181], v[122:125]
	v_mfma_f32_16x16x32_bf16 v[110:113], v[138:141], v[186:189], v[110:113]
	v_mfma_f32_16x16x32_bf16 v[106:109], v[154:157], v[186:189], v[106:109]
	v_mfma_f32_16x16x32_bf16 v[94:97], v[138:141], v[194:197], v[94:97]
	v_mfma_f32_16x16x32_bf16 v[90:93], v[154:157], v[194:197], v[90:93]
	v_mfma_f32_16x16x32_bf16 v[78:81], v[138:141], v[202:205], v[78:81]
	v_mfma_f32_16x16x32_bf16 v[74:77], v[154:157], v[202:205], v[74:77]
	v_mfma_f32_16x16x32_bf16 v[126:129], v[150:153], v[182:185], v[126:129]
	v_mfma_f32_16x16x32_bf16 v[122:125], v[158:161], v[182:185], v[122:125]
	v_mfma_f32_16x16x32_bf16 v[110:113], v[150:153], v[190:193], v[110:113]
	v_mfma_f32_16x16x32_bf16 v[106:109], v[158:161], v[190:193], v[106:109]
	v_mfma_f32_16x16x32_bf16 v[94:97], v[150:153], v[198:201], v[94:97]
	v_mfma_f32_16x16x32_bf16 v[90:93], v[158:161], v[198:201], v[90:93]
	v_mfma_f32_16x16x32_bf16 v[78:81], v[150:153], v[206:209], v[78:81]
	v_mfma_f32_16x16x32_bf16 v[74:77], v[158:161], v[206:209], v[74:77]
	s_setprio 0
	s_setprio 1
	v_mfma_f32_16x16x32_bf16 v[118:121], v[162:165], v[178:181], v[118:121]
	v_mfma_f32_16x16x32_bf16 v[114:117], v[170:173], v[178:181], v[114:117]
	v_mfma_f32_16x16x32_bf16 v[102:105], v[162:165], v[186:189], v[102:105]
	v_mfma_f32_16x16x32_bf16 v[98:101], v[170:173], v[186:189], v[98:101]
	v_mfma_f32_16x16x32_bf16 v[86:89], v[162:165], v[194:197], v[86:89]
	v_mfma_f32_16x16x32_bf16 v[82:85], v[170:173], v[194:197], v[82:85]
	v_mfma_f32_16x16x32_bf16 v[70:73], v[162:165], v[202:205], v[70:73]
	v_mfma_f32_16x16x32_bf16 v[66:69], v[170:173], v[202:205], v[66:69]
	v_mfma_f32_16x16x32_bf16 v[118:121], v[166:169], v[182:185], v[118:121]
	v_mfma_f32_16x16x32_bf16 v[114:117], v[174:177], v[182:185], v[114:117]
	v_mfma_f32_16x16x32_bf16 v[102:105], v[166:169], v[190:193], v[102:105]
	v_mfma_f32_16x16x32_bf16 v[98:101], v[174:177], v[190:193], v[98:101]
	v_mfma_f32_16x16x32_bf16 v[86:89], v[166:169], v[198:201], v[86:89]
	v_mfma_f32_16x16x32_bf16 v[82:85], v[174:177], v[198:201], v[82:85]
	v_mfma_f32_16x16x32_bf16 v[70:73], v[166:169], v[206:209], v[70:73]
	v_mfma_f32_16x16x32_bf16 v[66:69], v[174:177], v[206:209], v[66:69]
	s_setprio 0
	s_barrier
	s_mov_b32 m0, s43
	v_lshl_add_u64 v[210:211], s[24:25], 0, v[132:133]
	s_add_u32 s20, s24, 0x160000
	global_load_lds_dwordx4 v[210:211], off
	v_lshl_add_u64 v[212:213], s[24:25], 0, v[130:131]
	s_mov_b32 m0, s44
	s_addc_u32 s21, s25, 0
	global_load_lds_dwordx4 v[212:213], off
	v_lshl_add_u64 v[214:215], s[20:21], 0, v[132:133]
	s_mov_b32 m0, s45
	v_lshl_add_u64 v[216:217], s[26:27], 0, v[130:131]
	global_load_lds_dwordx4 v[214:215], off
	v_lshl_add_u64 v[214:215], s[20:21], 0, v[130:131]
	s_mov_b32 m0, s46
	s_nop 0
	global_load_lds_dwordx4 v[214:215], off
	v_lshl_add_u64 v[214:215], s[26:27], 0, v[132:133]
	s_mov_b32 m0, s30
	s_nop 0
	global_load_lds_dwordx4 v[214:215], off
	s_mov_b32 m0, s31
	s_nop 0
	global_load_lds_dwordx4 v[216:217], off
	ds_read_b128 v[178:181], v145 offset:16384
	ds_read_b128 v[182:185], v145 offset:17408
	ds_read_b128 v[186:189], v145 offset:18432
	ds_read_b128 v[190:193], v145 offset:19456
	ds_read_b128 v[194:197], v145 offset:20480
	ds_read_b128 v[198:201], v145 offset:21504
	ds_read_b128 v[202:205], v145 offset:22528
	ds_read_b128 v[206:209], v145 offset:23552
	s_waitcnt vmcnt(8)
	s_waitcnt lgkmcnt(0)
	s_barrier
	s_setprio 1
	s_waitcnt lgkmcnt(0)
	v_mfma_f32_16x16x32_bf16 v[62:65], v[138:141], v[178:181], v[62:65]
	v_mfma_f32_16x16x32_bf16 v[58:61], v[154:157], v[178:181], v[58:61]
	v_mfma_f32_16x16x32_bf16 v[46:49], v[138:141], v[186:189], v[46:49]
	v_mfma_f32_16x16x32_bf16 v[42:45], v[154:157], v[186:189], v[42:45]
	v_mfma_f32_16x16x32_bf16 v[30:33], v[138:141], v[194:197], v[30:33]
	v_mfma_f32_16x16x32_bf16 v[26:29], v[154:157], v[194:197], v[26:29]
	v_mfma_f32_16x16x32_bf16 v[14:17], v[138:141], v[202:205], v[14:17]
	v_mfma_f32_16x16x32_bf16 v[10:13], v[154:157], v[202:205], v[10:13]
	v_mfma_f32_16x16x32_bf16 v[62:65], v[150:153], v[182:185], v[62:65]
	v_mfma_f32_16x16x32_bf16 v[58:61], v[158:161], v[182:185], v[58:61]
	v_mfma_f32_16x16x32_bf16 v[46:49], v[150:153], v[190:193], v[46:49]
	v_mfma_f32_16x16x32_bf16 v[42:45], v[158:161], v[190:193], v[42:45]
	v_mfma_f32_16x16x32_bf16 v[30:33], v[150:153], v[198:201], v[30:33]
	v_mfma_f32_16x16x32_bf16 v[26:29], v[158:161], v[198:201], v[26:29]
	v_mfma_f32_16x16x32_bf16 v[14:17], v[150:153], v[206:209], v[14:17]
	v_mfma_f32_16x16x32_bf16 v[10:13], v[158:161], v[206:209], v[10:13]
	s_setprio 0
	s_setprio 1
	v_mfma_f32_16x16x32_bf16 v[54:57], v[162:165], v[178:181], v[54:57]
	v_mfma_f32_16x16x32_bf16 v[50:53], v[170:173], v[178:181], v[50:53]
	v_mfma_f32_16x16x32_bf16 v[38:41], v[162:165], v[186:189], v[38:41]
	v_mfma_f32_16x16x32_bf16 v[34:37], v[170:173], v[186:189], v[34:37]
	v_mfma_f32_16x16x32_bf16 v[22:25], v[162:165], v[194:197], v[22:25]
	v_mfma_f32_16x16x32_bf16 v[18:21], v[170:173], v[194:197], v[18:21]
	v_mfma_f32_16x16x32_bf16 v[6:9], v[162:165], v[202:205], v[6:9]
	v_mfma_f32_16x16x32_bf16 v[2:5], v[170:173], v[202:205], v[2:5]
	v_mfma_f32_16x16x32_bf16 v[54:57], v[166:169], v[182:185], v[54:57]
	v_mfma_f32_16x16x32_bf16 v[50:53], v[174:177], v[182:185], v[50:53]
	v_mfma_f32_16x16x32_bf16 v[38:41], v[166:169], v[190:193], v[38:41]
	v_mfma_f32_16x16x32_bf16 v[34:37], v[174:177], v[190:193], v[34:37]
	v_mfma_f32_16x16x32_bf16 v[22:25], v[166:169], v[198:201], v[22:25]
	v_mfma_f32_16x16x32_bf16 v[18:21], v[174:177], v[198:201], v[18:21]
	v_mfma_f32_16x16x32_bf16 v[6:9], v[166:169], v[206:209], v[6:9]
	v_mfma_f32_16x16x32_bf16 v[2:5], v[174:177], v[206:209], v[2:5]
	s_setprio 0
	s_barrier
	s_add_u32 s20, s26, 0x160000
	s_addc_u32 s21, s27, 0
	s_mov_b32 m0, s33
	v_lshl_add_u64 v[218:219], s[20:21], 0, v[132:133]
	global_load_lds_dwordx4 v[218:219], off
	v_lshl_add_u64 v[218:219], s[20:21], 0, v[130:131]
	s_mov_b32 m0, s34
	s_nop 0
	global_load_lds_dwordx4 v[218:219], off
	ds_read_b128 v[138:141], v147
	ds_read_b128 v[150:153], v147 offset:1024
	ds_read_b128 v[154:157], v147 offset:2048
	ds_read_b128 v[158:161], v147 offset:3072
	ds_read_b128 v[162:165], v148
	ds_read_b128 v[166:169], v148 offset:1024
	ds_read_b128 v[170:173], v148 offset:2048
	ds_read_b128 v[174:177], v148 offset:3072
	ds_read_b128 v[178:181], v145 offset:32768
	ds_read_b128 v[182:185], v145 offset:33792
	ds_read_b128 v[186:189], v145 offset:34816
	ds_read_b128 v[190:193], v145 offset:35840
	ds_read_b128 v[194:197], v145 offset:36864
	ds_read_b128 v[198:201], v145 offset:37888
	ds_read_b128 v[202:205], v145 offset:38912
	ds_read_b128 v[206:209], v145 offset:39936
	s_waitcnt vmcnt(8)
	s_waitcnt lgkmcnt(0)
	s_barrier
	s_setprio 1
	s_waitcnt lgkmcnt(0)
	v_mfma_f32_16x16x32_bf16 v[126:129], v[138:141], v[178:181], v[126:129]
	v_mfma_f32_16x16x32_bf16 v[122:125], v[154:157], v[178:181], v[122:125]
	v_mfma_f32_16x16x32_bf16 v[110:113], v[138:141], v[186:189], v[110:113]
	v_mfma_f32_16x16x32_bf16 v[106:109], v[154:157], v[186:189], v[106:109]
	v_mfma_f32_16x16x32_bf16 v[94:97], v[138:141], v[194:197], v[94:97]
	v_mfma_f32_16x16x32_bf16 v[90:93], v[154:157], v[194:197], v[90:93]
	v_mfma_f32_16x16x32_bf16 v[78:81], v[138:141], v[202:205], v[78:81]
	v_mfma_f32_16x16x32_bf16 v[74:77], v[154:157], v[202:205], v[74:77]
	v_mfma_f32_16x16x32_bf16 v[126:129], v[150:153], v[182:185], v[126:129]
	v_mfma_f32_16x16x32_bf16 v[122:125], v[158:161], v[182:185], v[122:125]
	v_mfma_f32_16x16x32_bf16 v[110:113], v[150:153], v[190:193], v[110:113]
	v_mfma_f32_16x16x32_bf16 v[106:109], v[158:161], v[190:193], v[106:109]
	v_mfma_f32_16x16x32_bf16 v[94:97], v[150:153], v[198:201], v[94:97]
	v_mfma_f32_16x16x32_bf16 v[90:93], v[158:161], v[198:201], v[90:93]
	v_mfma_f32_16x16x32_bf16 v[78:81], v[150:153], v[206:209], v[78:81]
	v_mfma_f32_16x16x32_bf16 v[74:77], v[158:161], v[206:209], v[74:77]
	s_setprio 0
	s_setprio 1
	v_mfma_f32_16x16x32_bf16 v[118:121], v[162:165], v[178:181], v[118:121]
	v_mfma_f32_16x16x32_bf16 v[114:117], v[170:173], v[178:181], v[114:117]
	v_mfma_f32_16x16x32_bf16 v[102:105], v[162:165], v[186:189], v[102:105]
	v_mfma_f32_16x16x32_bf16 v[98:101], v[170:173], v[186:189], v[98:101]
	v_mfma_f32_16x16x32_bf16 v[86:89], v[162:165], v[194:197], v[86:89]
	v_mfma_f32_16x16x32_bf16 v[82:85], v[170:173], v[194:197], v[82:85]
	v_mfma_f32_16x16x32_bf16 v[70:73], v[162:165], v[202:205], v[70:73]
	v_mfma_f32_16x16x32_bf16 v[66:69], v[170:173], v[202:205], v[66:69]
	v_mfma_f32_16x16x32_bf16 v[118:121], v[166:169], v[182:185], v[118:121]
	v_mfma_f32_16x16x32_bf16 v[114:117], v[174:177], v[182:185], v[114:117]
	v_mfma_f32_16x16x32_bf16 v[102:105], v[166:169], v[190:193], v[102:105]
	v_mfma_f32_16x16x32_bf16 v[98:101], v[174:177], v[190:193], v[98:101]
	v_mfma_f32_16x16x32_bf16 v[86:89], v[166:169], v[198:201], v[86:89]
	v_mfma_f32_16x16x32_bf16 v[82:85], v[174:177], v[198:201], v[82:85]
	v_mfma_f32_16x16x32_bf16 v[70:73], v[166:169], v[206:209], v[70:73]
	v_mfma_f32_16x16x32_bf16 v[66:69], v[174:177], v[206:209], v[66:69]
	s_setprio 0
	s_barrier
	s_mov_b32 m0, s47
	v_lshl_add_u64 v[210:211], v[210:211], 0, s[12:13]
	s_add_u32 s20, s24, 0x160080
	global_load_lds_dwordx4 v[210:211], off
	v_lshl_add_u64 v[210:211], v[212:213], 0, s[12:13]
	s_mov_b32 m0, s48
	s_addc_u32 s21, s25, 0
	global_load_lds_dwordx4 v[210:211], off
	v_lshl_add_u64 v[210:211], s[20:21], 0, v[132:133]
	s_mov_b32 m0, s49
	s_nop 0
	global_load_lds_dwordx4 v[210:211], off
	v_lshl_add_u64 v[210:211], s[20:21], 0, v[130:131]
	s_mov_b32 m0, s50
	s_nop 0
	global_load_lds_dwordx4 v[210:211], off
	v_lshl_add_u64 v[210:211], v[214:215], 0, s[12:13]
	s_mov_b32 m0, s37
	s_nop 0
	global_load_lds_dwordx4 v[210:211], off
	v_lshl_add_u64 v[210:211], v[216:217], 0, s[12:13]
	s_mov_b32 m0, s39
	s_nop 0
	global_load_lds_dwordx4 v[210:211], off
	ds_read_b128 v[178:181], v145 offset:49152
	ds_read_b128 v[182:185], v145 offset:50176
	ds_read_b128 v[186:189], v145 offset:51200
	ds_read_b128 v[190:193], v145 offset:52224
	ds_read_b128 v[194:197], v145 offset:53248
	ds_read_b128 v[198:201], v145 offset:54272
	ds_read_b128 v[202:205], v145 offset:55296
	ds_read_b128 v[206:209], v145 offset:56320
	s_waitcnt vmcnt(8)
	s_waitcnt lgkmcnt(0)
	s_barrier
	s_setprio 1
	s_waitcnt lgkmcnt(0)
	v_mfma_f32_16x16x32_bf16 v[62:65], v[138:141], v[178:181], v[62:65]
	v_mfma_f32_16x16x32_bf16 v[58:61], v[154:157], v[178:181], v[58:61]
	v_mfma_f32_16x16x32_bf16 v[46:49], v[138:141], v[186:189], v[46:49]
	v_mfma_f32_16x16x32_bf16 v[42:45], v[154:157], v[186:189], v[42:45]
	v_mfma_f32_16x16x32_bf16 v[30:33], v[138:141], v[194:197], v[30:33]
	v_mfma_f32_16x16x32_bf16 v[26:29], v[154:157], v[194:197], v[26:29]
	v_mfma_f32_16x16x32_bf16 v[14:17], v[138:141], v[202:205], v[14:17]
	v_mfma_f32_16x16x32_bf16 v[10:13], v[154:157], v[202:205], v[10:13]
	v_mfma_f32_16x16x32_bf16 v[62:65], v[150:153], v[182:185], v[62:65]
	v_mfma_f32_16x16x32_bf16 v[58:61], v[158:161], v[182:185], v[58:61]
	v_mfma_f32_16x16x32_bf16 v[46:49], v[150:153], v[190:193], v[46:49]
	v_mfma_f32_16x16x32_bf16 v[42:45], v[158:161], v[190:193], v[42:45]
	v_mfma_f32_16x16x32_bf16 v[30:33], v[150:153], v[198:201], v[30:33]
	v_mfma_f32_16x16x32_bf16 v[26:29], v[158:161], v[198:201], v[26:29]
	v_mfma_f32_16x16x32_bf16 v[14:17], v[150:153], v[206:209], v[14:17]
	v_mfma_f32_16x16x32_bf16 v[10:13], v[158:161], v[206:209], v[10:13]
	s_setprio 0
	s_setprio 1
	v_mfma_f32_16x16x32_bf16 v[54:57], v[162:165], v[178:181], v[54:57]
	v_mfma_f32_16x16x32_bf16 v[50:53], v[170:173], v[178:181], v[50:53]
	v_mfma_f32_16x16x32_bf16 v[38:41], v[162:165], v[186:189], v[38:41]
	v_mfma_f32_16x16x32_bf16 v[34:37], v[170:173], v[186:189], v[34:37]
	v_mfma_f32_16x16x32_bf16 v[22:25], v[162:165], v[194:197], v[22:25]
	v_mfma_f32_16x16x32_bf16 v[18:21], v[170:173], v[194:197], v[18:21]
	v_mfma_f32_16x16x32_bf16 v[6:9], v[162:165], v[202:205], v[6:9]
	v_mfma_f32_16x16x32_bf16 v[2:5], v[170:173], v[202:205], v[2:5]
	v_mfma_f32_16x16x32_bf16 v[54:57], v[166:169], v[182:185], v[54:57]
	v_mfma_f32_16x16x32_bf16 v[50:53], v[174:177], v[182:185], v[50:53]
	v_mfma_f32_16x16x32_bf16 v[38:41], v[166:169], v[190:193], v[38:41]
	v_mfma_f32_16x16x32_bf16 v[34:37], v[174:177], v[190:193], v[34:37]
	v_mfma_f32_16x16x32_bf16 v[22:25], v[166:169], v[198:201], v[22:25]
	v_mfma_f32_16x16x32_bf16 v[18:21], v[174:177], v[198:201], v[18:21]
	v_mfma_f32_16x16x32_bf16 v[6:9], v[166:169], v[206:209], v[6:9]
	v_mfma_f32_16x16x32_bf16 v[2:5], v[174:177], v[206:209], v[2:5]
	s_setprio 0
	s_barrier
	s_add_i32 s6, s6, 2
	s_cmpk_gt_u32 s6, 0x55
	s_mov_b64 s[20:21], s[22:23]
	s_cbranch_scc0 .LBB0_1112
	s_and_b64 vcc, exec, s[14:15]
	s_cbranch_vccz .LBB0_1115
	s_barrier

.LBB0_1199:
	s_add_u32 s6, s0, 0xfff80080
	s_addc_u32 s7, s1, -1
	s_cmp_eq_u32 s54, 28
	s_cselect_b32 s27, s11, s7
	s_cselect_b32 s26, s10, s6
	s_cselect_b32 s7, s29, s53
	s_cselect_b32 s6, s30, s31
	s_mov_b32 m0, s48
	v_lshl_add_u64 v[166:167], s[0:1], 0, v[144:145]
	global_load_lds_dwordx4 v[166:167], off
	v_lshl_add_u64 v[166:167], s[0:1], 0, v[146:147]
	s_mov_b32 m0, s49
	s_nop 0
	global_load_lds_dwordx4 v[166:167], off
	ds_read_b128 v[130:133], v169
	ds_read_b128 v[134:137], v169 offset:1024
	ds_read_b128 v[150:153], v169 offset:2048
	ds_read_b128 v[154:157], v169 offset:3072
	ds_read_b128 v[158:161], v170
	ds_read_b128 v[162:165], v170 offset:1024
	ds_read_b128 v[174:177], v170 offset:2048
	ds_read_b128 v[178:181], v170 offset:3072
	ds_read_b128 v[182:185], v171
	ds_read_b128 v[186:189], v171 offset:1024
	ds_read_b128 v[190:193], v171 offset:2048
	ds_read_b128 v[194:197], v171 offset:3072
	ds_read_b128 v[198:201], v171 offset:4096
	ds_read_b128 v[202:205], v171 offset:5120
	ds_read_b128 v[206:209], v171 offset:6144
	ds_read_b128 v[210:213], v171 offset:7168
	s_waitcnt vmcnt(8)
	s_waitcnt lgkmcnt(0)
	s_barrier
	s_setprio 1
	s_waitcnt lgkmcnt(0)
	v_mfma_f32_16x16x32_bf16 v[126:129], v[130:133], v[182:185], v[126:129]
	v_mfma_f32_16x16x32_bf16 v[122:125], v[150:153], v[182:185], v[122:125]
	v_mfma_f32_16x16x32_bf16 v[110:113], v[130:133], v[190:193], v[110:113]
	v_mfma_f32_16x16x32_bf16 v[106:109], v[150:153], v[190:193], v[106:109]
	v_mfma_f32_16x16x32_bf16 v[94:97], v[130:133], v[198:201], v[94:97]
	v_mfma_f32_16x16x32_bf16 v[90:93], v[150:153], v[198:201], v[90:93]
	v_mfma_f32_16x16x32_bf16 v[78:81], v[130:133], v[206:209], v[78:81]
	v_mfma_f32_16x16x32_bf16 v[74:77], v[150:153], v[206:209], v[74:77]
	v_mfma_f32_16x16x32_bf16 v[126:129], v[134:137], v[186:189], v[126:129]
	v_mfma_f32_16x16x32_bf16 v[122:125], v[154:157], v[186:189], v[122:125]
	v_mfma_f32_16x16x32_bf16 v[110:113], v[134:137], v[194:197], v[110:113]
	v_mfma_f32_16x16x32_bf16 v[106:109], v[154:157], v[194:197], v[106:109]
	v_mfma_f32_16x16x32_bf16 v[94:97], v[134:137], v[202:205], v[94:97]
	v_mfma_f32_16x16x32_bf16 v[90:93], v[154:157], v[202:205], v[90:93]
	v_mfma_f32_16x16x32_bf16 v[78:81], v[134:137], v[210:213], v[78:81]
	v_mfma_f32_16x16x32_bf16 v[74:77], v[154:157], v[210:213], v[74:77]
	s_setprio 0
	s_setprio 1
	v_mfma_f32_16x16x32_bf16 v[118:121], v[158:161], v[182:185], v[118:121]
	v_mfma_f32_16x16x32_bf16 v[114:117], v[174:177], v[182:185], v[114:117]
	v_mfma_f32_16x16x32_bf16 v[102:105], v[158:161], v[190:193], v[102:105]
	v_mfma_f32_16x16x32_bf16 v[98:101], v[174:177], v[190:193], v[98:101]
	v_mfma_f32_16x16x32_bf16 v[86:89], v[158:161], v[198:201], v[86:89]
	v_mfma_f32_16x16x32_bf16 v[82:85], v[174:177], v[198:201], v[82:85]
	v_mfma_f32_16x16x32_bf16 v[70:73], v[158:161], v[206:209], v[70:73]
	v_mfma_f32_16x16x32_bf16 v[66:69], v[174:177], v[206:209], v[66:69]
	v_mfma_f32_16x16x32_bf16 v[118:121], v[162:165], v[186:189], v[118:121]
	v_mfma_f32_16x16x32_bf16 v[114:117], v[178:181], v[186:189], v[114:117]
	v_mfma_f32_16x16x32_bf16 v[102:105], v[162:165], v[194:197], v[102:105]
	v_mfma_f32_16x16x32_bf16 v[98:101], v[178:181], v[194:197], v[98:101]
	v_mfma_f32_16x16x32_bf16 v[86:89], v[162:165], v[202:205], v[86:89]
	v_mfma_f32_16x16x32_bf16 v[82:85], v[178:181], v[202:205], v[82:85]
	v_mfma_f32_16x16x32_bf16 v[70:73], v[162:165], v[210:213], v[70:73]
	v_mfma_f32_16x16x32_bf16 v[66:69], v[178:181], v[210:213], v[66:69]
	s_setprio 0
	s_barrier
	s_add_i32 s55, s46, s34
	v_lshl_add_u64 v[166:167], s[6:7], 0, v[140:141]
	s_mov_b32 m0, s55
	s_nop 0
	global_load_lds_dwordx4 v[166:167], off
	s_add_i32 m0, s55, 0x2000
	s_add_u32 s56, s6, 0x80000
	v_lshl_add_u64 v[214:215], s[6:7], 0, v[138:139]
	s_addc_u32 s57, s7, 0
	s_add_i32 s55, s47, s34
	global_load_lds_dwordx4 v[214:215], off
	v_lshl_add_u64 v[216:217], s[56:57], 0, v[140:141]
	s_mov_b32 m0, s55
	v_lshl_add_u64 v[218:219], s[26:27], 0, v[138:139]
	global_load_lds_dwordx4 v[216:217], off
	v_lshl_add_u64 v[216:217], s[56:57], 0, v[138:139]
	s_add_i32 m0, s55, 0x2000
	s_nop 0
	global_load_lds_dwordx4 v[216:217], off
	v_lshl_add_u64 v[216:217], s[26:27], 0, v[140:141]
	s_mov_b32 m0, s35
	s_nop 0
	global_load_lds_dwordx4 v[216:217], off
	s_mov_b32 m0, s36
	s_nop 0
	global_load_lds_dwordx4 v[218:219], off
	ds_read_b128 v[182:185], v171 offset:16384
	ds_read_b128 v[186:189], v171 offset:17408
	ds_read_b128 v[190:193], v171 offset:18432
	ds_read_b128 v[194:197], v171 offset:19456
	ds_read_b128 v[198:201], v171 offset:20480
	ds_read_b128 v[202:205], v171 offset:21504
	ds_read_b128 v[206:209], v171 offset:22528
	ds_read_b128 v[210:213], v171 offset:23552
	s_waitcnt vmcnt(8)
	s_waitcnt lgkmcnt(0)
	s_barrier
	s_setprio 1
	s_waitcnt lgkmcnt(0)
	v_mfma_f32_16x16x32_bf16 v[62:65], v[130:133], v[182:185], v[62:65]
	v_mfma_f32_16x16x32_bf16 v[58:61], v[150:153], v[182:185], v[58:61]
	v_mfma_f32_16x16x32_bf16 v[46:49], v[130:133], v[190:193], v[46:49]
	v_mfma_f32_16x16x32_bf16 v[42:45], v[150:153], v[190:193], v[42:45]
	v_mfma_f32_16x16x32_bf16 v[30:33], v[130:133], v[198:201], v[30:33]
	v_mfma_f32_16x16x32_bf16 v[26:29], v[150:153], v[198:201], v[26:29]
	v_mfma_f32_16x16x32_bf16 v[14:17], v[130:133], v[206:209], v[14:17]
	v_mfma_f32_16x16x32_bf16 v[10:13], v[150:153], v[206:209], v[10:13]
	v_mfma_f32_16x16x32_bf16 v[62:65], v[134:137], v[186:189], v[62:65]
	v_mfma_f32_16x16x32_bf16 v[58:61], v[154:157], v[186:189], v[58:61]
	v_mfma_f32_16x16x32_bf16 v[46:49], v[134:137], v[194:197], v[46:49]
	v_mfma_f32_16x16x32_bf16 v[42:45], v[154:157], v[194:197], v[42:45]
	v_mfma_f32_16x16x32_bf16 v[30:33], v[134:137], v[202:205], v[30:33]
	v_mfma_f32_16x16x32_bf16 v[26:29], v[154:157], v[202:205], v[26:29]
	v_mfma_f32_16x16x32_bf16 v[14:17], v[134:137], v[210:213], v[14:17]
	v_mfma_f32_16x16x32_bf16 v[10:13], v[154:157], v[210:213], v[10:13]
	s_setprio 0
	s_setprio 1
	v_mfma_f32_16x16x32_bf16 v[54:57], v[158:161], v[182:185], v[54:57]
	v_mfma_f32_16x16x32_bf16 v[50:53], v[174:177], v[182:185], v[50:53]
	v_mfma_f32_16x16x32_bf16 v[38:41], v[158:161], v[190:193], v[38:41]
	v_mfma_f32_16x16x32_bf16 v[34:37], v[174:177], v[190:193], v[34:37]
	v_mfma_f32_16x16x32_bf16 v[22:25], v[158:161], v[198:201], v[22:25]
	v_mfma_f32_16x16x32_bf16 v[18:21], v[174:177], v[198:201], v[18:21]
	v_mfma_f32_16x16x32_bf16 v[6:9], v[158:161], v[206:209], v[6:9]
	v_mfma_f32_16x16x32_bf16 v[2:5], v[174:177], v[206:209], v[2:5]
	v_mfma_f32_16x16x32_bf16 v[54:57], v[162:165], v[186:189], v[54:57]
	v_mfma_f32_16x16x32_bf16 v[50:53], v[178:181], v[186:189], v[50:53]
	v_mfma_f32_16x16x32_bf16 v[38:41], v[162:165], v[194:197], v[38:41]
	v_mfma_f32_16x16x32_bf16 v[34:37], v[178:181], v[194:197], v[34:37]
	v_mfma_f32_16x16x32_bf16 v[22:25], v[162:165], v[202:205], v[22:25]
	v_mfma_f32_16x16x32_bf16 v[18:21], v[178:181], v[202:205], v[18:21]
	v_mfma_f32_16x16x32_bf16 v[6:9], v[162:165], v[210:213], v[6:9]
	v_mfma_f32_16x16x32_bf16 v[2:5], v[178:181], v[210:213], v[2:5]
	s_setprio 0
	s_barrier
	s_add_i32 s55, 0, 0x18000
	s_add_i32 s56, 0, 0x1c000
	s_add_u32 s26, s26, 0x80000
	s_addc_u32 s27, s27, 0
	s_mov_b32 m0, s37
	v_lshl_add_u64 v[220:221], s[26:27], 0, v[140:141]
	global_load_lds_dwordx4 v[220:221], off
	v_lshl_add_u64 v[220:221], s[26:27], 0, v[138:139]
	s_mov_b32 m0, s39
	s_nop 0
	global_load_lds_dwordx4 v[220:221], off
	v_add_u32_e32 v142, s55, v168
	ds_read_b128 v[130:133], v142
	ds_read_b128 v[134:137], v142 offset:1024
	ds_read_b128 v[150:153], v142 offset:2048
	ds_read_b128 v[154:157], v142 offset:3072
	v_add_u32_e32 v142, s56, v168
	ds_read_b128 v[158:161], v142
	ds_read_b128 v[162:165], v142 offset:1024
	ds_read_b128 v[174:177], v142 offset:2048
	ds_read_b128 v[178:181], v142 offset:3072
	ds_read_b128 v[182:185], v171 offset:32768
	ds_read_b128 v[186:189], v171 offset:33792
	ds_read_b128 v[190:193], v171 offset:34816
	ds_read_b128 v[194:197], v171 offset:35840
	ds_read_b128 v[198:201], v171 offset:36864
	ds_read_b128 v[202:205], v171 offset:37888
	ds_read_b128 v[206:209], v171 offset:38912
	ds_read_b128 v[210:213], v171 offset:39936
	s_waitcnt vmcnt(8)
	s_waitcnt lgkmcnt(0)
	s_barrier
	s_setprio 1
	s_waitcnt lgkmcnt(0)
	v_mfma_f32_16x16x32_bf16 v[126:129], v[130:133], v[182:185], v[126:129]
	v_mfma_f32_16x16x32_bf16 v[122:125], v[150:153], v[182:185], v[122:125]
	v_mfma_f32_16x16x32_bf16 v[110:113], v[130:133], v[190:193], v[110:113]
	v_mfma_f32_16x16x32_bf16 v[106:109], v[150:153], v[190:193], v[106:109]
	v_mfma_f32_16x16x32_bf16 v[94:97], v[130:133], v[198:201], v[94:97]
	v_mfma_f32_16x16x32_bf16 v[90:93], v[150:153], v[198:201], v[90:93]
	v_mfma_f32_16x16x32_bf16 v[78:81], v[130:133], v[206:209], v[78:81]
	v_mfma_f32_16x16x32_bf16 v[74:77], v[150:153], v[206:209], v[74:77]
	v_mfma_f32_16x16x32_bf16 v[126:129], v[134:137], v[186:189], v[126:129]
	v_mfma_f32_16x16x32_bf16 v[122:125], v[154:157], v[186:189], v[122:125]
	v_mfma_f32_16x16x32_bf16 v[110:113], v[134:137], v[194:197], v[110:113]
	v_mfma_f32_16x16x32_bf16 v[106:109], v[154:157], v[194:197], v[106:109]
	v_mfma_f32_16x16x32_bf16 v[94:97], v[134:137], v[202:205], v[94:97]
	v_mfma_f32_16x16x32_bf16 v[90:93], v[154:157], v[202:205], v[90:93]
	v_mfma_f32_16x16x32_bf16 v[78:81], v[134:137], v[210:213], v[78:81]
	v_mfma_f32_16x16x32_bf16 v[74:77], v[154:157], v[210:213], v[74:77]
	s_setprio 0
	s_setprio 1
	v_mfma_f32_16x16x32_bf16 v[118:121], v[158:161], v[182:185], v[118:121]
	v_mfma_f32_16x16x32_bf16 v[114:117], v[174:177], v[182:185], v[114:117]
	v_mfma_f32_16x16x32_bf16 v[102:105], v[158:161], v[190:193], v[102:105]
	v_mfma_f32_16x16x32_bf16 v[98:101], v[174:177], v[190:193], v[98:101]
	v_mfma_f32_16x16x32_bf16 v[86:89], v[158:161], v[198:201], v[86:89]
	v_mfma_f32_16x16x32_bf16 v[82:85], v[174:177], v[198:201], v[82:85]
	v_mfma_f32_16x16x32_bf16 v[70:73], v[158:161], v[206:209], v[70:73]
	v_mfma_f32_16x16x32_bf16 v[66:69], v[174:177], v[206:209], v[66:69]
	v_mfma_f32_16x16x32_bf16 v[118:121], v[162:165], v[186:189], v[118:121]
	v_mfma_f32_16x16x32_bf16 v[114:117], v[178:181], v[186:189], v[114:117]
	v_mfma_f32_16x16x32_bf16 v[102:105], v[162:165], v[194:197], v[102:105]
	v_mfma_f32_16x16x32_bf16 v[98:101], v[178:181], v[194:197], v[98:101]
	v_mfma_f32_16x16x32_bf16 v[86:89], v[162:165], v[202:205], v[86:89]
	v_mfma_f32_16x16x32_bf16 v[82:85], v[178:181], v[202:205], v[82:85]
	v_mfma_f32_16x16x32_bf16 v[70:73], v[162:165], v[210:213], v[70:73]
	v_mfma_f32_16x16x32_bf16 v[66:69], v[178:181], v[210:213], v[66:69]
	s_setprio 0
	s_barrier
	s_add_i32 s26, s55, s34
	v_lshl_add_u64 v[166:167], v[166:167], 0, s[14:15]
	s_mov_b32 m0, s26
	s_nop 0
	global_load_lds_dwordx4 v[166:167], off
	s_add_i32 m0, s26, 0x2000
	s_add_u32 s6, s6, 0x80080
	v_lshl_add_u64 v[166:167], v[214:215], 0, s[14:15]
	s_addc_u32 s7, s7, 0
	s_add_i32 s26, s56, s34
	global_load_lds_dwordx4 v[166:167], off
	v_lshl_add_u64 v[166:167], s[6:7], 0, v[140:141]
	s_mov_b32 m0, s26
	s_nop 0
	global_load_lds_dwordx4 v[166:167], off
	v_lshl_add_u64 v[166:167], s[6:7], 0, v[138:139]
	s_add_i32 m0, s26, 0x2000
	s_nop 0
	global_load_lds_dwordx4 v[166:167], off
	v_lshl_add_u64 v[166:167], v[216:217], 0, s[14:15]
	s_mov_b32 m0, s43
	s_nop 0
	global_load_lds_dwordx4 v[166:167], off
	v_lshl_add_u64 v[166:167], v[218:219], 0, s[14:15]
	s_mov_b32 m0, s44
	s_nop 0
	global_load_lds_dwordx4 v[166:167], off
	ds_read_b128 v[182:185], v171 offset:49152
	ds_read_b128 v[186:189], v171 offset:50176
	ds_read_b128 v[190:193], v171 offset:51200
	ds_read_b128 v[194:197], v171 offset:52224
	ds_read_b128 v[198:201], v171 offset:53248
	ds_read_b128 v[202:205], v171 offset:54272
	ds_read_b128 v[206:209], v171 offset:55296
	ds_read_b128 v[210:213], v171 offset:56320
	s_waitcnt vmcnt(8)
	s_waitcnt lgkmcnt(0)
	s_barrier
	s_setprio 1
	s_waitcnt lgkmcnt(0)
	v_mfma_f32_16x16x32_bf16 v[62:65], v[130:133], v[182:185], v[62:65]
	v_mfma_f32_16x16x32_bf16 v[58:61], v[150:153], v[182:185], v[58:61]
	v_mfma_f32_16x16x32_bf16 v[46:49], v[130:133], v[190:193], v[46:49]
	v_mfma_f32_16x16x32_bf16 v[42:45], v[150:153], v[190:193], v[42:45]
	v_mfma_f32_16x16x32_bf16 v[30:33], v[130:133], v[198:201], v[30:33]
	v_mfma_f32_16x16x32_bf16 v[26:29], v[150:153], v[198:201], v[26:29]
	v_mfma_f32_16x16x32_bf16 v[14:17], v[130:133], v[206:209], v[14:17]
	v_mfma_f32_16x16x32_bf16 v[10:13], v[150:153], v[206:209], v[10:13]
	v_mfma_f32_16x16x32_bf16 v[62:65], v[134:137], v[186:189], v[62:65]
	v_mfma_f32_16x16x32_bf16 v[58:61], v[154:157], v[186:189], v[58:61]
	v_mfma_f32_16x16x32_bf16 v[46:49], v[134:137], v[194:197], v[46:49]
	v_mfma_f32_16x16x32_bf16 v[42:45], v[154:157], v[194:197], v[42:45]
	v_mfma_f32_16x16x32_bf16 v[30:33], v[134:137], v[202:205], v[30:33]
	v_mfma_f32_16x16x32_bf16 v[26:29], v[154:157], v[202:205], v[26:29]
	v_mfma_f32_16x16x32_bf16 v[14:17], v[134:137], v[210:213], v[14:17]
	v_mfma_f32_16x16x32_bf16 v[10:13], v[154:157], v[210:213], v[10:13]
	s_setprio 0
	s_setprio 1
	v_mfma_f32_16x16x32_bf16 v[54:57], v[158:161], v[182:185], v[54:57]
	v_mfma_f32_16x16x32_bf16 v[50:53], v[174:177], v[182:185], v[50:53]
	v_mfma_f32_16x16x32_bf16 v[38:41], v[158:161], v[190:193], v[38:41]
	v_mfma_f32_16x16x32_bf16 v[34:37], v[174:177], v[190:193], v[34:37]
	v_mfma_f32_16x16x32_bf16 v[22:25], v[158:161], v[198:201], v[22:25]
	v_mfma_f32_16x16x32_bf16 v[18:21], v[174:177], v[198:201], v[18:21]
	v_mfma_f32_16x16x32_bf16 v[6:9], v[158:161], v[206:209], v[6:9]
	v_mfma_f32_16x16x32_bf16 v[2:5], v[174:177], v[206:209], v[2:5]
	v_mfma_f32_16x16x32_bf16 v[54:57], v[162:165], v[186:189], v[54:57]
	v_mfma_f32_16x16x32_bf16 v[50:53], v[178:181], v[186:189], v[50:53]
	v_mfma_f32_16x16x32_bf16 v[38:41], v[162:165], v[194:197], v[38:41]
	v_mfma_f32_16x16x32_bf16 v[34:37], v[178:181], v[194:197], v[34:37]
	v_mfma_f32_16x16x32_bf16 v[22:25], v[162:165], v[202:205], v[22:25]
	v_mfma_f32_16x16x32_bf16 v[18:21], v[178:181], v[202:205], v[18:21]
	v_mfma_f32_16x16x32_bf16 v[6:9], v[162:165], v[210:213], v[6:9]
	v_mfma_f32_16x16x32_bf16 v[2:5], v[178:181], v[210:213], v[2:5]
	s_setprio 0
	s_barrier
	s_add_i32 s54, s54, 2
	s_add_u32 s0, s0, 0x100
	s_addc_u32 s1, s1, 0
	s_add_u32 s31, s31, 0x100
	s_addc_u32 s53, s53, 0
	s_cmp_gt_u32 s54, 29
	s_cbranch_scc0 .LBB0_1199
	s_and_b64 vcc, exec, s[16:17]
	s_cbranch_vccz .LBB0_1202
	s_barrier

.LBB0_2412:
	s_add_u32 s24, s22, 0x100
	s_addc_u32 s25, s23, 0
	s_add_u32 s26, s54, s22
	s_addc_u32 s27, s55, s23
	s_cmp_eq_u32 s56, 28
	s_cselect_b32 s28, 0, s24
	s_cselect_b32 s29, 0, s25
	s_cselect_b32 s26, s19, s26
	s_cselect_b32 s27, s10, s27
	s_add_u32 s28, s8, s28
	s_addc_u32 s29, s9, s29
	s_mov_b32 m0, s42
	v_lshl_add_u64 v[210:211], v[134:135], 0, s[22:23]
	global_load_lds_dwordx4 v[210:211], off
	v_lshl_add_u64 v[210:211], v[136:137], 0, s[22:23]
	s_mov_b32 m0, s43
	s_nop 0
	global_load_lds_dwordx4 v[210:211], off
	ds_read_b128 v[138:141], v144
	ds_read_b128 v[150:153], v144 offset:1024
	ds_read_b128 v[154:157], v144 offset:2048
	ds_read_b128 v[158:161], v144 offset:3072
	ds_read_b128 v[162:165], v145
	ds_read_b128 v[166:169], v145 offset:1024
	ds_read_b128 v[170:173], v145 offset:2048
	ds_read_b128 v[174:177], v145 offset:3072
	ds_read_b128 v[178:181], v146
	ds_read_b128 v[182:185], v146 offset:1024
	ds_read_b128 v[186:189], v146 offset:2048
	ds_read_b128 v[190:193], v146 offset:3072
	ds_read_b128 v[194:197], v146 offset:4096
	ds_read_b128 v[198:201], v146 offset:5120
	ds_read_b128 v[202:205], v146 offset:6144
	ds_read_b128 v[206:209], v146 offset:7168
	s_waitcnt vmcnt(8)
	s_waitcnt lgkmcnt(0)
	s_barrier
	s_setprio 1
	s_waitcnt lgkmcnt(0)
	v_mfma_f32_16x16x32_bf16 v[126:129], v[138:141], v[178:181], v[126:129]
	v_mfma_f32_16x16x32_bf16 v[122:125], v[154:157], v[178:181], v[122:125]
	v_mfma_f32_16x16x32_bf16 v[110:113], v[138:141], v[186:189], v[110:113]
	v_mfma_f32_16x16x32_bf16 v[106:109], v[154:157], v[186:189], v[106:109]
	v_mfma_f32_16x16x32_bf16 v[94:97], v[138:141], v[194:197], v[94:97]
	v_mfma_f32_16x16x32_bf16 v[90:93], v[154:157], v[194:197], v[90:93]
	v_mfma_f32_16x16x32_bf16 v[78:81], v[138:141], v[202:205], v[78:81]
	v_mfma_f32_16x16x32_bf16 v[74:77], v[154:157], v[202:205], v[74:77]
	v_mfma_f32_16x16x32_bf16 v[126:129], v[150:153], v[182:185], v[126:129]
	v_mfma_f32_16x16x32_bf16 v[122:125], v[158:161], v[182:185], v[122:125]
	v_mfma_f32_16x16x32_bf16 v[110:113], v[150:153], v[190:193], v[110:113]
	v_mfma_f32_16x16x32_bf16 v[106:109], v[158:161], v[190:193], v[106:109]
	v_mfma_f32_16x16x32_bf16 v[94:97], v[150:153], v[198:201], v[94:97]
	v_mfma_f32_16x16x32_bf16 v[90:93], v[158:161], v[198:201], v[90:93]
	v_mfma_f32_16x16x32_bf16 v[78:81], v[150:153], v[206:209], v[78:81]
	v_mfma_f32_16x16x32_bf16 v[74:77], v[158:161], v[206:209], v[74:77]
	s_setprio 0
	s_setprio 1
	v_mfma_f32_16x16x32_bf16 v[118:121], v[162:165], v[178:181], v[118:121]
	v_mfma_f32_16x16x32_bf16 v[114:117], v[170:173], v[178:181], v[114:117]
	v_mfma_f32_16x16x32_bf16 v[102:105], v[162:165], v[186:189], v[102:105]
	v_mfma_f32_16x16x32_bf16 v[98:101], v[170:173], v[186:189], v[98:101]
	v_mfma_f32_16x16x32_bf16 v[86:89], v[162:165], v[194:197], v[86:89]
	v_mfma_f32_16x16x32_bf16 v[82:85], v[170:173], v[194:197], v[82:85]
	v_mfma_f32_16x16x32_bf16 v[70:73], v[162:165], v[202:205], v[70:73]
	v_mfma_f32_16x16x32_bf16 v[66:69], v[170:173], v[202:205], v[66:69]
	v_mfma_f32_16x16x32_bf16 v[118:121], v[166:169], v[182:185], v[118:121]
	v_mfma_f32_16x16x32_bf16 v[114:117], v[174:177], v[182:185], v[114:117]
	v_mfma_f32_16x16x32_bf16 v[102:105], v[166:169], v[190:193], v[102:105]
	v_mfma_f32_16x16x32_bf16 v[98:101], v[174:177], v[190:193], v[98:101]
	v_mfma_f32_16x16x32_bf16 v[86:89], v[166:169], v[198:201], v[86:89]
	v_mfma_f32_16x16x32_bf16 v[82:85], v[174:177], v[198:201], v[82:85]
	v_mfma_f32_16x16x32_bf16 v[70:73], v[166:169], v[206:209], v[70:73]
	v_mfma_f32_16x16x32_bf16 v[66:69], v[174:177], v[206:209], v[66:69]
	s_setprio 0
	s_barrier
	s_mov_b32 m0, s44
	v_lshl_add_u64 v[210:211], s[26:27], 0, v[132:133]
	s_add_u32 s22, s26, 0x80000
	global_load_lds_dwordx4 v[210:211], off
	v_lshl_add_u64 v[212:213], s[26:27], 0, v[130:131]
	s_mov_b32 m0, s45
	s_addc_u32 s23, s27, 0
	global_load_lds_dwordx4 v[212:213], off
	v_lshl_add_u64 v[214:215], s[22:23], 0, v[132:133]
	s_mov_b32 m0, s46
	v_lshl_add_u64 v[216:217], s[28:29], 0, v[130:131]
	global_load_lds_dwordx4 v[214:215], off
	v_lshl_add_u64 v[214:215], s[22:23], 0, v[130:131]
	s_mov_b32 m0, s47
	s_nop 0
	global_load_lds_dwordx4 v[214:215], off
	v_lshl_add_u64 v[214:215], s[28:29], 0, v[132:133]
	s_mov_b32 m0, s33
	s_nop 0
	global_load_lds_dwordx4 v[214:215], off
	s_mov_b32 m0, s34
	s_nop 0
	global_load_lds_dwordx4 v[216:217], off
	ds_read_b128 v[178:181], v146 offset:16384
	ds_read_b128 v[182:185], v146 offset:17408
	ds_read_b128 v[186:189], v146 offset:18432
	ds_read_b128 v[190:193], v146 offset:19456
	ds_read_b128 v[194:197], v146 offset:20480
	ds_read_b128 v[198:201], v146 offset:21504
	ds_read_b128 v[202:205], v146 offset:22528
	ds_read_b128 v[206:209], v146 offset:23552
	s_waitcnt vmcnt(8)
	s_waitcnt lgkmcnt(0)
	s_barrier
	s_setprio 1
	s_waitcnt lgkmcnt(0)
	v_mfma_f32_16x16x32_bf16 v[62:65], v[138:141], v[178:181], v[62:65]
	v_mfma_f32_16x16x32_bf16 v[58:61], v[154:157], v[178:181], v[58:61]
	v_mfma_f32_16x16x32_bf16 v[46:49], v[138:141], v[186:189], v[46:49]
	v_mfma_f32_16x16x32_bf16 v[42:45], v[154:157], v[186:189], v[42:45]
	v_mfma_f32_16x16x32_bf16 v[30:33], v[138:141], v[194:197], v[30:33]
	v_mfma_f32_16x16x32_bf16 v[26:29], v[154:157], v[194:197], v[26:29]
	v_mfma_f32_16x16x32_bf16 v[14:17], v[138:141], v[202:205], v[14:17]
	v_mfma_f32_16x16x32_bf16 v[10:13], v[154:157], v[202:205], v[10:13]
	v_mfma_f32_16x16x32_bf16 v[62:65], v[150:153], v[182:185], v[62:65]
	v_mfma_f32_16x16x32_bf16 v[58:61], v[158:161], v[182:185], v[58:61]
	v_mfma_f32_16x16x32_bf16 v[46:49], v[150:153], v[190:193], v[46:49]
	v_mfma_f32_16x16x32_bf16 v[42:45], v[158:161], v[190:193], v[42:45]
	v_mfma_f32_16x16x32_bf16 v[30:33], v[150:153], v[198:201], v[30:33]
	v_mfma_f32_16x16x32_bf16 v[26:29], v[158:161], v[198:201], v[26:29]
	v_mfma_f32_16x16x32_bf16 v[14:17], v[150:153], v[206:209], v[14:17]
	v_mfma_f32_16x16x32_bf16 v[10:13], v[158:161], v[206:209], v[10:13]
	s_setprio 0
	s_setprio 1
	v_mfma_f32_16x16x32_bf16 v[54:57], v[162:165], v[178:181], v[54:57]
	v_mfma_f32_16x16x32_bf16 v[50:53], v[170:173], v[178:181], v[50:53]
	v_mfma_f32_16x16x32_bf16 v[38:41], v[162:165], v[186:189], v[38:41]
	v_mfma_f32_16x16x32_bf16 v[34:37], v[170:173], v[186:189], v[34:37]
	v_mfma_f32_16x16x32_bf16 v[22:25], v[162:165], v[194:197], v[22:25]
	v_mfma_f32_16x16x32_bf16 v[18:21], v[170:173], v[194:197], v[18:21]
	v_mfma_f32_16x16x32_bf16 v[6:9], v[162:165], v[202:205], v[6:9]
	v_mfma_f32_16x16x32_bf16 v[2:5], v[170:173], v[202:205], v[2:5]
	v_mfma_f32_16x16x32_bf16 v[54:57], v[166:169], v[182:185], v[54:57]
	v_mfma_f32_16x16x32_bf16 v[50:53], v[174:177], v[182:185], v[50:53]
	v_mfma_f32_16x16x32_bf16 v[38:41], v[166:169], v[190:193], v[38:41]
	v_mfma_f32_16x16x32_bf16 v[34:37], v[174:177], v[190:193], v[34:37]
	v_mfma_f32_16x16x32_bf16 v[22:25], v[166:169], v[198:201], v[22:25]
	v_mfma_f32_16x16x32_bf16 v[18:21], v[174:177], v[198:201], v[18:21]
	v_mfma_f32_16x16x32_bf16 v[6:9], v[166:169], v[206:209], v[6:9]
	v_mfma_f32_16x16x32_bf16 v[2:5], v[174:177], v[206:209], v[2:5]
	s_setprio 0
	s_barrier
	s_add_u32 s22, s28, 0x80000
	s_addc_u32 s23, s29, 0
	s_mov_b32 m0, s35
	v_lshl_add_u64 v[218:219], s[22:23], 0, v[132:133]
	global_load_lds_dwordx4 v[218:219], off
	v_lshl_add_u64 v[218:219], s[22:23], 0, v[130:131]
	s_mov_b32 m0, s36
	s_nop 0
	global_load_lds_dwordx4 v[218:219], off
	ds_read_b128 v[138:141], v147
	ds_read_b128 v[150:153], v147 offset:1024
	ds_read_b128 v[154:157], v147 offset:2048
	ds_read_b128 v[158:161], v147 offset:3072
	ds_read_b128 v[162:165], v148
	ds_read_b128 v[166:169], v148 offset:1024
	ds_read_b128 v[170:173], v148 offset:2048
	ds_read_b128 v[174:177], v148 offset:3072
	ds_read_b128 v[178:181], v146 offset:32768
	ds_read_b128 v[182:185], v146 offset:33792
	ds_read_b128 v[186:189], v146 offset:34816
	ds_read_b128 v[190:193], v146 offset:35840
	ds_read_b128 v[194:197], v146 offset:36864
	ds_read_b128 v[198:201], v146 offset:37888
	ds_read_b128 v[202:205], v146 offset:38912
	ds_read_b128 v[206:209], v146 offset:39936
	s_waitcnt vmcnt(8)
	s_waitcnt lgkmcnt(0)
	s_barrier
	s_setprio 1
	s_waitcnt lgkmcnt(0)
	v_mfma_f32_16x16x32_bf16 v[126:129], v[138:141], v[178:181], v[126:129]
	v_mfma_f32_16x16x32_bf16 v[122:125], v[154:157], v[178:181], v[122:125]
	v_mfma_f32_16x16x32_bf16 v[110:113], v[138:141], v[186:189], v[110:113]
	v_mfma_f32_16x16x32_bf16 v[106:109], v[154:157], v[186:189], v[106:109]
	v_mfma_f32_16x16x32_bf16 v[94:97], v[138:141], v[194:197], v[94:97]
	v_mfma_f32_16x16x32_bf16 v[90:93], v[154:157], v[194:197], v[90:93]
	v_mfma_f32_16x16x32_bf16 v[78:81], v[138:141], v[202:205], v[78:81]
	v_mfma_f32_16x16x32_bf16 v[74:77], v[154:157], v[202:205], v[74:77]
	v_mfma_f32_16x16x32_bf16 v[126:129], v[150:153], v[182:185], v[126:129]
	v_mfma_f32_16x16x32_bf16 v[122:125], v[158:161], v[182:185], v[122:125]
	v_mfma_f32_16x16x32_bf16 v[110:113], v[150:153], v[190:193], v[110:113]
	v_mfma_f32_16x16x32_bf16 v[106:109], v[158:161], v[190:193], v[106:109]
	v_mfma_f32_16x16x32_bf16 v[94:97], v[150:153], v[198:201], v[94:97]
	v_mfma_f32_16x16x32_bf16 v[90:93], v[158:161], v[198:201], v[90:93]
	v_mfma_f32_16x16x32_bf16 v[78:81], v[150:153], v[206:209], v[78:81]
	v_mfma_f32_16x16x32_bf16 v[74:77], v[158:161], v[206:209], v[74:77]
	s_setprio 0
	s_setprio 1
	v_mfma_f32_16x16x32_bf16 v[118:121], v[162:165], v[178:181], v[118:121]
	v_mfma_f32_16x16x32_bf16 v[114:117], v[170:173], v[178:181], v[114:117]
	v_mfma_f32_16x16x32_bf16 v[102:105], v[162:165], v[186:189], v[102:105]
	v_mfma_f32_16x16x32_bf16 v[98:101], v[170:173], v[186:189], v[98:101]
	v_mfma_f32_16x16x32_bf16 v[86:89], v[162:165], v[194:197], v[86:89]
	v_mfma_f32_16x16x32_bf16 v[82:85], v[170:173], v[194:197], v[82:85]
	v_mfma_f32_16x16x32_bf16 v[70:73], v[162:165], v[202:205], v[70:73]
	v_mfma_f32_16x16x32_bf16 v[66:69], v[170:173], v[202:205], v[66:69]
	v_mfma_f32_16x16x32_bf16 v[118:121], v[166:169], v[182:185], v[118:121]
	v_mfma_f32_16x16x32_bf16 v[114:117], v[174:177], v[182:185], v[114:117]
	v_mfma_f32_16x16x32_bf16 v[102:105], v[166:169], v[190:193], v[102:105]
	v_mfma_f32_16x16x32_bf16 v[98:101], v[174:177], v[190:193], v[98:101]
	v_mfma_f32_16x16x32_bf16 v[86:89], v[166:169], v[198:201], v[86:89]
	v_mfma_f32_16x16x32_bf16 v[82:85], v[174:177], v[198:201], v[82:85]
	v_mfma_f32_16x16x32_bf16 v[70:73], v[166:169], v[206:209], v[70:73]
	v_mfma_f32_16x16x32_bf16 v[66:69], v[174:177], v[206:209], v[66:69]
	s_setprio 0
	s_barrier
	s_mov_b32 m0, s48
	v_lshl_add_u64 v[210:211], v[210:211], 0, s[14:15]
	s_add_u32 s22, s26, 0x80080
	global_load_lds_dwordx4 v[210:211], off
	v_lshl_add_u64 v[210:211], v[212:213], 0, s[14:15]
	s_mov_b32 m0, s49
	s_addc_u32 s23, s27, 0
	global_load_lds_dwordx4 v[210:211], off
	v_lshl_add_u64 v[210:211], s[22:23], 0, v[132:133]
	s_mov_b32 m0, s50
	s_nop 0
	global_load_lds_dwordx4 v[210:211], off
	v_lshl_add_u64 v[210:211], s[22:23], 0, v[130:131]
	s_mov_b32 m0, s51
	s_nop 0
	global_load_lds_dwordx4 v[210:211], off
	v_lshl_add_u64 v[210:211], v[214:215], 0, s[14:15]
	s_mov_b32 m0, s39
	s_nop 0
	global_load_lds_dwordx4 v[210:211], off
	v_lshl_add_u64 v[210:211], v[216:217], 0, s[14:15]
	s_mov_b32 m0, s40
	s_nop 0
	global_load_lds_dwordx4 v[210:211], off
	ds_read_b128 v[178:181], v146 offset:49152
	ds_read_b128 v[182:185], v146 offset:50176
	ds_read_b128 v[186:189], v146 offset:51200
	ds_read_b128 v[190:193], v146 offset:52224
	ds_read_b128 v[194:197], v146 offset:53248
	ds_read_b128 v[198:201], v146 offset:54272
	ds_read_b128 v[202:205], v146 offset:55296
	ds_read_b128 v[206:209], v146 offset:56320
	s_waitcnt vmcnt(8)
	s_waitcnt lgkmcnt(0)
	s_barrier
	s_setprio 1
	s_waitcnt lgkmcnt(0)
	v_mfma_f32_16x16x32_bf16 v[62:65], v[138:141], v[178:181], v[62:65]
	v_mfma_f32_16x16x32_bf16 v[58:61], v[154:157], v[178:181], v[58:61]
	v_mfma_f32_16x16x32_bf16 v[46:49], v[138:141], v[186:189], v[46:49]
	v_mfma_f32_16x16x32_bf16 v[42:45], v[154:157], v[186:189], v[42:45]
	v_mfma_f32_16x16x32_bf16 v[30:33], v[138:141], v[194:197], v[30:33]
	v_mfma_f32_16x16x32_bf16 v[26:29], v[154:157], v[194:197], v[26:29]
	v_mfma_f32_16x16x32_bf16 v[14:17], v[138:141], v[202:205], v[14:17]
	v_mfma_f32_16x16x32_bf16 v[10:13], v[154:157], v[202:205], v[10:13]
	v_mfma_f32_16x16x32_bf16 v[62:65], v[150:153], v[182:185], v[62:65]
	v_mfma_f32_16x16x32_bf16 v[58:61], v[158:161], v[182:185], v[58:61]
	v_mfma_f32_16x16x32_bf16 v[46:49], v[150:153], v[190:193], v[46:49]
	v_mfma_f32_16x16x32_bf16 v[42:45], v[158:161], v[190:193], v[42:45]
	v_mfma_f32_16x16x32_bf16 v[30:33], v[150:153], v[198:201], v[30:33]
	v_mfma_f32_16x16x32_bf16 v[26:29], v[158:161], v[198:201], v[26:29]
	v_mfma_f32_16x16x32_bf16 v[14:17], v[150:153], v[206:209], v[14:17]
	v_mfma_f32_16x16x32_bf16 v[10:13], v[158:161], v[206:209], v[10:13]
	s_setprio 0
	s_setprio 1
	v_mfma_f32_16x16x32_bf16 v[54:57], v[162:165], v[178:181], v[54:57]
	v_mfma_f32_16x16x32_bf16 v[50:53], v[170:173], v[178:181], v[50:53]
	v_mfma_f32_16x16x32_bf16 v[38:41], v[162:165], v[186:189], v[38:41]
	v_mfma_f32_16x16x32_bf16 v[34:37], v[170:173], v[186:189], v[34:37]
	v_mfma_f32_16x16x32_bf16 v[22:25], v[162:165], v[194:197], v[22:25]
	v_mfma_f32_16x16x32_bf16 v[18:21], v[170:173], v[194:197], v[18:21]
	v_mfma_f32_16x16x32_bf16 v[6:9], v[162:165], v[202:205], v[6:9]
	v_mfma_f32_16x16x32_bf16 v[2:5], v[170:173], v[202:205], v[2:5]
	v_mfma_f32_16x16x32_bf16 v[54:57], v[166:169], v[182:185], v[54:57]
	v_mfma_f32_16x16x32_bf16 v[50:53], v[174:177], v[182:185], v[50:53]
	v_mfma_f32_16x16x32_bf16 v[38:41], v[166:169], v[190:193], v[38:41]
	v_mfma_f32_16x16x32_bf16 v[34:37], v[174:177], v[190:193], v[34:37]
	v_mfma_f32_16x16x32_bf16 v[22:25], v[166:169], v[198:201], v[22:25]
	v_mfma_f32_16x16x32_bf16 v[18:21], v[174:177], v[198:201], v[18:21]
	v_mfma_f32_16x16x32_bf16 v[6:9], v[166:169], v[206:209], v[6:9]
	v_mfma_f32_16x16x32_bf16 v[2:5], v[174:177], v[206:209], v[2:5]
	s_setprio 0
	s_barrier
	s_add_i32 s56, s56, 2
	s_cmp_gt_u32 s56, 29
	s_mov_b64 s[22:23], s[24:25]
	s_cbranch_scc0 .LBB0_2412
	s_and_b64 vcc, exec, s[16:17]
	s_cbranch_vccz .LBB0_2415
	s_barrier

.LBB0_2492:
	s_add_u32 s22, s0, 0xfff80080
	s_addc_u32 s23, s1, -1
	s_cmp_eq_u32 s48, 28
	s_cselect_b32 s25, s9, s23
	s_cselect_b32 s24, s8, s22
	s_cselect_b32 s23, s44, s47
	s_cselect_b32 s22, s45, s46
	v_lshl_add_u64 v[154:155], s[0:1], 0, v[146:147]
	s_add_i32 m0, s28, 0xc000
	s_nop 0
	global_load_lds_dwordx4 v[154:155], off
	v_lshl_add_u64 v[154:155], s[0:1], 0, v[148:149]
	s_add_i32 m0, s28, 0xe000
	s_nop 0
	global_load_lds_dwordx4 v[154:155], off
	ds_read_b128 v[130:133], v159
	ds_read_b128 v[134:137], v159 offset:1024
	ds_read_b128 v[164:167], v159 offset:2048
	ds_read_b128 v[168:171], v159 offset:3072
	ds_read_b128 v[172:175], v161
	ds_read_b128 v[182:185], v161 offset:1024
	ds_read_b128 v[186:189], v161 offset:2048
	ds_read_b128 v[190:193], v161 offset:3072
	ds_read_b128 v[194:197], v163
	ds_read_b128 v[198:201], v163 offset:1024
	ds_read_b128 v[202:205], v163 offset:2048
	ds_read_b128 v[206:209], v163 offset:3072
	ds_read_b128 v[210:213], v163 offset:4096
	ds_read_b128 v[214:217], v163 offset:5120
	ds_read_b128 v[218:221], v163 offset:6144
	ds_read_b128 v[222:225], v163 offset:7168
	s_waitcnt vmcnt(8)
	s_waitcnt lgkmcnt(0)
	s_barrier
	s_setprio 1
	s_waitcnt lgkmcnt(0)
	v_mfma_f32_16x16x32_bf16 v[126:129], v[130:133], v[194:197], v[126:129]
	v_mfma_f32_16x16x32_bf16 v[122:125], v[164:167], v[194:197], v[122:125]
	v_mfma_f32_16x16x32_bf16 v[118:121], v[130:133], v[202:205], v[118:121]
	v_mfma_f32_16x16x32_bf16 v[110:113], v[164:167], v[202:205], v[110:113]
	v_mfma_f32_16x16x32_bf16 v[102:105], v[130:133], v[210:213], v[102:105]
	v_mfma_f32_16x16x32_bf16 v[94:97], v[164:167], v[210:213], v[94:97]
	v_mfma_f32_16x16x32_bf16 v[86:89], v[130:133], v[218:221], v[86:89]
	v_mfma_f32_16x16x32_bf16 v[78:81], v[164:167], v[218:221], v[78:81]
	v_mfma_f32_16x16x32_bf16 v[126:129], v[134:137], v[198:201], v[126:129]
	v_mfma_f32_16x16x32_bf16 v[122:125], v[168:171], v[198:201], v[122:125]
	v_mfma_f32_16x16x32_bf16 v[118:121], v[134:137], v[206:209], v[118:121]
	v_mfma_f32_16x16x32_bf16 v[110:113], v[168:171], v[206:209], v[110:113]
	v_mfma_f32_16x16x32_bf16 v[102:105], v[134:137], v[214:217], v[102:105]
	v_mfma_f32_16x16x32_bf16 v[94:97], v[168:171], v[214:217], v[94:97]
	v_mfma_f32_16x16x32_bf16 v[86:89], v[134:137], v[222:225], v[86:89]
	v_mfma_f32_16x16x32_bf16 v[78:81], v[168:171], v[222:225], v[78:81]
	s_setprio 0
	s_setprio 1
	v_mfma_f32_16x16x32_bf16 v[114:117], v[172:175], v[194:197], v[114:117]
	v_mfma_f32_16x16x32_bf16 v[106:109], v[186:189], v[194:197], v[106:109]
	v_mfma_f32_16x16x32_bf16 v[98:101], v[172:175], v[202:205], v[98:101]
	v_mfma_f32_16x16x32_bf16 v[90:93], v[186:189], v[202:205], v[90:93]
	v_mfma_f32_16x16x32_bf16 v[82:85], v[172:175], v[210:213], v[82:85]
	v_mfma_f32_16x16x32_bf16 v[74:77], v[186:189], v[210:213], v[74:77]
	v_mfma_f32_16x16x32_bf16 v[70:73], v[172:175], v[218:221], v[70:73]
	v_mfma_f32_16x16x32_bf16 v[66:69], v[186:189], v[218:221], v[66:69]
	v_mfma_f32_16x16x32_bf16 v[114:117], v[182:185], v[198:201], v[114:117]
	v_mfma_f32_16x16x32_bf16 v[106:109], v[190:193], v[198:201], v[106:109]
	v_mfma_f32_16x16x32_bf16 v[98:101], v[182:185], v[206:209], v[98:101]
	v_mfma_f32_16x16x32_bf16 v[90:93], v[190:193], v[206:209], v[90:93]
	v_mfma_f32_16x16x32_bf16 v[82:85], v[182:185], v[214:217], v[82:85]
	v_mfma_f32_16x16x32_bf16 v[74:77], v[190:193], v[214:217], v[74:77]
	v_mfma_f32_16x16x32_bf16 v[70:73], v[182:185], v[222:225], v[70:73]
	v_mfma_f32_16x16x32_bf16 v[66:69], v[190:193], v[222:225], v[66:69]
	s_setprio 0
	s_barrier
	s_add_i32 s49, s64, s27
	v_lshl_add_u64 v[154:155], s[22:23], 0, v[142:143]
	s_mov_b32 m0, s49
	s_nop 0
	global_load_lds_dwordx4 v[154:155], off
	s_add_i32 m0, s49, 0x2000
	s_add_u32 s50, s22, 0x80000
	v_lshl_add_u64 v[176:177], s[22:23], 0, v[138:139]
	s_addc_u32 s51, s23, 0
	s_add_i32 s49, s65, s27
	global_load_lds_dwordx4 v[176:177], off
	v_lshl_add_u64 v[226:227], s[50:51], 0, v[142:143]
	s_mov_b32 m0, s49
	v_lshl_add_u64 v[228:229], s[24:25], 0, v[140:141]
	global_load_lds_dwordx4 v[226:227], off
	v_lshl_add_u64 v[226:227], s[50:51], 0, v[138:139]
	s_add_i32 m0, s49, 0x2000
	s_nop 0
	global_load_lds_dwordx4 v[226:227], off
	v_lshl_add_u64 v[226:227], s[24:25], 0, v[144:145]
	s_mov_b32 m0, s28
	s_nop 0
	global_load_lds_dwordx4 v[226:227], off
	s_mov_b32 m0, s29
	s_nop 0
	global_load_lds_dwordx4 v[228:229], off
	ds_read_b128 v[194:197], v163 offset:16384
	ds_read_b128 v[198:201], v163 offset:17408
	ds_read_b128 v[202:205], v163 offset:18432
	ds_read_b128 v[206:209], v163 offset:19456
	ds_read_b128 v[210:213], v163 offset:20480
	ds_read_b128 v[214:217], v163 offset:21504
	ds_read_b128 v[218:221], v163 offset:22528
	ds_read_b128 v[222:225], v163 offset:23552
	s_waitcnt vmcnt(8)
	s_waitcnt lgkmcnt(0)
	s_barrier
	s_setprio 1
	s_waitcnt lgkmcnt(0)
	v_mfma_f32_16x16x32_bf16 v[62:65], v[130:133], v[194:197], v[62:65]
	v_mfma_f32_16x16x32_bf16 v[58:61], v[164:167], v[194:197], v[58:61]
	v_mfma_f32_16x16x32_bf16 v[54:57], v[130:133], v[202:205], v[54:57]
	v_mfma_f32_16x16x32_bf16 v[46:49], v[164:167], v[202:205], v[46:49]
	v_mfma_f32_16x16x32_bf16 v[38:41], v[130:133], v[210:213], v[38:41]
	v_mfma_f32_16x16x32_bf16 v[30:33], v[164:167], v[210:213], v[30:33]
	v_mfma_f32_16x16x32_bf16 v[22:25], v[130:133], v[218:221], v[22:25]
	v_mfma_f32_16x16x32_bf16 v[14:17], v[164:167], v[218:221], v[14:17]
	v_mfma_f32_16x16x32_bf16 v[62:65], v[134:137], v[198:201], v[62:65]
	v_mfma_f32_16x16x32_bf16 v[58:61], v[168:171], v[198:201], v[58:61]
	v_mfma_f32_16x16x32_bf16 v[54:57], v[134:137], v[206:209], v[54:57]
	v_mfma_f32_16x16x32_bf16 v[46:49], v[168:171], v[206:209], v[46:49]
	v_mfma_f32_16x16x32_bf16 v[38:41], v[134:137], v[214:217], v[38:41]
	v_mfma_f32_16x16x32_bf16 v[30:33], v[168:171], v[214:217], v[30:33]
	v_mfma_f32_16x16x32_bf16 v[22:25], v[134:137], v[222:225], v[22:25]
	v_mfma_f32_16x16x32_bf16 v[14:17], v[168:171], v[222:225], v[14:17]
	s_setprio 0
	s_setprio 1
	v_mfma_f32_16x16x32_bf16 v[50:53], v[172:175], v[194:197], v[50:53]
	v_mfma_f32_16x16x32_bf16 v[42:45], v[186:189], v[194:197], v[42:45]
	v_mfma_f32_16x16x32_bf16 v[34:37], v[172:175], v[202:205], v[34:37]
	v_mfma_f32_16x16x32_bf16 v[26:29], v[186:189], v[202:205], v[26:29]
	v_mfma_f32_16x16x32_bf16 v[18:21], v[172:175], v[210:213], v[18:21]
	v_mfma_f32_16x16x32_bf16 v[10:13], v[186:189], v[210:213], v[10:13]
	v_mfma_f32_16x16x32_bf16 v[6:9], v[172:175], v[218:221], v[6:9]
	v_mfma_f32_16x16x32_bf16 v[2:5], v[186:189], v[218:221], v[2:5]
	v_mfma_f32_16x16x32_bf16 v[50:53], v[182:185], v[198:201], v[50:53]
	v_mfma_f32_16x16x32_bf16 v[42:45], v[190:193], v[198:201], v[42:45]
	v_mfma_f32_16x16x32_bf16 v[34:37], v[182:185], v[206:209], v[34:37]
	v_mfma_f32_16x16x32_bf16 v[26:29], v[190:193], v[206:209], v[26:29]
	v_mfma_f32_16x16x32_bf16 v[18:21], v[182:185], v[214:217], v[18:21]
	v_mfma_f32_16x16x32_bf16 v[10:13], v[190:193], v[214:217], v[10:13]
	v_mfma_f32_16x16x32_bf16 v[6:9], v[182:185], v[222:225], v[6:9]
	v_mfma_f32_16x16x32_bf16 v[2:5], v[190:193], v[222:225], v[2:5]
	s_setprio 0
	s_barrier
	s_add_u32 s24, s24, 0x80000
	s_addc_u32 s25, s25, 0
	s_mov_b32 m0, s30
	v_lshl_add_u64 v[230:231], s[24:25], 0, v[144:145]
	global_load_lds_dwordx4 v[230:231], off
	v_lshl_add_u64 v[230:231], s[24:25], 0, v[140:141]
	s_mov_b32 m0, s31
	s_nop 0
	global_load_lds_dwordx4 v[230:231], off
	v_add_u32_e32 v150, s66, v157
	ds_read_b128 v[130:133], v150
	ds_read_b128 v[134:137], v150 offset:1024
	ds_read_b128 v[164:167], v150 offset:2048
	ds_read_b128 v[168:171], v150 offset:3072
	v_add_u32_e32 v150, s67, v157
	ds_read_b128 v[172:175], v150
	ds_read_b128 v[182:185], v150 offset:1024
	ds_read_b128 v[186:189], v150 offset:2048
	ds_read_b128 v[190:193], v150 offset:3072
	ds_read_b128 v[194:197], v163 offset:32768
	ds_read_b128 v[198:201], v163 offset:33792
	ds_read_b128 v[202:205], v163 offset:34816
	ds_read_b128 v[206:209], v163 offset:35840
	ds_read_b128 v[210:213], v163 offset:36864
	ds_read_b128 v[214:217], v163 offset:37888
	ds_read_b128 v[218:221], v163 offset:38912
	ds_read_b128 v[222:225], v163 offset:39936
	s_waitcnt vmcnt(8)
	s_waitcnt lgkmcnt(0)
	s_barrier
	s_setprio 1
	s_waitcnt lgkmcnt(0)
	v_mfma_f32_16x16x32_bf16 v[126:129], v[130:133], v[194:197], v[126:129]
	v_mfma_f32_16x16x32_bf16 v[122:125], v[164:167], v[194:197], v[122:125]
	v_mfma_f32_16x16x32_bf16 v[118:121], v[130:133], v[202:205], v[118:121]
	v_mfma_f32_16x16x32_bf16 v[110:113], v[164:167], v[202:205], v[110:113]
	v_mfma_f32_16x16x32_bf16 v[102:105], v[130:133], v[210:213], v[102:105]
	v_mfma_f32_16x16x32_bf16 v[94:97], v[164:167], v[210:213], v[94:97]
	v_mfma_f32_16x16x32_bf16 v[86:89], v[130:133], v[218:221], v[86:89]
	v_mfma_f32_16x16x32_bf16 v[78:81], v[164:167], v[218:221], v[78:81]
	v_mfma_f32_16x16x32_bf16 v[126:129], v[134:137], v[198:201], v[126:129]
	v_mfma_f32_16x16x32_bf16 v[122:125], v[168:171], v[198:201], v[122:125]
	v_mfma_f32_16x16x32_bf16 v[118:121], v[134:137], v[206:209], v[118:121]
	v_mfma_f32_16x16x32_bf16 v[110:113], v[168:171], v[206:209], v[110:113]
	v_mfma_f32_16x16x32_bf16 v[102:105], v[134:137], v[214:217], v[102:105]
	v_mfma_f32_16x16x32_bf16 v[94:97], v[168:171], v[214:217], v[94:97]
	v_mfma_f32_16x16x32_bf16 v[86:89], v[134:137], v[222:225], v[86:89]
	v_mfma_f32_16x16x32_bf16 v[78:81], v[168:171], v[222:225], v[78:81]
	s_setprio 0
	s_setprio 1
	v_mfma_f32_16x16x32_bf16 v[114:117], v[172:175], v[194:197], v[114:117]
	v_mfma_f32_16x16x32_bf16 v[106:109], v[186:189], v[194:197], v[106:109]
	v_mfma_f32_16x16x32_bf16 v[98:101], v[172:175], v[202:205], v[98:101]
	v_mfma_f32_16x16x32_bf16 v[90:93], v[186:189], v[202:205], v[90:93]
	v_mfma_f32_16x16x32_bf16 v[82:85], v[172:175], v[210:213], v[82:85]
	v_mfma_f32_16x16x32_bf16 v[74:77], v[186:189], v[210:213], v[74:77]
	v_mfma_f32_16x16x32_bf16 v[70:73], v[172:175], v[218:221], v[70:73]
	v_mfma_f32_16x16x32_bf16 v[66:69], v[186:189], v[218:221], v[66:69]
	v_mfma_f32_16x16x32_bf16 v[114:117], v[182:185], v[198:201], v[114:117]
	v_mfma_f32_16x16x32_bf16 v[106:109], v[190:193], v[198:201], v[106:109]
	v_mfma_f32_16x16x32_bf16 v[98:101], v[182:185], v[206:209], v[98:101]
	v_mfma_f32_16x16x32_bf16 v[90:93], v[190:193], v[206:209], v[90:93]
	v_mfma_f32_16x16x32_bf16 v[82:85], v[182:185], v[214:217], v[82:85]
	v_mfma_f32_16x16x32_bf16 v[74:77], v[190:193], v[214:217], v[74:77]
	v_mfma_f32_16x16x32_bf16 v[70:73], v[182:185], v[222:225], v[70:73]
	v_mfma_f32_16x16x32_bf16 v[66:69], v[190:193], v[222:225], v[66:69]
	s_setprio 0
	s_barrier
	s_add_i32 s24, s66, s27
	v_lshl_add_u64 v[154:155], v[154:155], 0, s[12:13]
	s_mov_b32 m0, s24
	s_nop 0
	global_load_lds_dwordx4 v[154:155], off
	s_add_i32 m0, s24, 0x2000
	s_add_u32 s22, s22, 0x80080
	v_lshl_add_u64 v[154:155], v[176:177], 0, s[12:13]
	s_addc_u32 s23, s23, 0
	s_add_i32 s24, s67, s27
	global_load_lds_dwordx4 v[154:155], off
	v_lshl_add_u64 v[154:155], s[22:23], 0, v[142:143]
	s_mov_b32 m0, s24
	s_nop 0
	global_load_lds_dwordx4 v[154:155], off
	v_lshl_add_u64 v[154:155], s[22:23], 0, v[138:139]
	s_add_i32 m0, s24, 0x2000
	s_nop 0
	global_load_lds_dwordx4 v[154:155], off
	v_lshl_add_u64 v[154:155], v[226:227], 0, s[12:13]
	s_mov_b32 m0, s35
	s_nop 0
	global_load_lds_dwordx4 v[154:155], off
	v_lshl_add_u64 v[154:155], v[228:229], 0, s[12:13]
	s_mov_b32 m0, s36
	s_nop 0
	global_load_lds_dwordx4 v[154:155], off
	ds_read_b128 v[194:197], v163 offset:49152
	ds_read_b128 v[198:201], v163 offset:50176
	ds_read_b128 v[202:205], v163 offset:51200
	ds_read_b128 v[206:209], v163 offset:52224
	ds_read_b128 v[210:213], v163 offset:53248
	ds_read_b128 v[214:217], v163 offset:54272
	ds_read_b128 v[218:221], v163 offset:55296
	ds_read_b128 v[222:225], v163 offset:56320
	s_waitcnt vmcnt(8)
	s_waitcnt lgkmcnt(0)
	s_barrier
	s_setprio 1
	s_waitcnt lgkmcnt(0)
	v_mfma_f32_16x16x32_bf16 v[62:65], v[130:133], v[194:197], v[62:65]
	v_mfma_f32_16x16x32_bf16 v[58:61], v[164:167], v[194:197], v[58:61]
	v_mfma_f32_16x16x32_bf16 v[54:57], v[130:133], v[202:205], v[54:57]
	v_mfma_f32_16x16x32_bf16 v[46:49], v[164:167], v[202:205], v[46:49]
	v_mfma_f32_16x16x32_bf16 v[38:41], v[130:133], v[210:213], v[38:41]
	v_mfma_f32_16x16x32_bf16 v[30:33], v[164:167], v[210:213], v[30:33]
	v_mfma_f32_16x16x32_bf16 v[22:25], v[130:133], v[218:221], v[22:25]
	v_mfma_f32_16x16x32_bf16 v[14:17], v[164:167], v[218:221], v[14:17]
	v_mfma_f32_16x16x32_bf16 v[62:65], v[134:137], v[198:201], v[62:65]
	v_mfma_f32_16x16x32_bf16 v[58:61], v[168:171], v[198:201], v[58:61]
	v_mfma_f32_16x16x32_bf16 v[54:57], v[134:137], v[206:209], v[54:57]
	v_mfma_f32_16x16x32_bf16 v[46:49], v[168:171], v[206:209], v[46:49]
	v_mfma_f32_16x16x32_bf16 v[38:41], v[134:137], v[214:217], v[38:41]
	v_mfma_f32_16x16x32_bf16 v[30:33], v[168:171], v[214:217], v[30:33]
	v_mfma_f32_16x16x32_bf16 v[22:25], v[134:137], v[222:225], v[22:25]
	v_mfma_f32_16x16x32_bf16 v[14:17], v[168:171], v[222:225], v[14:17]
	s_setprio 0
	s_setprio 1
	v_mfma_f32_16x16x32_bf16 v[50:53], v[172:175], v[194:197], v[50:53]
	v_mfma_f32_16x16x32_bf16 v[42:45], v[186:189], v[194:197], v[42:45]
	v_mfma_f32_16x16x32_bf16 v[34:37], v[172:175], v[202:205], v[34:37]
	v_mfma_f32_16x16x32_bf16 v[26:29], v[186:189], v[202:205], v[26:29]
	v_mfma_f32_16x16x32_bf16 v[18:21], v[172:175], v[210:213], v[18:21]
	v_mfma_f32_16x16x32_bf16 v[10:13], v[186:189], v[210:213], v[10:13]
	v_mfma_f32_16x16x32_bf16 v[6:9], v[172:175], v[218:221], v[6:9]
	v_mfma_f32_16x16x32_bf16 v[2:5], v[186:189], v[218:221], v[2:5]
	v_mfma_f32_16x16x32_bf16 v[50:53], v[182:185], v[198:201], v[50:53]
	v_mfma_f32_16x16x32_bf16 v[42:45], v[190:193], v[198:201], v[42:45]
	v_mfma_f32_16x16x32_bf16 v[34:37], v[182:185], v[206:209], v[34:37]
	v_mfma_f32_16x16x32_bf16 v[26:29], v[190:193], v[206:209], v[26:29]
	v_mfma_f32_16x16x32_bf16 v[18:21], v[182:185], v[214:217], v[18:21]
	v_mfma_f32_16x16x32_bf16 v[10:13], v[190:193], v[214:217], v[10:13]
	v_mfma_f32_16x16x32_bf16 v[6:9], v[182:185], v[222:225], v[6:9]
	v_mfma_f32_16x16x32_bf16 v[2:5], v[190:193], v[222:225], v[2:5]
	s_setprio 0
	s_barrier
	s_add_i32 s48, s48, 2
	s_add_u32 s0, s0, 0x100
	s_addc_u32 s1, s1, 0
	s_add_u32 s46, s46, 0x100
	s_addc_u32 s47, s47, 0
	s_cmp_gt_u32 s48, 29
	s_cbranch_scc0 .LBB0_2492
	s_and_b64 vcc, exec, s[14:15]
	s_cbranch_vccz .LBB0_2495
	s_barrier

.LBB0_2644:
	s_add_u32 s20, s18, 0x100
	s_addc_u32 s21, s19, 0
	s_add_u32 s22, s4, s18
	s_addc_u32 s23, s52, s19
	s_cmpk_eq_i32 s53, 0x54
	s_cselect_b32 s24, 0, s20
	s_cselect_b32 s25, 0, s21
	s_cselect_b32 s22, s14, s22
	s_cselect_b32 s23, s15, s23
	s_add_u32 s24, s0, s24
	s_addc_u32 s25, s1, s25
	s_mov_b32 m0, s39
	v_lshl_add_u64 v[214:215], v[134:135], 0, s[18:19]
	global_load_lds_dwordx4 v[214:215], off
	v_lshl_add_u64 v[214:215], v[136:137], 0, s[18:19]
	s_mov_b32 m0, s41
	s_nop 0
	global_load_lds_dwordx4 v[214:215], off
	ds_read_b128 v[138:141], v144
	ds_read_b128 v[150:153], v144 offset:1024
	ds_read_b128 v[154:157], v144 offset:2048
	ds_read_b128 v[158:161], v144 offset:3072
	ds_read_b128 v[162:165], v145
	ds_read_b128 v[166:169], v145 offset:1024
	ds_read_b128 v[170:173], v145 offset:2048
	ds_read_b128 v[174:177], v145 offset:3072
	ds_read_b128 v[182:185], v146
	ds_read_b128 v[186:189], v146 offset:1024
	ds_read_b128 v[190:193], v146 offset:2048
	ds_read_b128 v[194:197], v146 offset:3072
	ds_read_b128 v[198:201], v146 offset:4096
	ds_read_b128 v[202:205], v146 offset:5120
	ds_read_b128 v[206:209], v146 offset:6144
	ds_read_b128 v[210:213], v146 offset:7168
	s_waitcnt vmcnt(8)
	s_waitcnt lgkmcnt(0)
	s_barrier
	s_setprio 1
	s_waitcnt lgkmcnt(0)
	v_mfma_f32_16x16x32_bf16 v[126:129], v[138:141], v[182:185], v[126:129]
	v_mfma_f32_16x16x32_bf16 v[122:125], v[154:157], v[182:185], v[122:125]
	v_mfma_f32_16x16x32_bf16 v[110:113], v[138:141], v[190:193], v[110:113]
	v_mfma_f32_16x16x32_bf16 v[106:109], v[154:157], v[190:193], v[106:109]
	v_mfma_f32_16x16x32_bf16 v[94:97], v[138:141], v[198:201], v[94:97]
	v_mfma_f32_16x16x32_bf16 v[90:93], v[154:157], v[198:201], v[90:93]
	v_mfma_f32_16x16x32_bf16 v[78:81], v[138:141], v[206:209], v[78:81]
	v_mfma_f32_16x16x32_bf16 v[74:77], v[154:157], v[206:209], v[74:77]
	v_mfma_f32_16x16x32_bf16 v[126:129], v[150:153], v[186:189], v[126:129]
	v_mfma_f32_16x16x32_bf16 v[122:125], v[158:161], v[186:189], v[122:125]
	v_mfma_f32_16x16x32_bf16 v[110:113], v[150:153], v[194:197], v[110:113]
	v_mfma_f32_16x16x32_bf16 v[106:109], v[158:161], v[194:197], v[106:109]
	v_mfma_f32_16x16x32_bf16 v[94:97], v[150:153], v[202:205], v[94:97]
	v_mfma_f32_16x16x32_bf16 v[90:93], v[158:161], v[202:205], v[90:93]
	v_mfma_f32_16x16x32_bf16 v[78:81], v[150:153], v[210:213], v[78:81]
	v_mfma_f32_16x16x32_bf16 v[74:77], v[158:161], v[210:213], v[74:77]
	s_setprio 0
	s_setprio 1
	v_mfma_f32_16x16x32_bf16 v[118:121], v[162:165], v[182:185], v[118:121]
	v_mfma_f32_16x16x32_bf16 v[114:117], v[170:173], v[182:185], v[114:117]
	v_mfma_f32_16x16x32_bf16 v[102:105], v[162:165], v[190:193], v[102:105]
	v_mfma_f32_16x16x32_bf16 v[98:101], v[170:173], v[190:193], v[98:101]
	v_mfma_f32_16x16x32_bf16 v[86:89], v[162:165], v[198:201], v[86:89]
	v_mfma_f32_16x16x32_bf16 v[82:85], v[170:173], v[198:201], v[82:85]
	v_mfma_f32_16x16x32_bf16 v[70:73], v[162:165], v[206:209], v[70:73]
	v_mfma_f32_16x16x32_bf16 v[66:69], v[170:173], v[206:209], v[66:69]
	v_mfma_f32_16x16x32_bf16 v[118:121], v[166:169], v[186:189], v[118:121]
	v_mfma_f32_16x16x32_bf16 v[114:117], v[174:177], v[186:189], v[114:117]
	v_mfma_f32_16x16x32_bf16 v[102:105], v[166:169], v[194:197], v[102:105]
	v_mfma_f32_16x16x32_bf16 v[98:101], v[174:177], v[194:197], v[98:101]
	v_mfma_f32_16x16x32_bf16 v[86:89], v[166:169], v[202:205], v[86:89]
	v_mfma_f32_16x16x32_bf16 v[82:85], v[174:177], v[202:205], v[82:85]
	v_mfma_f32_16x16x32_bf16 v[70:73], v[166:169], v[210:213], v[70:73]
	v_mfma_f32_16x16x32_bf16 v[66:69], v[174:177], v[210:213], v[66:69]
	s_setprio 0
	s_barrier
	s_mov_b32 m0, s42
	v_lshl_add_u64 v[214:215], s[22:23], 0, v[132:133]
	s_add_u32 s18, s22, 0x160000
	global_load_lds_dwordx4 v[214:215], off
	v_lshl_add_u64 v[216:217], s[22:23], 0, v[130:131]
	s_mov_b32 m0, s43
	s_addc_u32 s19, s23, 0
	global_load_lds_dwordx4 v[216:217], off
	v_lshl_add_u64 v[218:219], s[18:19], 0, v[132:133]
	s_mov_b32 m0, s44
	v_lshl_add_u64 v[220:221], s[24:25], 0, v[130:131]
	global_load_lds_dwordx4 v[218:219], off
	v_lshl_add_u64 v[218:219], s[18:19], 0, v[130:131]
	s_mov_b32 m0, s45
	s_nop 0
	global_load_lds_dwordx4 v[218:219], off
	v_lshl_add_u64 v[218:219], s[24:25], 0, v[132:133]
	s_mov_b32 m0, s28
	s_nop 0
	global_load_lds_dwordx4 v[218:219], off
	s_mov_b32 m0, s29
	s_nop 0
	global_load_lds_dwordx4 v[220:221], off
	ds_read_b128 v[182:185], v146 offset:16384
	ds_read_b128 v[186:189], v146 offset:17408
	ds_read_b128 v[190:193], v146 offset:18432
	ds_read_b128 v[194:197], v146 offset:19456
	ds_read_b128 v[198:201], v146 offset:20480
	ds_read_b128 v[202:205], v146 offset:21504
	ds_read_b128 v[206:209], v146 offset:22528
	ds_read_b128 v[210:213], v146 offset:23552
	s_waitcnt vmcnt(8)
	s_waitcnt lgkmcnt(0)
	s_barrier
	s_setprio 1
	s_waitcnt lgkmcnt(0)
	v_mfma_f32_16x16x32_bf16 v[62:65], v[138:141], v[182:185], v[62:65]
	v_mfma_f32_16x16x32_bf16 v[58:61], v[154:157], v[182:185], v[58:61]
	v_mfma_f32_16x16x32_bf16 v[46:49], v[138:141], v[190:193], v[46:49]
	v_mfma_f32_16x16x32_bf16 v[42:45], v[154:157], v[190:193], v[42:45]
	v_mfma_f32_16x16x32_bf16 v[30:33], v[138:141], v[198:201], v[30:33]
	v_mfma_f32_16x16x32_bf16 v[26:29], v[154:157], v[198:201], v[26:29]
	v_mfma_f32_16x16x32_bf16 v[14:17], v[138:141], v[206:209], v[14:17]
	v_mfma_f32_16x16x32_bf16 v[10:13], v[154:157], v[206:209], v[10:13]
	v_mfma_f32_16x16x32_bf16 v[62:65], v[150:153], v[186:189], v[62:65]
	v_mfma_f32_16x16x32_bf16 v[58:61], v[158:161], v[186:189], v[58:61]
	v_mfma_f32_16x16x32_bf16 v[46:49], v[150:153], v[194:197], v[46:49]
	v_mfma_f32_16x16x32_bf16 v[42:45], v[158:161], v[194:197], v[42:45]
	v_mfma_f32_16x16x32_bf16 v[30:33], v[150:153], v[202:205], v[30:33]
	v_mfma_f32_16x16x32_bf16 v[26:29], v[158:161], v[202:205], v[26:29]
	v_mfma_f32_16x16x32_bf16 v[14:17], v[150:153], v[210:213], v[14:17]
	v_mfma_f32_16x16x32_bf16 v[10:13], v[158:161], v[210:213], v[10:13]
	s_setprio 0
	s_setprio 1
	v_mfma_f32_16x16x32_bf16 v[54:57], v[162:165], v[182:185], v[54:57]
	v_mfma_f32_16x16x32_bf16 v[50:53], v[170:173], v[182:185], v[50:53]
	v_mfma_f32_16x16x32_bf16 v[38:41], v[162:165], v[190:193], v[38:41]
	v_mfma_f32_16x16x32_bf16 v[34:37], v[170:173], v[190:193], v[34:37]
	v_mfma_f32_16x16x32_bf16 v[22:25], v[162:165], v[198:201], v[22:25]
	v_mfma_f32_16x16x32_bf16 v[18:21], v[170:173], v[198:201], v[18:21]
	v_mfma_f32_16x16x32_bf16 v[6:9], v[162:165], v[206:209], v[6:9]
	v_mfma_f32_16x16x32_bf16 v[2:5], v[170:173], v[206:209], v[2:5]
	v_mfma_f32_16x16x32_bf16 v[54:57], v[166:169], v[186:189], v[54:57]
	v_mfma_f32_16x16x32_bf16 v[50:53], v[174:177], v[186:189], v[50:53]
	v_mfma_f32_16x16x32_bf16 v[38:41], v[166:169], v[194:197], v[38:41]
	v_mfma_f32_16x16x32_bf16 v[34:37], v[174:177], v[194:197], v[34:37]
	v_mfma_f32_16x16x32_bf16 v[22:25], v[166:169], v[202:205], v[22:25]
	v_mfma_f32_16x16x32_bf16 v[18:21], v[174:177], v[202:205], v[18:21]
	v_mfma_f32_16x16x32_bf16 v[6:9], v[166:169], v[210:213], v[6:9]
	v_mfma_f32_16x16x32_bf16 v[2:5], v[174:177], v[210:213], v[2:5]
	s_setprio 0
	s_barrier
	s_add_u32 s18, s24, 0x160000
	s_addc_u32 s19, s25, 0
	s_mov_b32 m0, s30
	v_lshl_add_u64 v[222:223], s[18:19], 0, v[132:133]
	global_load_lds_dwordx4 v[222:223], off
	v_lshl_add_u64 v[222:223], s[18:19], 0, v[130:131]
	s_mov_b32 m0, s31
	s_nop 0
	global_load_lds_dwordx4 v[222:223], off
	ds_read_b128 v[138:141], v147
	ds_read_b128 v[150:153], v147 offset:1024
	ds_read_b128 v[154:157], v147 offset:2048
	ds_read_b128 v[158:161], v147 offset:3072
	ds_read_b128 v[162:165], v148
	ds_read_b128 v[166:169], v148 offset:1024
	ds_read_b128 v[170:173], v148 offset:2048
	ds_read_b128 v[174:177], v148 offset:3072
	ds_read_b128 v[182:185], v146 offset:32768
	ds_read_b128 v[186:189], v146 offset:33792
	ds_read_b128 v[190:193], v146 offset:34816
	ds_read_b128 v[194:197], v146 offset:35840
	ds_read_b128 v[198:201], v146 offset:36864
	ds_read_b128 v[202:205], v146 offset:37888
	ds_read_b128 v[206:209], v146 offset:38912
	ds_read_b128 v[210:213], v146 offset:39936
	s_waitcnt vmcnt(8)
	s_waitcnt lgkmcnt(0)
	s_barrier
	s_setprio 1
	s_waitcnt lgkmcnt(0)
	v_mfma_f32_16x16x32_bf16 v[126:129], v[138:141], v[182:185], v[126:129]
	v_mfma_f32_16x16x32_bf16 v[122:125], v[154:157], v[182:185], v[122:125]
	v_mfma_f32_16x16x32_bf16 v[110:113], v[138:141], v[190:193], v[110:113]
	v_mfma_f32_16x16x32_bf16 v[106:109], v[154:157], v[190:193], v[106:109]
	v_mfma_f32_16x16x32_bf16 v[94:97], v[138:141], v[198:201], v[94:97]
	v_mfma_f32_16x16x32_bf16 v[90:93], v[154:157], v[198:201], v[90:93]
	v_mfma_f32_16x16x32_bf16 v[78:81], v[138:141], v[206:209], v[78:81]
	v_mfma_f32_16x16x32_bf16 v[74:77], v[154:157], v[206:209], v[74:77]
	v_mfma_f32_16x16x32_bf16 v[126:129], v[150:153], v[186:189], v[126:129]
	v_mfma_f32_16x16x32_bf16 v[122:125], v[158:161], v[186:189], v[122:125]
	v_mfma_f32_16x16x32_bf16 v[110:113], v[150:153], v[194:197], v[110:113]
	v_mfma_f32_16x16x32_bf16 v[106:109], v[158:161], v[194:197], v[106:109]
	v_mfma_f32_16x16x32_bf16 v[94:97], v[150:153], v[202:205], v[94:97]
	v_mfma_f32_16x16x32_bf16 v[90:93], v[158:161], v[202:205], v[90:93]
	v_mfma_f32_16x16x32_bf16 v[78:81], v[150:153], v[210:213], v[78:81]
	v_mfma_f32_16x16x32_bf16 v[74:77], v[158:161], v[210:213], v[74:77]
	s_setprio 0
	s_setprio 1
	v_mfma_f32_16x16x32_bf16 v[118:121], v[162:165], v[182:185], v[118:121]
	v_mfma_f32_16x16x32_bf16 v[114:117], v[170:173], v[182:185], v[114:117]
	v_mfma_f32_16x16x32_bf16 v[102:105], v[162:165], v[190:193], v[102:105]
	v_mfma_f32_16x16x32_bf16 v[98:101], v[170:173], v[190:193], v[98:101]
	v_mfma_f32_16x16x32_bf16 v[86:89], v[162:165], v[198:201], v[86:89]
	v_mfma_f32_16x16x32_bf16 v[82:85], v[170:173], v[198:201], v[82:85]
	v_mfma_f32_16x16x32_bf16 v[70:73], v[162:165], v[206:209], v[70:73]
	v_mfma_f32_16x16x32_bf16 v[66:69], v[170:173], v[206:209], v[66:69]
	v_mfma_f32_16x16x32_bf16 v[118:121], v[166:169], v[186:189], v[118:121]
	v_mfma_f32_16x16x32_bf16 v[114:117], v[174:177], v[186:189], v[114:117]
	v_mfma_f32_16x16x32_bf16 v[102:105], v[166:169], v[194:197], v[102:105]
	v_mfma_f32_16x16x32_bf16 v[98:101], v[174:177], v[194:197], v[98:101]
	v_mfma_f32_16x16x32_bf16 v[86:89], v[166:169], v[202:205], v[86:89]
	v_mfma_f32_16x16x32_bf16 v[82:85], v[174:177], v[202:205], v[82:85]
	v_mfma_f32_16x16x32_bf16 v[70:73], v[166:169], v[210:213], v[70:73]
	v_mfma_f32_16x16x32_bf16 v[66:69], v[174:177], v[210:213], v[66:69]
	s_setprio 0
	s_barrier
	s_mov_b32 m0, s46
	v_lshl_add_u64 v[214:215], v[214:215], 0, s[10:11]
	s_add_u32 s18, s22, 0x160080
	global_load_lds_dwordx4 v[214:215], off
	v_lshl_add_u64 v[214:215], v[216:217], 0, s[10:11]
	s_mov_b32 m0, s47
	s_addc_u32 s19, s23, 0
	global_load_lds_dwordx4 v[214:215], off
	v_lshl_add_u64 v[214:215], s[18:19], 0, v[132:133]
	s_mov_b32 m0, s48
	s_nop 0
	global_load_lds_dwordx4 v[214:215], off
	v_lshl_add_u64 v[214:215], s[18:19], 0, v[130:131]
	s_mov_b32 m0, s49
	s_nop 0
	global_load_lds_dwordx4 v[214:215], off
	v_lshl_add_u64 v[214:215], v[218:219], 0, s[10:11]
	s_mov_b32 m0, s36
	s_nop 0
	global_load_lds_dwordx4 v[214:215], off
	v_lshl_add_u64 v[214:215], v[220:221], 0, s[10:11]
	s_mov_b32 m0, s37
	s_nop 0
	global_load_lds_dwordx4 v[214:215], off
	ds_read_b128 v[182:185], v146 offset:49152
	ds_read_b128 v[186:189], v146 offset:50176
	ds_read_b128 v[190:193], v146 offset:51200
	ds_read_b128 v[194:197], v146 offset:52224
	ds_read_b128 v[198:201], v146 offset:53248
	ds_read_b128 v[202:205], v146 offset:54272
	ds_read_b128 v[206:209], v146 offset:55296
	ds_read_b128 v[210:213], v146 offset:56320
	s_waitcnt vmcnt(8)
	s_waitcnt lgkmcnt(0)
	s_barrier
	s_setprio 1
	s_waitcnt lgkmcnt(0)
	v_mfma_f32_16x16x32_bf16 v[62:65], v[138:141], v[182:185], v[62:65]
	v_mfma_f32_16x16x32_bf16 v[58:61], v[154:157], v[182:185], v[58:61]
	v_mfma_f32_16x16x32_bf16 v[46:49], v[138:141], v[190:193], v[46:49]
	v_mfma_f32_16x16x32_bf16 v[42:45], v[154:157], v[190:193], v[42:45]
	v_mfma_f32_16x16x32_bf16 v[30:33], v[138:141], v[198:201], v[30:33]
	v_mfma_f32_16x16x32_bf16 v[26:29], v[154:157], v[198:201], v[26:29]
	v_mfma_f32_16x16x32_bf16 v[14:17], v[138:141], v[206:209], v[14:17]
	v_mfma_f32_16x16x32_bf16 v[10:13], v[154:157], v[206:209], v[10:13]
	v_mfma_f32_16x16x32_bf16 v[62:65], v[150:153], v[186:189], v[62:65]
	v_mfma_f32_16x16x32_bf16 v[58:61], v[158:161], v[186:189], v[58:61]
	v_mfma_f32_16x16x32_bf16 v[46:49], v[150:153], v[194:197], v[46:49]
	v_mfma_f32_16x16x32_bf16 v[42:45], v[158:161], v[194:197], v[42:45]
	v_mfma_f32_16x16x32_bf16 v[30:33], v[150:153], v[202:205], v[30:33]
	v_mfma_f32_16x16x32_bf16 v[26:29], v[158:161], v[202:205], v[26:29]
	v_mfma_f32_16x16x32_bf16 v[14:17], v[150:153], v[210:213], v[14:17]
	v_mfma_f32_16x16x32_bf16 v[10:13], v[158:161], v[210:213], v[10:13]
	s_setprio 0
	s_setprio 1
	v_mfma_f32_16x16x32_bf16 v[54:57], v[162:165], v[182:185], v[54:57]
	v_mfma_f32_16x16x32_bf16 v[50:53], v[170:173], v[182:185], v[50:53]
	v_mfma_f32_16x16x32_bf16 v[38:41], v[162:165], v[190:193], v[38:41]
	v_mfma_f32_16x16x32_bf16 v[34:37], v[170:173], v[190:193], v[34:37]
	v_mfma_f32_16x16x32_bf16 v[22:25], v[162:165], v[198:201], v[22:25]
	v_mfma_f32_16x16x32_bf16 v[18:21], v[170:173], v[198:201], v[18:21]
	v_mfma_f32_16x16x32_bf16 v[6:9], v[162:165], v[206:209], v[6:9]
	v_mfma_f32_16x16x32_bf16 v[2:5], v[170:173], v[206:209], v[2:5]
	v_mfma_f32_16x16x32_bf16 v[54:57], v[166:169], v[186:189], v[54:57]
	v_mfma_f32_16x16x32_bf16 v[50:53], v[174:177], v[186:189], v[50:53]
	v_mfma_f32_16x16x32_bf16 v[38:41], v[166:169], v[194:197], v[38:41]
	v_mfma_f32_16x16x32_bf16 v[34:37], v[174:177], v[194:197], v[34:37]
	v_mfma_f32_16x16x32_bf16 v[22:25], v[166:169], v[202:205], v[22:25]
	v_mfma_f32_16x16x32_bf16 v[18:21], v[174:177], v[202:205], v[18:21]
	v_mfma_f32_16x16x32_bf16 v[6:9], v[166:169], v[210:213], v[6:9]
	v_mfma_f32_16x16x32_bf16 v[2:5], v[174:177], v[210:213], v[2:5]
	s_setprio 0
	s_barrier
	s_add_i32 s53, s53, 2
	s_cmpk_gt_u32 s53, 0x55
	s_mov_b64 s[18:19], s[20:21]
	s_cbranch_scc0 .LBB0_2644
	s_and_b64 vcc, exec, s[12:13]
	s_cbranch_vccz .LBB0_2647
	s_barrier

.LBB0_3378:
	s_add_u32 s20, s18, 0x100
	s_addc_u32 s21, s19, 0
	s_cmpk_eq_i32 s49, 0x54
	s_cselect_b32 s25, s7, s21
	s_cselect_b32 s24, s6, s20
	s_cselect_b32 s23, s17, s48
	s_cselect_b32 s22, s16, s47
	v_lshl_add_u64 v[212:213], s[18:19], 0, v[134:135]
	s_add_i32 m0, s28, 0xc000
	s_nop 0
	global_load_lds_dwordx4 v[212:213], off
	v_lshl_add_u64 v[212:213], s[18:19], 0, v[136:137]
	s_add_i32 m0, s28, 0xe000
	s_nop 0
	global_load_lds_dwordx4 v[212:213], off
	ds_read_b128 v[142:145], v148
	ds_read_b128 v[152:155], v148 offset:1024
	ds_read_b128 v[156:159], v148 offset:2048
	ds_read_b128 v[160:163], v148 offset:3072
	ds_read_b128 v[164:167], v149
	ds_read_b128 v[168:171], v149 offset:1024
	ds_read_b128 v[172:175], v149 offset:2048
	ds_read_b128 v[176:179], v149 offset:3072
	ds_read_b128 v[180:183], v150
	ds_read_b128 v[184:187], v150 offset:1024
	ds_read_b128 v[188:191], v150 offset:2048
	ds_read_b128 v[192:195], v150 offset:3072
	ds_read_b128 v[196:199], v150 offset:4096
	ds_read_b128 v[200:203], v150 offset:5120
	ds_read_b128 v[204:207], v150 offset:6144
	ds_read_b128 v[208:211], v150 offset:7168
	s_waitcnt vmcnt(8)
	s_waitcnt lgkmcnt(0)
	s_barrier
	s_setprio 1
	s_waitcnt lgkmcnt(0)
	v_mfma_f32_16x16x32_bf16 v[126:129], v[142:145], v[180:183], v[126:129]
	v_mfma_f32_16x16x32_bf16 v[122:125], v[156:159], v[180:183], v[122:125]
	v_mfma_f32_16x16x32_bf16 v[110:113], v[142:145], v[188:191], v[110:113]
	v_mfma_f32_16x16x32_bf16 v[106:109], v[156:159], v[188:191], v[106:109]
	v_mfma_f32_16x16x32_bf16 v[94:97], v[142:145], v[196:199], v[94:97]
	v_mfma_f32_16x16x32_bf16 v[90:93], v[156:159], v[196:199], v[90:93]
	v_mfma_f32_16x16x32_bf16 v[78:81], v[142:145], v[204:207], v[78:81]
	v_mfma_f32_16x16x32_bf16 v[74:77], v[156:159], v[204:207], v[74:77]
	v_mfma_f32_16x16x32_bf16 v[126:129], v[152:155], v[184:187], v[126:129]
	v_mfma_f32_16x16x32_bf16 v[122:125], v[160:163], v[184:187], v[122:125]
	v_mfma_f32_16x16x32_bf16 v[110:113], v[152:155], v[192:195], v[110:113]
	v_mfma_f32_16x16x32_bf16 v[106:109], v[160:163], v[192:195], v[106:109]
	v_mfma_f32_16x16x32_bf16 v[94:97], v[152:155], v[200:203], v[94:97]
	v_mfma_f32_16x16x32_bf16 v[90:93], v[160:163], v[200:203], v[90:93]
	v_mfma_f32_16x16x32_bf16 v[78:81], v[152:155], v[208:211], v[78:81]
	v_mfma_f32_16x16x32_bf16 v[74:77], v[160:163], v[208:211], v[74:77]
	s_setprio 0
	s_setprio 1
	v_mfma_f32_16x16x32_bf16 v[118:121], v[164:167], v[180:183], v[118:121]
	v_mfma_f32_16x16x32_bf16 v[114:117], v[172:175], v[180:183], v[114:117]
	v_mfma_f32_16x16x32_bf16 v[102:105], v[164:167], v[188:191], v[102:105]
	v_mfma_f32_16x16x32_bf16 v[98:101], v[172:175], v[188:191], v[98:101]
	v_mfma_f32_16x16x32_bf16 v[86:89], v[164:167], v[196:199], v[86:89]
	v_mfma_f32_16x16x32_bf16 v[82:85], v[172:175], v[196:199], v[82:85]
	v_mfma_f32_16x16x32_bf16 v[70:73], v[164:167], v[204:207], v[70:73]
	v_mfma_f32_16x16x32_bf16 v[66:69], v[172:175], v[204:207], v[66:69]
	v_mfma_f32_16x16x32_bf16 v[118:121], v[168:171], v[184:187], v[118:121]
	v_mfma_f32_16x16x32_bf16 v[114:117], v[176:179], v[184:187], v[114:117]
	v_mfma_f32_16x16x32_bf16 v[102:105], v[168:171], v[192:195], v[102:105]
	v_mfma_f32_16x16x32_bf16 v[98:101], v[176:179], v[192:195], v[98:101]
	v_mfma_f32_16x16x32_bf16 v[86:89], v[168:171], v[200:203], v[86:89]
	v_mfma_f32_16x16x32_bf16 v[82:85], v[176:179], v[200:203], v[82:85]
	v_mfma_f32_16x16x32_bf16 v[70:73], v[168:171], v[208:211], v[70:73]
	v_mfma_f32_16x16x32_bf16 v[66:69], v[176:179], v[208:211], v[66:69]
	s_setprio 0
	s_barrier
	s_add_i32 s18, s41, s27
	v_lshl_add_u64 v[212:213], s[22:23], 0, v[130:131]
	s_mov_b32 m0, s18
	s_nop 0
	global_load_lds_dwordx4 v[212:213], off
	s_add_i32 m0, s18, 0x2000
	s_add_u32 s18, s22, 0x160000
	v_lshl_add_u64 v[214:215], s[22:23], 0, v[132:133]
	s_addc_u32 s19, s23, 0
	s_add_i32 s50, s42, s27
	global_load_lds_dwordx4 v[214:215], off
	v_lshl_add_u64 v[216:217], s[18:19], 0, v[130:131]
	s_mov_b32 m0, s50
	v_lshl_add_u64 v[218:219], s[24:25], 0, v[132:133]
	global_load_lds_dwordx4 v[216:217], off
	v_lshl_add_u64 v[216:217], s[18:19], 0, v[132:133]
	s_add_i32 m0, s50, 0x2000
	s_nop 0
	global_load_lds_dwordx4 v[216:217], off
	v_lshl_add_u64 v[216:217], s[24:25], 0, v[130:131]
	s_mov_b32 m0, s28
	s_nop 0
	global_load_lds_dwordx4 v[216:217], off
	s_mov_b32 m0, s29
	s_nop 0
	global_load_lds_dwordx4 v[218:219], off
	ds_read_b128 v[180:183], v150 offset:16384
	ds_read_b128 v[184:187], v150 offset:17408
	ds_read_b128 v[188:191], v150 offset:18432
	ds_read_b128 v[192:195], v150 offset:19456
	ds_read_b128 v[196:199], v150 offset:20480
	ds_read_b128 v[200:203], v150 offset:21504
	ds_read_b128 v[204:207], v150 offset:22528
	ds_read_b128 v[208:211], v150 offset:23552
	s_waitcnt vmcnt(8)
	s_waitcnt lgkmcnt(0)
	s_barrier
	s_setprio 1
	s_waitcnt lgkmcnt(0)
	v_mfma_f32_16x16x32_bf16 v[62:65], v[142:145], v[180:183], v[62:65]
	v_mfma_f32_16x16x32_bf16 v[58:61], v[156:159], v[180:183], v[58:61]
	v_mfma_f32_16x16x32_bf16 v[46:49], v[142:145], v[188:191], v[46:49]
	v_mfma_f32_16x16x32_bf16 v[42:45], v[156:159], v[188:191], v[42:45]
	v_mfma_f32_16x16x32_bf16 v[30:33], v[142:145], v[196:199], v[30:33]
	v_mfma_f32_16x16x32_bf16 v[26:29], v[156:159], v[196:199], v[26:29]
	v_mfma_f32_16x16x32_bf16 v[14:17], v[142:145], v[204:207], v[14:17]
	v_mfma_f32_16x16x32_bf16 v[10:13], v[156:159], v[204:207], v[10:13]
	v_mfma_f32_16x16x32_bf16 v[62:65], v[152:155], v[184:187], v[62:65]
	v_mfma_f32_16x16x32_bf16 v[58:61], v[160:163], v[184:187], v[58:61]
	v_mfma_f32_16x16x32_bf16 v[46:49], v[152:155], v[192:195], v[46:49]
	v_mfma_f32_16x16x32_bf16 v[42:45], v[160:163], v[192:195], v[42:45]
	v_mfma_f32_16x16x32_bf16 v[30:33], v[152:155], v[200:203], v[30:33]
	v_mfma_f32_16x16x32_bf16 v[26:29], v[160:163], v[200:203], v[26:29]
	v_mfma_f32_16x16x32_bf16 v[14:17], v[152:155], v[208:211], v[14:17]
	v_mfma_f32_16x16x32_bf16 v[10:13], v[160:163], v[208:211], v[10:13]
	s_setprio 0
	s_setprio 1
	v_mfma_f32_16x16x32_bf16 v[54:57], v[164:167], v[180:183], v[54:57]
	v_mfma_f32_16x16x32_bf16 v[50:53], v[172:175], v[180:183], v[50:53]
	v_mfma_f32_16x16x32_bf16 v[38:41], v[164:167], v[188:191], v[38:41]
	v_mfma_f32_16x16x32_bf16 v[34:37], v[172:175], v[188:191], v[34:37]
	v_mfma_f32_16x16x32_bf16 v[22:25], v[164:167], v[196:199], v[22:25]
	v_mfma_f32_16x16x32_bf16 v[18:21], v[172:175], v[196:199], v[18:21]
	v_mfma_f32_16x16x32_bf16 v[6:9], v[164:167], v[204:207], v[6:9]
	v_mfma_f32_16x16x32_bf16 v[2:5], v[172:175], v[204:207], v[2:5]
	v_mfma_f32_16x16x32_bf16 v[54:57], v[168:171], v[184:187], v[54:57]
	v_mfma_f32_16x16x32_bf16 v[50:53], v[176:179], v[184:187], v[50:53]
	v_mfma_f32_16x16x32_bf16 v[38:41], v[168:171], v[192:195], v[38:41]
	v_mfma_f32_16x16x32_bf16 v[34:37], v[176:179], v[192:195], v[34:37]
	v_mfma_f32_16x16x32_bf16 v[22:25], v[168:171], v[200:203], v[22:25]
	v_mfma_f32_16x16x32_bf16 v[18:21], v[176:179], v[200:203], v[18:21]
	v_mfma_f32_16x16x32_bf16 v[6:9], v[168:171], v[208:211], v[6:9]
	v_mfma_f32_16x16x32_bf16 v[2:5], v[176:179], v[208:211], v[2:5]
	s_setprio 0
	s_barrier
	s_add_i32 s50, 0, 0x18000
	s_add_i32 s51, 0, 0x1c000
	s_add_u32 s18, s24, 0x160000
	s_addc_u32 s19, s25, 0
	s_mov_b32 m0, s30
	v_lshl_add_u64 v[220:221], s[18:19], 0, v[130:131]
	global_load_lds_dwordx4 v[220:221], off
	v_lshl_add_u64 v[220:221], s[18:19], 0, v[132:133]
	s_mov_b32 m0, s31
	s_nop 0
	global_load_lds_dwordx4 v[220:221], off
	v_add_u32_e32 v160, s50, v147
	v_add_u32_e32 v176, s51, v147
	ds_read_b128 v[142:145], v160
	ds_read_b128 v[152:155], v160 offset:1024
	ds_read_b128 v[156:159], v160 offset:2048
	ds_read_b128 v[160:163], v160 offset:3072
	ds_read_b128 v[164:167], v176
	ds_read_b128 v[168:171], v176 offset:1024
	ds_read_b128 v[172:175], v176 offset:2048
	ds_read_b128 v[176:179], v176 offset:3072
	ds_read_b128 v[180:183], v150 offset:32768
	ds_read_b128 v[184:187], v150 offset:33792
	ds_read_b128 v[188:191], v150 offset:34816
	ds_read_b128 v[192:195], v150 offset:35840
	ds_read_b128 v[196:199], v150 offset:36864
	ds_read_b128 v[200:203], v150 offset:37888
	ds_read_b128 v[204:207], v150 offset:38912
	ds_read_b128 v[208:211], v150 offset:39936
	s_waitcnt vmcnt(8)
	s_waitcnt lgkmcnt(0)
	s_barrier
	s_setprio 1
	s_waitcnt lgkmcnt(0)
	v_mfma_f32_16x16x32_bf16 v[126:129], v[142:145], v[180:183], v[126:129]
	v_mfma_f32_16x16x32_bf16 v[122:125], v[156:159], v[180:183], v[122:125]
	v_mfma_f32_16x16x32_bf16 v[110:113], v[142:145], v[188:191], v[110:113]
	v_mfma_f32_16x16x32_bf16 v[106:109], v[156:159], v[188:191], v[106:109]
	v_mfma_f32_16x16x32_bf16 v[94:97], v[142:145], v[196:199], v[94:97]
	v_mfma_f32_16x16x32_bf16 v[90:93], v[156:159], v[196:199], v[90:93]
	v_mfma_f32_16x16x32_bf16 v[78:81], v[142:145], v[204:207], v[78:81]
	v_mfma_f32_16x16x32_bf16 v[74:77], v[156:159], v[204:207], v[74:77]
	v_mfma_f32_16x16x32_bf16 v[126:129], v[152:155], v[184:187], v[126:129]
	v_mfma_f32_16x16x32_bf16 v[122:125], v[160:163], v[184:187], v[122:125]
	v_mfma_f32_16x16x32_bf16 v[110:113], v[152:155], v[192:195], v[110:113]
	v_mfma_f32_16x16x32_bf16 v[106:109], v[160:163], v[192:195], v[106:109]
	v_mfma_f32_16x16x32_bf16 v[94:97], v[152:155], v[200:203], v[94:97]
	v_mfma_f32_16x16x32_bf16 v[90:93], v[160:163], v[200:203], v[90:93]
	v_mfma_f32_16x16x32_bf16 v[78:81], v[152:155], v[208:211], v[78:81]
	v_mfma_f32_16x16x32_bf16 v[74:77], v[160:163], v[208:211], v[74:77]
	s_setprio 0
	s_setprio 1
	v_mfma_f32_16x16x32_bf16 v[118:121], v[164:167], v[180:183], v[118:121]
	v_mfma_f32_16x16x32_bf16 v[114:117], v[172:175], v[180:183], v[114:117]
	v_mfma_f32_16x16x32_bf16 v[102:105], v[164:167], v[188:191], v[102:105]
	v_mfma_f32_16x16x32_bf16 v[98:101], v[172:175], v[188:191], v[98:101]
	v_mfma_f32_16x16x32_bf16 v[86:89], v[164:167], v[196:199], v[86:89]
	v_mfma_f32_16x16x32_bf16 v[82:85], v[172:175], v[196:199], v[82:85]
	v_mfma_f32_16x16x32_bf16 v[70:73], v[164:167], v[204:207], v[70:73]
	v_mfma_f32_16x16x32_bf16 v[66:69], v[172:175], v[204:207], v[66:69]
	v_mfma_f32_16x16x32_bf16 v[118:121], v[168:171], v[184:187], v[118:121]
	v_mfma_f32_16x16x32_bf16 v[114:117], v[176:179], v[184:187], v[114:117]
	v_mfma_f32_16x16x32_bf16 v[102:105], v[168:171], v[192:195], v[102:105]
	v_mfma_f32_16x16x32_bf16 v[98:101], v[176:179], v[192:195], v[98:101]
	v_mfma_f32_16x16x32_bf16 v[86:89], v[168:171], v[200:203], v[86:89]
	v_mfma_f32_16x16x32_bf16 v[82:85], v[176:179], v[200:203], v[82:85]
	v_mfma_f32_16x16x32_bf16 v[70:73], v[168:171], v[208:211], v[70:73]
	v_mfma_f32_16x16x32_bf16 v[66:69], v[176:179], v[208:211], v[66:69]
	s_setprio 0
	s_barrier
	s_add_i32 s18, s50, s27
	v_lshl_add_u64 v[212:213], v[212:213], 0, s[12:13]
	s_mov_b32 m0, s18
	s_nop 0
	global_load_lds_dwordx4 v[212:213], off
	s_add_i32 m0, s18, 0x2000
	s_add_u32 s18, s22, 0x160080
	v_lshl_add_u64 v[212:213], v[214:215], 0, s[12:13]
	s_addc_u32 s19, s23, 0
	s_add_i32 s22, s51, s27
	global_load_lds_dwordx4 v[212:213], off
	v_lshl_add_u64 v[212:213], s[18:19], 0, v[130:131]
	s_mov_b32 m0, s22
	s_nop 0
	global_load_lds_dwordx4 v[212:213], off
	v_lshl_add_u64 v[212:213], s[18:19], 0, v[132:133]
	s_add_i32 m0, s22, 0x2000
	s_nop 0
	global_load_lds_dwordx4 v[212:213], off
	v_lshl_add_u64 v[212:213], v[216:217], 0, s[12:13]
	s_mov_b32 m0, s37
	s_nop 0
	global_load_lds_dwordx4 v[212:213], off
	v_lshl_add_u64 v[212:213], v[218:219], 0, s[12:13]
	s_mov_b32 m0, s38
	s_nop 0
	global_load_lds_dwordx4 v[212:213], off
	ds_read_b128 v[180:183], v150 offset:49152
	ds_read_b128 v[184:187], v150 offset:50176
	ds_read_b128 v[188:191], v150 offset:51200
	ds_read_b128 v[192:195], v150 offset:52224
	ds_read_b128 v[196:199], v150 offset:53248
	ds_read_b128 v[200:203], v150 offset:54272
	ds_read_b128 v[204:207], v150 offset:55296
	ds_read_b128 v[208:211], v150 offset:56320
	s_waitcnt vmcnt(8)
	s_waitcnt lgkmcnt(0)
	s_barrier
	s_setprio 1
	s_waitcnt lgkmcnt(0)
	v_mfma_f32_16x16x32_bf16 v[62:65], v[142:145], v[180:183], v[62:65]
	v_mfma_f32_16x16x32_bf16 v[58:61], v[156:159], v[180:183], v[58:61]
	v_mfma_f32_16x16x32_bf16 v[46:49], v[142:145], v[188:191], v[46:49]
	v_mfma_f32_16x16x32_bf16 v[42:45], v[156:159], v[188:191], v[42:45]
	v_mfma_f32_16x16x32_bf16 v[30:33], v[142:145], v[196:199], v[30:33]
	v_mfma_f32_16x16x32_bf16 v[26:29], v[156:159], v[196:199], v[26:29]
	v_mfma_f32_16x16x32_bf16 v[14:17], v[142:145], v[204:207], v[14:17]
	v_mfma_f32_16x16x32_bf16 v[10:13], v[156:159], v[204:207], v[10:13]
	v_mfma_f32_16x16x32_bf16 v[62:65], v[152:155], v[184:187], v[62:65]
	v_mfma_f32_16x16x32_bf16 v[58:61], v[160:163], v[184:187], v[58:61]
	v_mfma_f32_16x16x32_bf16 v[46:49], v[152:155], v[192:195], v[46:49]
	v_mfma_f32_16x16x32_bf16 v[42:45], v[160:163], v[192:195], v[42:45]
	v_mfma_f32_16x16x32_bf16 v[30:33], v[152:155], v[200:203], v[30:33]
	v_mfma_f32_16x16x32_bf16 v[26:29], v[160:163], v[200:203], v[26:29]
	v_mfma_f32_16x16x32_bf16 v[14:17], v[152:155], v[208:211], v[14:17]
	v_mfma_f32_16x16x32_bf16 v[10:13], v[160:163], v[208:211], v[10:13]
	s_setprio 0
	s_setprio 1
	v_mfma_f32_16x16x32_bf16 v[54:57], v[164:167], v[180:183], v[54:57]
	v_mfma_f32_16x16x32_bf16 v[50:53], v[172:175], v[180:183], v[50:53]
	v_mfma_f32_16x16x32_bf16 v[38:41], v[164:167], v[188:191], v[38:41]
	v_mfma_f32_16x16x32_bf16 v[34:37], v[172:175], v[188:191], v[34:37]
	v_mfma_f32_16x16x32_bf16 v[22:25], v[164:167], v[196:199], v[22:25]
	v_mfma_f32_16x16x32_bf16 v[18:21], v[172:175], v[196:199], v[18:21]
	v_mfma_f32_16x16x32_bf16 v[6:9], v[164:167], v[204:207], v[6:9]
	v_mfma_f32_16x16x32_bf16 v[2:5], v[172:175], v[204:207], v[2:5]
	v_mfma_f32_16x16x32_bf16 v[54:57], v[168:171], v[184:187], v[54:57]
	v_mfma_f32_16x16x32_bf16 v[50:53], v[176:179], v[184:187], v[50:53]
	v_mfma_f32_16x16x32_bf16 v[38:41], v[168:171], v[192:195], v[38:41]
	v_mfma_f32_16x16x32_bf16 v[34:37], v[176:179], v[192:195], v[34:37]
	v_mfma_f32_16x16x32_bf16 v[22:25], v[168:171], v[200:203], v[22:25]
	v_mfma_f32_16x16x32_bf16 v[18:21], v[176:179], v[200:203], v[18:21]
	v_mfma_f32_16x16x32_bf16 v[6:9], v[168:171], v[208:211], v[6:9]
	v_mfma_f32_16x16x32_bf16 v[2:5], v[176:179], v[208:211], v[2:5]
	s_setprio 0
	s_barrier
	s_add_i32 s49, s49, 2
	s_add_u32 s47, s47, 0x100
	s_addc_u32 s48, s48, 0
	s_cmpk_gt_u32 s49, 0x55
	s_mov_b64 s[18:19], s[20:21]
	s_cbranch_scc0 .LBB0_3378
	s_and_b64 vcc, exec, s[14:15]
	s_cbranch_vccz .LBB0_3381
	s_barrier
